# fgate: weights staged once per workgroup into LDS by LDS-DMA (8x less L2 traffic on the hot 32 KB), then read into VGPRs
# baseline (speedup 1.0000x reference)
; __device__ __forceinline__ void fgate_phase(const bfr* x, const float* wf, const float* bfg, float* cl, float* ctot, LAS float* scr, int bx, int G, int tid, int lane, int wave) {
;     ...
;         for (int j = 0; j < 8; j += 2) { const int row = chunk * 64 + wave * 8 + j; typedef unsigned u32x2 __attribute__((ext_vector_type(2))); const u32x2* xa = (const u32x2*)(x + (size_t)row * D) + lane; const u32x2* xb2 = xa + D / 4; f32x4 va[4], vb[4]; float r[18]; int zo = 0; asm volatile("" : "+v"(zo));
; #pragma unroll
;             for (int jj = 0; jj < 4; ++jj) { const u32x2 wa = xa[64 * jj], wb = xb2[64 * jj]; va[jj] = (f32x4){bf_lo(wa.x), bf_hi(wa.x), bf_lo(wa.y), bf_hi(wa.y)}; vb[jj] = (f32x4){bf_lo(wb.x), bf_hi(wb.x), bf_lo(wb.y), bf_hi(wb.y)}; }
;             r[16] = 0.f; r[17] = 0.f;
; #pragma unroll
;             for (int jj = 0; jj < 4; ++jj) { r[16] += (va[jj].x * va[jj].x + va[jj].y * va[jj].y) + (va[jj].z * va[jj].z + va[jj].w * va[jj].w); r[17] += (vb[jj].x * vb[jj].x + vb[jj].y * vb[jj].y) + (vb[jj].z * vb[jj].z + vb[jj].w * vb[jj].w); }
; #pragma unroll
;             for (int h = 0; h < NH; ++h) { const f32x4* wr = (const f32x4*)(wf + h * D) + lane + zo; float da = 0.f, db = 0.f;
; #pragma unroll
;                 for (int jj = 0; jj < 4; ++jj) { const f32x4 w = wr[64 * jj]; da += (va[jj].x * w.x + va[jj].y * w.y) + (va[jj].z * w.z + va[jj].w * w.w); db += (vb[jj].x * w.x + vb[jj].y * w.y) + (vb[jj].z * w.z + vb[jj].w * w.w); }
;                 r[h] = da; r[8 + h] = db; }
.LBB0_424:
	s_mov_b32 s38, s33
	s_ashr_i32 s39, s33, 31
	s_lshl_b64 s[38:39], s[38:39], 11
	s_mov_b64 s[98:99], 0x1000
	s_mov_b64 s[100:101], 0x2000
	v_lshl_add_u64 v[26:27], v[28:29], 0, s[38:39]
	v_lshl_add_u64 v[40:41], v[26:27], 0, s[98:99]
	global_load_dwordx2 v[38:39], v[26:27], off
	global_load_dwordx2 v[98:99], v[26:27], off offset:512
	global_load_dwordx2 v[160:161], v[26:27], off offset:1024
	global_load_dwordx2 v[0:1], v[26:27], off offset:1536
	global_load_dwordx2 v[2:3], v[26:27], off offset:2048
	global_load_dwordx2 v[4:5], v[26:27], off offset:2560
	global_load_dwordx2 v[6:7], v[26:27], off offset:3072
	global_load_dwordx2 v[8:9], v[26:27], off offset:3584
	global_load_dwordx2 v[10:11], v[40:41], off
	global_load_dwordx2 v[12:13], v[40:41], off offset:512
	global_load_dwordx2 v[14:15], v[40:41], off offset:1024
	global_load_dwordx2 v[16:17], v[40:41], off offset:1536
	global_load_dwordx2 v[18:19], v[40:41], off offset:2048
	global_load_dwordx2 v[20:21], v[40:41], off offset:2560
	global_load_dwordx2 v[22:23], v[40:41], off offset:3072
	global_load_dwordx2 v[24:25], v[40:41], off offset:3584
	global_load_dword v103, v[32:33], off
	v_lshrrev_b32_e32 v104, 6, v128
	v_lshlrev_b32_e32 v105, 4, v158
	v_readfirstlane_b32 s20, v30
	v_readfirstlane_b32 s21, v31
	v_readfirstlane_b32 s66, v104
	s_lshl_b32 s66, s66, 12
	s_add_u32 s20, s20, s66
	s_addc_u32 s21, s21, 0
	s_add_i32 s66, s66, 0x1000
	s_mov_b32 m0, s66
	s_nop 0
	global_load_lds_dwordx4 v105, s[20:21]
	s_add_u32 s20, s20, 0x400
	s_addc_u32 s21, s21, 0
	s_add_i32 s66, s66, 0x400
	s_mov_b32 m0, s66
	s_nop 0
	global_load_lds_dwordx4 v105, s[20:21]
	s_add_u32 s20, s20, 0x400
	s_addc_u32 s21, s21, 0
	s_add_i32 s66, s66, 0x400
	s_mov_b32 m0, s66
	s_nop 0
	global_load_lds_dwordx4 v105, s[20:21]
	s_add_u32 s20, s20, 0x400
	s_addc_u32 s21, s21, 0
	s_add_i32 s66, s66, 0x400
	s_mov_b32 m0, s66
	s_nop 0
	global_load_lds_dwordx4 v105, s[20:21]
	s_waitcnt vmcnt(0)
	s_barrier
	ds_read_b128 v[248:251], v105 offset:4096
	ds_read_b128 v[244:247], v105 offset:5120
	ds_read_b128 v[240:243], v105 offset:6144
	ds_read_b128 v[236:239], v105 offset:7168
	ds_read_b128 v[232:235], v105 offset:8192
	ds_read_b128 v[228:231], v105 offset:9216
	ds_read_b128 v[224:227], v105 offset:10240
	ds_read_b128 v[220:223], v105 offset:11264
	ds_read_b128 v[216:219], v105 offset:12288
	ds_read_b128 v[212:215], v105 offset:13312
	ds_read_b128 v[208:211], v105 offset:14336
	ds_read_b128 v[204:207], v105 offset:15360
	ds_read_b128 v[200:203], v105 offset:16384
	ds_read_b128 v[196:199], v105 offset:17408
	ds_read_b128 v[192:195], v105 offset:18432
	ds_read_b128 v[188:191], v105 offset:19456
	ds_read_b128 v[182:185], v105 offset:20480
	ds_read_b128 v[178:181], v105 offset:21504
	ds_read_b128 v[174:177], v105 offset:22528
	ds_read_b128 v[170:173], v105 offset:23552
	ds_read_b128 v[166:169], v105 offset:24576
	ds_read_b128 v[162:165], v105 offset:25600
	ds_read_b128 v[154:157], v105 offset:26624
	ds_read_b128 v[150:153], v105 offset:27648
	ds_read_b128 v[146:149], v105 offset:28672
	ds_read_b128 v[142:145], v105 offset:29696
	ds_read_b128 v[138:141], v105 offset:30720
	ds_read_b128 v[134:137], v105 offset:31744
	ds_read_b128 v[130:133], v105 offset:32768
	ds_read_b128 v[124:127], v105 offset:33792
	ds_read_b128 v[120:123], v105 offset:34816
	ds_read_b128 v[116:119], v105 offset:35840
	v_and_b32_e32 v106, 7, v158
	v_cmp_eq_u32_e64 s[6:7], 1, v106
	v_cmp_eq_u32_e64 s[8:9], 2, v106
	v_cmp_eq_u32_e64 s[10:11], 3, v106
	v_cmp_eq_u32_e64 s[12:13], 4, v106
	v_cmp_eq_u32_e64 s[14:15], 5, v106
	v_cmp_eq_u32_e64 s[16:17], 6, v106
	v_cmp_eq_u32_e64 s[18:19], 7, v106
	v_lshrrev_b32_e32 v104, 4, v158
	v_lshlrev_b32_e32 v104, 5, v104
	v_sub_u32_e32 v107, v95, v104
	s_mov_b32 s40, 0xffff0000
	s_waitcnt vmcnt(0) lgkmcnt(0)
	v_lshlrev_b32_e32 v97, 16, v38
	v_and_b32_e32 v159, s40, v38
	v_lshlrev_b32_e32 v187, 16, v39
	v_and_b32_e32 v42, s40, v39
	v_lshlrev_b32_e32 v43, 16, v98
	v_and_b32_e32 v44, s40, v98
	v_lshlrev_b32_e32 v45, 16, v99
	v_and_b32_e32 v46, s40, v99
	v_lshlrev_b32_e32 v47, 16, v160
	v_and_b32_e32 v48, s40, v160
	v_lshlrev_b32_e32 v49, 16, v161
	v_and_b32_e32 v50, s40, v161
	v_lshlrev_b32_e32 v51, 16, v0
	v_and_b32_e32 v52, s40, v0
	v_lshlrev_b32_e32 v53, 16, v1
	v_and_b32_e32 v54, s40, v1
	v_mul_f32_e32 v87, v97, v97
	v_mul_f32_e32 v55, v97, v248
	v_mul_f32_e32 v56, v97, v232
	v_mul_f32_e32 v57, v97, v216
	v_mul_f32_e32 v58, v97, v200
	v_mul_f32_e32 v59, v97, v182
	v_mul_f32_e32 v60, v97, v166
	v_mul_f32_e32 v61, v97, v146
	v_mul_f32_e32 v62, v97, v130
	v_fmac_f32_e32 v87, v159, v159
	v_fmac_f32_e32 v55, v159, v249
	v_fmac_f32_e32 v56, v159, v233
	v_fmac_f32_e32 v57, v159, v217
	v_fmac_f32_e32 v58, v159, v201
	v_fmac_f32_e32 v59, v159, v183
	v_fmac_f32_e32 v60, v159, v167
	v_fmac_f32_e32 v61, v159, v147
	v_fmac_f32_e32 v62, v159, v131
	v_fmac_f32_e32 v87, v187, v187
	v_fmac_f32_e32 v55, v187, v250
	v_fmac_f32_e32 v56, v187, v234
	v_fmac_f32_e32 v57, v187, v218
	v_fmac_f32_e32 v58, v187, v202
	v_fmac_f32_e32 v59, v187, v184
	v_fmac_f32_e32 v60, v187, v168
	v_fmac_f32_e32 v61, v187, v148
	v_fmac_f32_e32 v62, v187, v132
	v_fmac_f32_e32 v87, v42, v42
	v_fmac_f32_e32 v55, v42, v251
	v_fmac_f32_e32 v56, v42, v235
	v_fmac_f32_e32 v57, v42, v219
	v_fmac_f32_e32 v58, v42, v203
	v_fmac_f32_e32 v59, v42, v185
	v_fmac_f32_e32 v60, v42, v169
	v_fmac_f32_e32 v61, v42, v149
	v_fmac_f32_e32 v62, v42, v133
	v_fmac_f32_e32 v87, v43, v43
	v_fmac_f32_e32 v55, v43, v244
	v_fmac_f32_e32 v56, v43, v228
	v_fmac_f32_e32 v57, v43, v212
	v_fmac_f32_e32 v58, v43, v196
	v_fmac_f32_e32 v59, v43, v178
	v_fmac_f32_e32 v60, v43, v162
	v_fmac_f32_e32 v61, v43, v142
; __device__ __forceinline__ void fgate_phase(const bfr* x, const float* wf, const float* bfg, float* cl, float* ctot, LAS float* scr, int bx, int G, int tid, int lane, int wave) {
;     ...
;             for (int jj = 0; jj < 4; ++jj) { const u32x2 wa = xa[64 * jj], wb = xb2[64 * jj]; va[jj] = (f32x4){bf_lo(wa.x), bf_hi(wa.x), bf_lo(wa.y), bf_hi(wa.y)}; vb[jj] = (f32x4){bf_lo(wb.x), bf_hi(wb.x), bf_lo(wb.y), bf_hi(wb.y)}; }
;             r[16] = 0.f; r[17] = 0.f;
; #pragma unroll
;             for (int jj = 0; jj < 4; ++jj) { r[16] += (va[jj].x * va[jj].x + va[jj].y * va[jj].y) + (va[jj].z * va[jj].z + va[jj].w * va[jj].w); r[17] += (vb[jj].x * vb[jj].x + vb[jj].y * vb[jj].y) + (vb[jj].z * vb[jj].z + vb[jj].w * vb[jj].w); }
; #pragma unroll
;             for (int h = 0; h < NH; ++h) { const f32x4* wr = (const f32x4*)(wf + h * D) + lane + zo; float da = 0.f, db = 0.f;
; #pragma unroll
;                 for (int jj = 0; jj < 4; ++jj) { const f32x4 w = wr[64 * jj]; da += (va[jj].x * w.x + va[jj].y * w.y) + (va[jj].z * w.z + va[jj].w * w.w); db += (vb[jj].x * w.x + vb[jj].y * w.y) + (vb[jj].z * w.z + vb[jj].w * w.w); }
;                 r[h] = da; r[8 + h] = db; }
	v_fmac_f32_e32 v62, v43, v124
	v_fmac_f32_e32 v87, v44, v44
	v_fmac_f32_e32 v55, v44, v245
	v_fmac_f32_e32 v56, v44, v229
	v_fmac_f32_e32 v57, v44, v213
	v_fmac_f32_e32 v58, v44, v197
	v_fmac_f32_e32 v59, v44, v179
	v_fmac_f32_e32 v60, v44, v163
	v_fmac_f32_e32 v61, v44, v143
	v_fmac_f32_e32 v62, v44, v125
	v_fmac_f32_e32 v87, v45, v45
	v_fmac_f32_e32 v55, v45, v246
	v_fmac_f32_e32 v56, v45, v230
	v_fmac_f32_e32 v57, v45, v214
	v_fmac_f32_e32 v58, v45, v198
	v_fmac_f32_e32 v59, v45, v180
	v_fmac_f32_e32 v60, v45, v164
	v_fmac_f32_e32 v61, v45, v144
	v_fmac_f32_e32 v62, v45, v126
	v_fmac_f32_e32 v87, v46, v46
	v_fmac_f32_e32 v55, v46, v247
	v_fmac_f32_e32 v56, v46, v231
	v_fmac_f32_e32 v57, v46, v215
	v_fmac_f32_e32 v58, v46, v199
	v_fmac_f32_e32 v59, v46, v181
	v_fmac_f32_e32 v60, v46, v165
	v_fmac_f32_e32 v61, v46, v145
	v_fmac_f32_e32 v62, v46, v127
	v_fmac_f32_e32 v87, v47, v47
	v_fmac_f32_e32 v55, v47, v240
	v_fmac_f32_e32 v56, v47, v224
	v_fmac_f32_e32 v57, v47, v208
	v_fmac_f32_e32 v58, v47, v192
	v_fmac_f32_e32 v59, v47, v174
	v_fmac_f32_e32 v60, v47, v154
	v_fmac_f32_e32 v61, v47, v138
	v_fmac_f32_e32 v62, v47, v120
	v_fmac_f32_e32 v87, v48, v48
	v_fmac_f32_e32 v55, v48, v241
	v_fmac_f32_e32 v56, v48, v225
	v_fmac_f32_e32 v57, v48, v209
	v_fmac_f32_e32 v58, v48, v193
	v_fmac_f32_e32 v59, v48, v175
	v_fmac_f32_e32 v60, v48, v155
	v_fmac_f32_e32 v61, v48, v139
	v_fmac_f32_e32 v62, v48, v121
	v_fmac_f32_e32 v87, v49, v49
	v_fmac_f32_e32 v55, v49, v242
	v_fmac_f32_e32 v56, v49, v226
	v_fmac_f32_e32 v57, v49, v210
	v_fmac_f32_e32 v58, v49, v194
	v_fmac_f32_e32 v59, v49, v176
	v_fmac_f32_e32 v60, v49, v156
	v_fmac_f32_e32 v61, v49, v140
	v_fmac_f32_e32 v62, v49, v122
	v_fmac_f32_e32 v87, v50, v50
	v_fmac_f32_e32 v55, v50, v243
	v_fmac_f32_e32 v56, v50, v227
	v_fmac_f32_e32 v57, v50, v211
	v_fmac_f32_e32 v58, v50, v195
	v_fmac_f32_e32 v59, v50, v177
	v_fmac_f32_e32 v60, v50, v157
	v_fmac_f32_e32 v61, v50, v141
	v_fmac_f32_e32 v62, v50, v123
	v_fmac_f32_e32 v87, v51, v51
	v_fmac_f32_e32 v55, v51, v236
	v_fmac_f32_e32 v56, v51, v220
	v_fmac_f32_e32 v57, v51, v204
	v_fmac_f32_e32 v58, v51, v188
	v_fmac_f32_e32 v59, v51, v170
	v_fmac_f32_e32 v60, v51, v150
	v_fmac_f32_e32 v61, v51, v134
	v_fmac_f32_e32 v62, v51, v116
	v_fmac_f32_e32 v87, v52, v52
	v_fmac_f32_e32 v55, v52, v237
	v_fmac_f32_e32 v56, v52, v221
	v_fmac_f32_e32 v57, v52, v205
	v_fmac_f32_e32 v58, v52, v189
	v_fmac_f32_e32 v59, v52, v171
	v_fmac_f32_e32 v60, v52, v151
	v_fmac_f32_e32 v61, v52, v135
	v_fmac_f32_e32 v62, v52, v117
	v_fmac_f32_e32 v87, v53, v53
	v_fmac_f32_e32 v55, v53, v238
	v_fmac_f32_e32 v56, v53, v222
	v_fmac_f32_e32 v57, v53, v206
	v_fmac_f32_e32 v58, v53, v190
	v_fmac_f32_e32 v59, v53, v172
	v_fmac_f32_e32 v60, v53, v152
	v_fmac_f32_e32 v61, v53, v136
	v_fmac_f32_e32 v62, v53, v118
	v_fmac_f32_e32 v87, v54, v54
	v_fmac_f32_e32 v55, v54, v239
	v_fmac_f32_e32 v56, v54, v223
	v_fmac_f32_e32 v57, v54, v207
	v_fmac_f32_e32 v58, v54, v191
	v_fmac_f32_e32 v59, v54, v173
	v_fmac_f32_e32 v60, v54, v153
	v_fmac_f32_e32 v61, v54, v137
	v_fmac_f32_e32 v62, v54, v119
	v_lshlrev_b32_e32 v97, 16, v2
	v_and_b32_e32 v159, s40, v2
	v_lshlrev_b32_e32 v187, 16, v3
	v_and_b32_e32 v42, s40, v3
	v_lshlrev_b32_e32 v43, 16, v4
	v_and_b32_e32 v44, s40, v4
	v_lshlrev_b32_e32 v45, 16, v5
	v_and_b32_e32 v46, s40, v5
	v_lshlrev_b32_e32 v47, 16, v6
	v_and_b32_e32 v48, s40, v6
	v_lshlrev_b32_e32 v49, 16, v7
	v_and_b32_e32 v50, s40, v7
	v_lshlrev_b32_e32 v51, 16, v8
	v_and_b32_e32 v52, s40, v8
	v_lshlrev_b32_e32 v53, 16, v9
	v_and_b32_e32 v54, s40, v9
	v_mul_f32_e32 v100, v97, v97
	v_mul_f32_e32 v63, v97, v248
	v_mul_f32_e32 v64, v97, v232
	v_mul_f32_e32 v65, v97, v216
	v_mul_f32_e32 v66, v97, v200
	v_mul_f32_e32 v67, v97, v182
	v_mul_f32_e32 v68, v97, v166
	v_mul_f32_e32 v69, v97, v146
	v_mul_f32_e32 v70, v97, v130
	v_fmac_f32_e32 v100, v159, v159
	v_fmac_f32_e32 v63, v159, v249
	v_fmac_f32_e32 v64, v159, v233
	v_fmac_f32_e32 v65, v159, v217
	v_fmac_f32_e32 v66, v159, v201
	v_fmac_f32_e32 v67, v159, v183
	v_fmac_f32_e32 v68, v159, v167
	v_fmac_f32_e32 v69, v159, v147
	v_fmac_f32_e32 v70, v159, v131
	v_fmac_f32_e32 v100, v187, v187
	v_fmac_f32_e32 v63, v187, v250
	v_fmac_f32_e32 v64, v187, v234
	v_fmac_f32_e32 v65, v187, v218
	v_fmac_f32_e32 v66, v187, v202
	v_fmac_f32_e32 v67, v187, v184
	v_fmac_f32_e32 v68, v187, v168
	v_fmac_f32_e32 v69, v187, v148
	v_fmac_f32_e32 v70, v187, v132
	v_fmac_f32_e32 v100, v42, v42
	v_fmac_f32_e32 v63, v42, v251
	v_fmac_f32_e32 v64, v42, v235
	v_fmac_f32_e32 v65, v42, v219
	v_fmac_f32_e32 v66, v42, v203
	v_fmac_f32_e32 v67, v42, v185
	v_fmac_f32_e32 v68, v42, v169
	v_fmac_f32_e32 v69, v42, v149
	v_fmac_f32_e32 v70, v42, v133
	v_fmac_f32_e32 v100, v43, v43
	v_fmac_f32_e32 v63, v43, v244
	v_fmac_f32_e32 v64, v43, v228
	v_fmac_f32_e32 v65, v43, v212
	v_fmac_f32_e32 v66, v43, v196
	v_fmac_f32_e32 v67, v43, v178
	v_fmac_f32_e32 v68, v43, v162
	v_fmac_f32_e32 v69, v43, v142
	v_fmac_f32_e32 v70, v43, v124
	v_fmac_f32_e32 v100, v44, v44
	v_fmac_f32_e32 v63, v44, v245
	v_fmac_f32_e32 v64, v44, v229
	v_fmac_f32_e32 v65, v44, v213
	v_fmac_f32_e32 v66, v44, v197
	v_fmac_f32_e32 v67, v44, v179
	v_fmac_f32_e32 v68, v44, v163
	v_fmac_f32_e32 v69, v44, v143
	v_fmac_f32_e32 v70, v44, v125
	v_fmac_f32_e32 v100, v45, v45
	v_fmac_f32_e32 v63, v45, v246
	v_fmac_f32_e32 v64, v45, v230
	v_fmac_f32_e32 v65, v45, v214
	v_fmac_f32_e32 v66, v45, v198
	v_fmac_f32_e32 v67, v45, v180
	v_fmac_f32_e32 v68, v45, v164
	v_fmac_f32_e32 v69, v45, v144
	v_fmac_f32_e32 v70, v45, v126
	v_fmac_f32_e32 v100, v46, v46
	v_fmac_f32_e32 v63, v46, v247
	v_fmac_f32_e32 v64, v46, v231
	v_fmac_f32_e32 v65, v46, v215
; __device__ __forceinline__ void fgate_phase(const bfr* x, const float* wf, const float* bfg, float* cl, float* ctot, LAS float* scr, int bx, int G, int tid, int lane, int wave) {
;     ...
;             for (int jj = 0; jj < 4; ++jj) { const u32x2 wa = xa[64 * jj], wb = xb2[64 * jj]; va[jj] = (f32x4){bf_lo(wa.x), bf_hi(wa.x), bf_lo(wa.y), bf_hi(wa.y)}; vb[jj] = (f32x4){bf_lo(wb.x), bf_hi(wb.x), bf_lo(wb.y), bf_hi(wb.y)}; }
;             r[16] = 0.f; r[17] = 0.f;
; #pragma unroll
;             for (int jj = 0; jj < 4; ++jj) { r[16] += (va[jj].x * va[jj].x + va[jj].y * va[jj].y) + (va[jj].z * va[jj].z + va[jj].w * va[jj].w); r[17] += (vb[jj].x * vb[jj].x + vb[jj].y * vb[jj].y) + (vb[jj].z * vb[jj].z + vb[jj].w * vb[jj].w); }
; #pragma unroll
;             for (int h = 0; h < NH; ++h) { const f32x4* wr = (const f32x4*)(wf + h * D) + lane + zo; float da = 0.f, db = 0.f;
; #pragma unroll
;                 for (int jj = 0; jj < 4; ++jj) { const f32x4 w = wr[64 * jj]; da += (va[jj].x * w.x + va[jj].y * w.y) + (va[jj].z * w.z + va[jj].w * w.w); db += (vb[jj].x * w.x + vb[jj].y * w.y) + (vb[jj].z * w.z + vb[jj].w * w.w); }
;                 r[h] = da; r[8 + h] = db; }
	v_fmac_f32_e32 v66, v46, v199
	v_fmac_f32_e32 v67, v46, v181
	v_fmac_f32_e32 v68, v46, v165
	v_fmac_f32_e32 v69, v46, v145
	v_fmac_f32_e32 v70, v46, v127
	v_fmac_f32_e32 v100, v47, v47
	v_fmac_f32_e32 v63, v47, v240
	v_fmac_f32_e32 v64, v47, v224
	v_fmac_f32_e32 v65, v47, v208
	v_fmac_f32_e32 v66, v47, v192
	v_fmac_f32_e32 v67, v47, v174
	v_fmac_f32_e32 v68, v47, v154
	v_fmac_f32_e32 v69, v47, v138
	v_fmac_f32_e32 v70, v47, v120
	v_fmac_f32_e32 v100, v48, v48
	v_fmac_f32_e32 v63, v48, v241
	v_fmac_f32_e32 v64, v48, v225
	v_fmac_f32_e32 v65, v48, v209
	v_fmac_f32_e32 v66, v48, v193
	v_fmac_f32_e32 v67, v48, v175
	v_fmac_f32_e32 v68, v48, v155
	v_fmac_f32_e32 v69, v48, v139
	v_fmac_f32_e32 v70, v48, v121
	v_fmac_f32_e32 v100, v49, v49
	v_fmac_f32_e32 v63, v49, v242
	v_fmac_f32_e32 v64, v49, v226
	v_fmac_f32_e32 v65, v49, v210
	v_fmac_f32_e32 v66, v49, v194
	v_fmac_f32_e32 v67, v49, v176
	v_fmac_f32_e32 v68, v49, v156
	v_fmac_f32_e32 v69, v49, v140
	v_fmac_f32_e32 v70, v49, v122
	v_fmac_f32_e32 v100, v50, v50
	v_fmac_f32_e32 v63, v50, v243
	v_fmac_f32_e32 v64, v50, v227
	v_fmac_f32_e32 v65, v50, v211
	v_fmac_f32_e32 v66, v50, v195
	v_fmac_f32_e32 v67, v50, v177
	v_fmac_f32_e32 v68, v50, v157
	v_fmac_f32_e32 v69, v50, v141
	v_fmac_f32_e32 v70, v50, v123
	v_fmac_f32_e32 v100, v51, v51
	v_fmac_f32_e32 v63, v51, v236
	v_fmac_f32_e32 v64, v51, v220
	v_fmac_f32_e32 v65, v51, v204
	v_fmac_f32_e32 v66, v51, v188
	v_fmac_f32_e32 v67, v51, v170
	v_fmac_f32_e32 v68, v51, v150
	v_fmac_f32_e32 v69, v51, v134
	v_fmac_f32_e32 v70, v51, v116
	v_fmac_f32_e32 v100, v52, v52
	v_fmac_f32_e32 v63, v52, v237
	v_fmac_f32_e32 v64, v52, v221
	v_fmac_f32_e32 v65, v52, v205
	v_fmac_f32_e32 v66, v52, v189
	v_fmac_f32_e32 v67, v52, v171
	v_fmac_f32_e32 v68, v52, v151
	v_fmac_f32_e32 v69, v52, v135
	v_fmac_f32_e32 v70, v52, v117
	v_fmac_f32_e32 v100, v53, v53
	v_fmac_f32_e32 v63, v53, v238
	v_fmac_f32_e32 v64, v53, v222
	v_fmac_f32_e32 v65, v53, v206
	v_fmac_f32_e32 v66, v53, v190
	v_fmac_f32_e32 v67, v53, v172
	v_fmac_f32_e32 v68, v53, v152
	v_fmac_f32_e32 v69, v53, v136
	v_fmac_f32_e32 v70, v53, v118
	v_fmac_f32_e32 v100, v54, v54
	v_fmac_f32_e32 v63, v54, v239
	v_fmac_f32_e32 v64, v54, v223
	v_fmac_f32_e32 v65, v54, v207
	v_fmac_f32_e32 v66, v54, v191
	v_fmac_f32_e32 v67, v54, v173
	v_fmac_f32_e32 v68, v54, v153
	v_fmac_f32_e32 v69, v54, v137
	v_fmac_f32_e32 v70, v54, v119
	v_lshlrev_b32_e32 v97, 16, v10
	v_and_b32_e32 v159, s40, v10
	v_lshlrev_b32_e32 v187, 16, v11
	v_and_b32_e32 v42, s40, v11
	v_lshlrev_b32_e32 v43, 16, v12
	v_and_b32_e32 v44, s40, v12
	v_lshlrev_b32_e32 v45, 16, v13
	v_and_b32_e32 v46, s40, v13
	v_lshlrev_b32_e32 v47, 16, v14
	v_and_b32_e32 v48, s40, v14
	v_lshlrev_b32_e32 v49, 16, v15
	v_and_b32_e32 v50, s40, v15
	v_lshlrev_b32_e32 v51, 16, v16
	v_and_b32_e32 v52, s40, v16
	v_lshlrev_b32_e32 v53, 16, v17
	v_and_b32_e32 v54, s40, v17
	v_mul_f32_e32 v101, v97, v97
	v_mul_f32_e32 v71, v97, v248
	v_mul_f32_e32 v72, v97, v232
	v_mul_f32_e32 v73, v97, v216
	v_mul_f32_e32 v74, v97, v200
	v_mul_f32_e32 v75, v97, v182
	v_mul_f32_e32 v76, v97, v166
	v_mul_f32_e32 v77, v97, v146
	v_mul_f32_e32 v78, v97, v130
	v_fmac_f32_e32 v101, v159, v159
	v_fmac_f32_e32 v71, v159, v249
	v_fmac_f32_e32 v72, v159, v233
	v_fmac_f32_e32 v73, v159, v217
	v_fmac_f32_e32 v74, v159, v201
	v_fmac_f32_e32 v75, v159, v183
	v_fmac_f32_e32 v76, v159, v167
	v_fmac_f32_e32 v77, v159, v147
	v_fmac_f32_e32 v78, v159, v131
	v_fmac_f32_e32 v101, v187, v187
	v_fmac_f32_e32 v71, v187, v250
	v_fmac_f32_e32 v72, v187, v234
	v_fmac_f32_e32 v73, v187, v218
	v_fmac_f32_e32 v74, v187, v202
	v_fmac_f32_e32 v75, v187, v184
	v_fmac_f32_e32 v76, v187, v168
	v_fmac_f32_e32 v77, v187, v148
	v_fmac_f32_e32 v78, v187, v132
	v_fmac_f32_e32 v101, v42, v42
	v_fmac_f32_e32 v71, v42, v251
	v_fmac_f32_e32 v72, v42, v235
	v_fmac_f32_e32 v73, v42, v219
	v_fmac_f32_e32 v74, v42, v203
	v_fmac_f32_e32 v75, v42, v185
	v_fmac_f32_e32 v76, v42, v169
	v_fmac_f32_e32 v77, v42, v149
	v_fmac_f32_e32 v78, v42, v133
	v_fmac_f32_e32 v101, v43, v43
	v_fmac_f32_e32 v71, v43, v244
	v_fmac_f32_e32 v72, v43, v228
	v_fmac_f32_e32 v73, v43, v212
	v_fmac_f32_e32 v74, v43, v196
	v_fmac_f32_e32 v75, v43, v178
	v_fmac_f32_e32 v76, v43, v162
	v_fmac_f32_e32 v77, v43, v142
	v_fmac_f32_e32 v78, v43, v124
	v_fmac_f32_e32 v101, v44, v44
	v_fmac_f32_e32 v71, v44, v245
	v_fmac_f32_e32 v72, v44, v229
	v_fmac_f32_e32 v73, v44, v213
	v_fmac_f32_e32 v74, v44, v197
	v_fmac_f32_e32 v75, v44, v179
	v_fmac_f32_e32 v76, v44, v163
	v_fmac_f32_e32 v77, v44, v143
	v_fmac_f32_e32 v78, v44, v125
	v_fmac_f32_e32 v101, v45, v45
	v_fmac_f32_e32 v71, v45, v246
	v_fmac_f32_e32 v72, v45, v230
	v_fmac_f32_e32 v73, v45, v214
	v_fmac_f32_e32 v74, v45, v198
	v_fmac_f32_e32 v75, v45, v180
	v_fmac_f32_e32 v76, v45, v164
	v_fmac_f32_e32 v77, v45, v144
	v_fmac_f32_e32 v78, v45, v126
	v_fmac_f32_e32 v101, v46, v46
	v_fmac_f32_e32 v71, v46, v247
	v_fmac_f32_e32 v72, v46, v231
	v_fmac_f32_e32 v73, v46, v215
	v_fmac_f32_e32 v74, v46, v199
	v_fmac_f32_e32 v75, v46, v181
	v_fmac_f32_e32 v76, v46, v165
	v_fmac_f32_e32 v77, v46, v145
	v_fmac_f32_e32 v78, v46, v127
	v_fmac_f32_e32 v101, v47, v47
	v_fmac_f32_e32 v71, v47, v240
	v_fmac_f32_e32 v72, v47, v224
	v_fmac_f32_e32 v73, v47, v208
	v_fmac_f32_e32 v74, v47, v192
	v_fmac_f32_e32 v75, v47, v174
	v_fmac_f32_e32 v76, v47, v154
	v_fmac_f32_e32 v77, v47, v138
	v_fmac_f32_e32 v78, v47, v120
	v_fmac_f32_e32 v101, v48, v48
	v_fmac_f32_e32 v71, v48, v241
	v_fmac_f32_e32 v72, v48, v225
	v_fmac_f32_e32 v73, v48, v209
	v_fmac_f32_e32 v74, v48, v193
	v_fmac_f32_e32 v75, v48, v175
	v_fmac_f32_e32 v76, v48, v155
	v_fmac_f32_e32 v77, v48, v139
; __device__ __forceinline__ void fgate_phase(const bfr* x, const float* wf, const float* bfg, float* cl, float* ctot, LAS float* scr, int bx, int G, int tid, int lane, int wave) {
;     ...
;             for (int jj = 0; jj < 4; ++jj) { const u32x2 wa = xa[64 * jj], wb = xb2[64 * jj]; va[jj] = (f32x4){bf_lo(wa.x), bf_hi(wa.x), bf_lo(wa.y), bf_hi(wa.y)}; vb[jj] = (f32x4){bf_lo(wb.x), bf_hi(wb.x), bf_lo(wb.y), bf_hi(wb.y)}; }
;             r[16] = 0.f; r[17] = 0.f;
; #pragma unroll
;             for (int jj = 0; jj < 4; ++jj) { r[16] += (va[jj].x * va[jj].x + va[jj].y * va[jj].y) + (va[jj].z * va[jj].z + va[jj].w * va[jj].w); r[17] += (vb[jj].x * vb[jj].x + vb[jj].y * vb[jj].y) + (vb[jj].z * vb[jj].z + vb[jj].w * vb[jj].w); }
; #pragma unroll
;             for (int h = 0; h < NH; ++h) { const f32x4* wr = (const f32x4*)(wf + h * D) + lane + zo; float da = 0.f, db = 0.f;
; #pragma unroll
;                 for (int jj = 0; jj < 4; ++jj) { const f32x4 w = wr[64 * jj]; da += (va[jj].x * w.x + va[jj].y * w.y) + (va[jj].z * w.z + va[jj].w * w.w); db += (vb[jj].x * w.x + vb[jj].y * w.y) + (vb[jj].z * w.z + vb[jj].w * w.w); }
;                 r[h] = da; r[8 + h] = db; }
	v_fmac_f32_e32 v78, v48, v121
	v_fmac_f32_e32 v101, v49, v49
	v_fmac_f32_e32 v71, v49, v242
	v_fmac_f32_e32 v72, v49, v226
	v_fmac_f32_e32 v73, v49, v210
	v_fmac_f32_e32 v74, v49, v194
	v_fmac_f32_e32 v75, v49, v176
	v_fmac_f32_e32 v76, v49, v156
	v_fmac_f32_e32 v77, v49, v140
	v_fmac_f32_e32 v78, v49, v122
	v_fmac_f32_e32 v101, v50, v50
	v_fmac_f32_e32 v71, v50, v243
	v_fmac_f32_e32 v72, v50, v227
	v_fmac_f32_e32 v73, v50, v211
	v_fmac_f32_e32 v74, v50, v195
	v_fmac_f32_e32 v75, v50, v177
	v_fmac_f32_e32 v76, v50, v157
	v_fmac_f32_e32 v77, v50, v141
	v_fmac_f32_e32 v78, v50, v123
	v_fmac_f32_e32 v101, v51, v51
	v_fmac_f32_e32 v71, v51, v236
	v_fmac_f32_e32 v72, v51, v220
	v_fmac_f32_e32 v73, v51, v204
	v_fmac_f32_e32 v74, v51, v188
	v_fmac_f32_e32 v75, v51, v170
	v_fmac_f32_e32 v76, v51, v150
	v_fmac_f32_e32 v77, v51, v134
	v_fmac_f32_e32 v78, v51, v116
	v_fmac_f32_e32 v101, v52, v52
	v_fmac_f32_e32 v71, v52, v237
	v_fmac_f32_e32 v72, v52, v221
	v_fmac_f32_e32 v73, v52, v205
	v_fmac_f32_e32 v74, v52, v189
	v_fmac_f32_e32 v75, v52, v171
	v_fmac_f32_e32 v76, v52, v151
	v_fmac_f32_e32 v77, v52, v135
	v_fmac_f32_e32 v78, v52, v117
	v_fmac_f32_e32 v101, v53, v53
	v_fmac_f32_e32 v71, v53, v238
	v_fmac_f32_e32 v72, v53, v222
	v_fmac_f32_e32 v73, v53, v206
	v_fmac_f32_e32 v74, v53, v190
	v_fmac_f32_e32 v75, v53, v172
	v_fmac_f32_e32 v76, v53, v152
	v_fmac_f32_e32 v77, v53, v136
	v_fmac_f32_e32 v78, v53, v118
	v_fmac_f32_e32 v101, v54, v54
	v_fmac_f32_e32 v71, v54, v239
	v_fmac_f32_e32 v72, v54, v223
	v_fmac_f32_e32 v73, v54, v207
	v_fmac_f32_e32 v74, v54, v191
	v_fmac_f32_e32 v75, v54, v173
	v_fmac_f32_e32 v76, v54, v153
	v_fmac_f32_e32 v77, v54, v137
	v_fmac_f32_e32 v78, v54, v119
	v_lshlrev_b32_e32 v97, 16, v18
	v_and_b32_e32 v159, s40, v18
	v_lshlrev_b32_e32 v187, 16, v19
	v_and_b32_e32 v42, s40, v19
	v_lshlrev_b32_e32 v43, 16, v20
	v_and_b32_e32 v44, s40, v20
	v_lshlrev_b32_e32 v45, 16, v21
	v_and_b32_e32 v46, s40, v21
	v_lshlrev_b32_e32 v47, 16, v22
	v_and_b32_e32 v48, s40, v22
	v_lshlrev_b32_e32 v49, 16, v23
	v_and_b32_e32 v50, s40, v23
	v_lshlrev_b32_e32 v51, 16, v24
	v_and_b32_e32 v52, s40, v24
	v_lshlrev_b32_e32 v53, 16, v25
	v_and_b32_e32 v54, s40, v25
	v_mul_f32_e32 v102, v97, v97
	v_mul_f32_e32 v79, v97, v248
	v_mul_f32_e32 v80, v97, v232
	v_mul_f32_e32 v81, v97, v216
	v_mul_f32_e32 v82, v97, v200
	v_mul_f32_e32 v83, v97, v182
	v_mul_f32_e32 v84, v97, v166
	v_mul_f32_e32 v85, v97, v146
	v_mul_f32_e32 v86, v97, v130
	v_fmac_f32_e32 v102, v159, v159
	v_fmac_f32_e32 v79, v159, v249
	v_fmac_f32_e32 v80, v159, v233
	v_fmac_f32_e32 v81, v159, v217
	v_fmac_f32_e32 v82, v159, v201
	v_fmac_f32_e32 v83, v159, v183
	v_fmac_f32_e32 v84, v159, v167
	v_fmac_f32_e32 v85, v159, v147
	v_fmac_f32_e32 v86, v159, v131
	v_fmac_f32_e32 v102, v187, v187
	v_fmac_f32_e32 v79, v187, v250
	v_fmac_f32_e32 v80, v187, v234
	v_fmac_f32_e32 v81, v187, v218
	v_fmac_f32_e32 v82, v187, v202
	v_fmac_f32_e32 v83, v187, v184
	v_fmac_f32_e32 v84, v187, v168
	v_fmac_f32_e32 v85, v187, v148
	v_fmac_f32_e32 v86, v187, v132
	v_fmac_f32_e32 v102, v42, v42
	v_fmac_f32_e32 v79, v42, v251
	v_fmac_f32_e32 v80, v42, v235
	v_fmac_f32_e32 v81, v42, v219
	v_fmac_f32_e32 v82, v42, v203
	v_fmac_f32_e32 v83, v42, v185
	v_fmac_f32_e32 v84, v42, v169
	v_fmac_f32_e32 v85, v42, v149
	v_fmac_f32_e32 v86, v42, v133
	v_fmac_f32_e32 v102, v43, v43
	v_fmac_f32_e32 v79, v43, v244
	v_fmac_f32_e32 v80, v43, v228
	v_fmac_f32_e32 v81, v43, v212
	v_fmac_f32_e32 v82, v43, v196
	v_fmac_f32_e32 v83, v43, v178
	v_fmac_f32_e32 v84, v43, v162
	v_fmac_f32_e32 v85, v43, v142
	v_fmac_f32_e32 v86, v43, v124
	v_fmac_f32_e32 v102, v44, v44
	v_fmac_f32_e32 v79, v44, v245
	v_fmac_f32_e32 v80, v44, v229
	v_fmac_f32_e32 v81, v44, v213
	v_fmac_f32_e32 v82, v44, v197
	v_fmac_f32_e32 v83, v44, v179
	v_fmac_f32_e32 v84, v44, v163
	v_fmac_f32_e32 v85, v44, v143
	v_fmac_f32_e32 v86, v44, v125
	v_fmac_f32_e32 v102, v45, v45
	v_fmac_f32_e32 v79, v45, v246
	v_fmac_f32_e32 v80, v45, v230
	v_fmac_f32_e32 v81, v45, v214
	v_fmac_f32_e32 v82, v45, v198
	v_fmac_f32_e32 v83, v45, v180
	v_fmac_f32_e32 v84, v45, v164
	v_fmac_f32_e32 v85, v45, v144
	v_fmac_f32_e32 v86, v45, v126
	v_fmac_f32_e32 v102, v46, v46
	v_fmac_f32_e32 v79, v46, v247
	v_fmac_f32_e32 v80, v46, v231
	v_fmac_f32_e32 v81, v46, v215
	v_fmac_f32_e32 v82, v46, v199
	v_fmac_f32_e32 v83, v46, v181
	v_fmac_f32_e32 v84, v46, v165
	v_fmac_f32_e32 v85, v46, v145
	v_fmac_f32_e32 v86, v46, v127
	v_fmac_f32_e32 v102, v47, v47
	v_fmac_f32_e32 v79, v47, v240
	v_fmac_f32_e32 v80, v47, v224
	v_fmac_f32_e32 v81, v47, v208
	v_fmac_f32_e32 v82, v47, v192
	v_fmac_f32_e32 v83, v47, v174
	v_fmac_f32_e32 v84, v47, v154
	v_fmac_f32_e32 v85, v47, v138
	v_fmac_f32_e32 v86, v47, v120
	v_fmac_f32_e32 v102, v48, v48
	v_fmac_f32_e32 v79, v48, v241
	v_fmac_f32_e32 v80, v48, v225
	v_fmac_f32_e32 v81, v48, v209
	v_fmac_f32_e32 v82, v48, v193
	v_fmac_f32_e32 v83, v48, v175
	v_fmac_f32_e32 v84, v48, v155
	v_fmac_f32_e32 v85, v48, v139
	v_fmac_f32_e32 v86, v48, v121
	v_fmac_f32_e32 v102, v49, v49
	v_fmac_f32_e32 v79, v49, v242
	v_fmac_f32_e32 v80, v49, v226
	v_fmac_f32_e32 v81, v49, v210
	v_fmac_f32_e32 v82, v49, v194
	v_fmac_f32_e32 v83, v49, v176
	v_fmac_f32_e32 v84, v49, v156
	v_fmac_f32_e32 v85, v49, v140
	v_fmac_f32_e32 v86, v49, v122
	v_fmac_f32_e32 v102, v50, v50
	v_fmac_f32_e32 v79, v50, v243
	v_fmac_f32_e32 v80, v50, v227
	v_fmac_f32_e32 v81, v50, v211
	v_fmac_f32_e32 v82, v50, v195
	v_fmac_f32_e32 v83, v50, v177
	v_fmac_f32_e32 v84, v50, v157
	v_fmac_f32_e32 v85, v50, v141
	v_fmac_f32_e32 v86, v50, v123
	v_fmac_f32_e32 v102, v51, v51
	v_fmac_f32_e32 v79, v51, v236
	v_fmac_f32_e32 v80, v51, v220
; __device__ __forceinline__ float lane_get(float v, int src_lane) { return __builtin_bit_cast(float, __builtin_amdgcn_ds_bpermute(src_lane << 2, __builtin_bit_cast(int, v))); }
; __device__ __forceinline__ void fgate_phase(const bfr* x, const float* wf, const float* bfg, float* cl, float* ctot, LAS float* scr, int bx, int G, int tid, int lane, int wave) {
;     ...
;             for (int h = 0; h < NH; ++h) { const f32x4* wr = (const f32x4*)(wf + h * D) + lane + zo; float da = 0.f, db = 0.f;
; #pragma unroll
;                 for (int jj = 0; jj < 4; ++jj) { const f32x4 w = wr[64 * jj]; da += (va[jj].x * w.x + va[jj].y * w.y) + (va[jj].z * w.z + va[jj].w * w.w); db += (vb[jj].x * w.x + vb[jj].y * w.y) + (vb[jj].z * w.z + vb[jj].w * w.w); }
;                 r[h] = da; r[8 + h] = db; }
; #pragma unroll
;             for (int o = 1; o < 64; o <<= 1) {
; #pragma unroll
;                 for (int q = 0; q < 18; ++q) r[q] += lane_get(r[q], lane ^ o); }
	v_fmac_f32_e32 v81, v51, v204
	v_fmac_f32_e32 v82, v51, v188
	v_fmac_f32_e32 v83, v51, v170
	v_fmac_f32_e32 v84, v51, v150
	v_fmac_f32_e32 v85, v51, v134
	v_fmac_f32_e32 v86, v51, v116
	v_fmac_f32_e32 v102, v52, v52
	v_fmac_f32_e32 v79, v52, v237
	v_fmac_f32_e32 v80, v52, v221
	v_fmac_f32_e32 v81, v52, v205
	v_fmac_f32_e32 v82, v52, v189
	v_fmac_f32_e32 v83, v52, v171
	v_fmac_f32_e32 v84, v52, v151
	v_fmac_f32_e32 v85, v52, v135
	v_fmac_f32_e32 v86, v52, v117
	v_fmac_f32_e32 v102, v53, v53
	v_fmac_f32_e32 v79, v53, v238
	v_fmac_f32_e32 v80, v53, v222
	v_fmac_f32_e32 v81, v53, v206
	v_fmac_f32_e32 v82, v53, v190
	v_fmac_f32_e32 v83, v53, v172
	v_fmac_f32_e32 v84, v53, v152
	v_fmac_f32_e32 v85, v53, v136
	v_fmac_f32_e32 v86, v53, v118
	v_fmac_f32_e32 v102, v54, v54
	v_fmac_f32_e32 v79, v54, v239
	v_fmac_f32_e32 v80, v54, v223
	v_fmac_f32_e32 v81, v54, v207
	v_fmac_f32_e32 v82, v54, v191
	v_fmac_f32_e32 v83, v54, v173
	v_fmac_f32_e32 v84, v54, v153
	v_fmac_f32_e32 v85, v54, v137
	v_fmac_f32_e32 v86, v54, v119
	v_lshl_add_u64 v[26:27], v[26:27], 0, s[100:101]
	v_lshl_add_u64 v[40:41], v[40:41], 0, s[100:101]
	global_load_dwordx2 v[38:39], v[26:27], off
	global_load_dwordx2 v[98:99], v[26:27], off offset:512
	global_load_dwordx2 v[160:161], v[26:27], off offset:1024
	global_load_dwordx2 v[0:1], v[26:27], off offset:1536
	global_load_dwordx2 v[2:3], v[26:27], off offset:2048
	global_load_dwordx2 v[4:5], v[26:27], off offset:2560
	global_load_dwordx2 v[6:7], v[26:27], off offset:3072
	global_load_dwordx2 v[8:9], v[26:27], off offset:3584
	global_load_dwordx2 v[10:11], v[40:41], off
	global_load_dwordx2 v[12:13], v[40:41], off offset:512
	global_load_dwordx2 v[14:15], v[40:41], off offset:1024
	global_load_dwordx2 v[16:17], v[40:41], off offset:1536
	global_load_dwordx2 v[18:19], v[40:41], off offset:2048
	global_load_dwordx2 v[20:21], v[40:41], off offset:2560
	global_load_dwordx2 v[22:23], v[40:41], off offset:3072
	global_load_dwordx2 v[24:25], v[40:41], off offset:3584
	s_nop 1
	v_permlane32_swap_b32_e32 v55, v71
	v_permlane32_swap_b32_e32 v56, v72
	v_permlane32_swap_b32_e32 v57, v73
	v_permlane32_swap_b32_e32 v58, v74
	v_permlane32_swap_b32_e32 v59, v75
	v_permlane32_swap_b32_e32 v60, v76
	v_permlane32_swap_b32_e32 v61, v77
	v_permlane32_swap_b32_e32 v62, v78
	v_permlane32_swap_b32_e32 v63, v79
	v_permlane32_swap_b32_e32 v64, v80
	v_permlane32_swap_b32_e32 v65, v81
	v_permlane32_swap_b32_e32 v66, v82
	v_permlane32_swap_b32_e32 v67, v83
	v_permlane32_swap_b32_e32 v68, v84
	v_permlane32_swap_b32_e32 v69, v85
	v_permlane32_swap_b32_e32 v70, v86
	v_permlane32_swap_b32_e32 v87, v101
	v_permlane32_swap_b32_e32 v100, v102
	s_nop 1
	v_add_f32_e32 v55, v55, v71
	v_add_f32_e32 v56, v56, v72
	v_add_f32_e32 v57, v57, v73
	v_add_f32_e32 v58, v58, v74
	v_add_f32_e32 v59, v59, v75
	v_add_f32_e32 v60, v60, v76
	v_add_f32_e32 v61, v61, v77
	v_add_f32_e32 v62, v62, v78
	v_add_f32_e32 v63, v63, v79
	v_add_f32_e32 v64, v64, v80
	v_add_f32_e32 v65, v65, v81
	v_add_f32_e32 v66, v66, v82
	v_add_f32_e32 v67, v67, v83
	v_add_f32_e32 v68, v68, v84
	v_add_f32_e32 v69, v69, v85
	v_add_f32_e32 v70, v70, v86
	v_add_f32_e32 v87, v87, v101
	v_add_f32_e32 v100, v100, v102
	s_nop 1
	v_permlane16_swap_b32_e32 v55, v63
	v_permlane16_swap_b32_e32 v56, v64
	v_permlane16_swap_b32_e32 v57, v65
	v_permlane16_swap_b32_e32 v58, v66
	v_permlane16_swap_b32_e32 v59, v67
	v_permlane16_swap_b32_e32 v60, v68
	v_permlane16_swap_b32_e32 v61, v69
	v_permlane16_swap_b32_e32 v62, v70
	v_permlane16_swap_b32_e32 v87, v100
	s_nop 1
	v_add_f32_e32 v55, v55, v63
	v_add_f32_e32 v56, v56, v64
	v_add_f32_e32 v57, v57, v65
	v_add_f32_e32 v58, v58, v66
	v_add_f32_e32 v59, v59, v67
	v_add_f32_e32 v60, v60, v68
	v_add_f32_e32 v61, v61, v69
	v_add_f32_e32 v62, v62, v70
	v_add_f32_e32 v87, v87, v100
	s_nop 1
	v_add_f32_dpp v55, v55, v55 quad_perm:[1,0,3,2] row_mask:0xf bank_mask:0xf
	v_add_f32_dpp v56, v56, v56 quad_perm:[1,0,3,2] row_mask:0xf bank_mask:0xf
	v_add_f32_dpp v57, v57, v57 quad_perm:[1,0,3,2] row_mask:0xf bank_mask:0xf
	v_add_f32_dpp v58, v58, v58 quad_perm:[1,0,3,2] row_mask:0xf bank_mask:0xf
	v_add_f32_dpp v59, v59, v59 quad_perm:[1,0,3,2] row_mask:0xf bank_mask:0xf
	v_add_f32_dpp v60, v60, v60 quad_perm:[1,0,3,2] row_mask:0xf bank_mask:0xf
	v_add_f32_dpp v61, v61, v61 quad_perm:[1,0,3,2] row_mask:0xf bank_mask:0xf
	v_add_f32_dpp v62, v62, v62 quad_perm:[1,0,3,2] row_mask:0xf bank_mask:0xf
	v_add_f32_dpp v87, v87, v87 quad_perm:[1,0,3,2] row_mask:0xf bank_mask:0xf
	s_nop 1
	v_add_f32_dpp v55, v55, v55 quad_perm:[2,3,0,1] row_mask:0xf bank_mask:0xf
	v_add_f32_dpp v56, v56, v56 quad_perm:[2,3,0,1] row_mask:0xf bank_mask:0xf
	v_add_f32_dpp v57, v57, v57 quad_perm:[2,3,0,1] row_mask:0xf bank_mask:0xf
	v_add_f32_dpp v58, v58, v58 quad_perm:[2,3,0,1] row_mask:0xf bank_mask:0xf
	v_add_f32_dpp v59, v59, v59 quad_perm:[2,3,0,1] row_mask:0xf bank_mask:0xf
	v_add_f32_dpp v60, v60, v60 quad_perm:[2,3,0,1] row_mask:0xf bank_mask:0xf
	v_add_f32_dpp v61, v61, v61 quad_perm:[2,3,0,1] row_mask:0xf bank_mask:0xf
	v_add_f32_dpp v62, v62, v62 quad_perm:[2,3,0,1] row_mask:0xf bank_mask:0xf
	v_add_f32_dpp v87, v87, v87 quad_perm:[2,3,0,1] row_mask:0xf bank_mask:0xf
	s_nop 1
	v_add_f32_dpp v55, v55, v55 row_half_mirror row_mask:0xf bank_mask:0xf
	v_add_f32_dpp v56, v56, v56 row_half_mirror row_mask:0xf bank_mask:0xf
	v_add_f32_dpp v57, v57, v57 row_half_mirror row_mask:0xf bank_mask:0xf
	v_add_f32_dpp v58, v58, v58 row_half_mirror row_mask:0xf bank_mask:0xf
	v_add_f32_dpp v59, v59, v59 row_half_mirror row_mask:0xf bank_mask:0xf
	v_add_f32_dpp v60, v60, v60 row_half_mirror row_mask:0xf bank_mask:0xf
; __device__ __forceinline__ float lane_get(float v, int src_lane) { return __builtin_bit_cast(float, __builtin_amdgcn_ds_bpermute(src_lane << 2, __builtin_bit_cast(int, v))); }
; __device__ __forceinline__ void fgate_phase(const bfr* x, const float* wf, const float* bfg, float* cl, float* ctot, LAS float* scr, int bx, int G, int tid, int lane, int wave) {
;     ...
;             for (int o = 1; o < 64; o <<= 1) {
; #pragma unroll
;                 for (int q = 0; q < 18; ++q) r[q] += lane_get(r[q], lane ^ o); }
;             const float rsa = rsqrtf(r[16] * (1.f / D) + EPS), rsb = rsqrtf(r[17] * (1.f / D) + EPS);
;             if (lane < 16) { const int h = lane & 7; float dsel = r[0];
; #pragma unroll
;                 for (int q = 1; q < 16; ++q) dsel = (lane == q) ? r[q] : dsel;
;                 const float zz = dsel * (lane < 8 ? rsa : rsb) + bfg[h]; const float lf = fminf(zz, 0.f) - 0.6931471805599453f * __builtin_amdgcn_logf(1.0f + __builtin_amdgcn_exp2f(-LOG2E * fabsf(zz)));
;                 scr[(wave * 8 + j + (lane >> 3)) * 8 + h] = lf; } }
	v_add_f32_dpp v61, v61, v61 row_half_mirror row_mask:0xf bank_mask:0xf
	v_add_f32_dpp v62, v62, v62 row_half_mirror row_mask:0xf bank_mask:0xf
	v_add_f32_dpp v87, v87, v87 row_half_mirror row_mask:0xf bank_mask:0xf
	s_nop 1
	v_add_f32_dpp v55, v55, v55 row_mirror row_mask:0xf bank_mask:0xf
	v_add_f32_dpp v56, v56, v56 row_mirror row_mask:0xf bank_mask:0xf
	v_add_f32_dpp v57, v57, v57 row_mirror row_mask:0xf bank_mask:0xf
	v_add_f32_dpp v58, v58, v58 row_mirror row_mask:0xf bank_mask:0xf
	v_add_f32_dpp v59, v59, v59 row_mirror row_mask:0xf bank_mask:0xf
	v_add_f32_dpp v60, v60, v60 row_mirror row_mask:0xf bank_mask:0xf
	v_add_f32_dpp v61, v61, v61 row_mirror row_mask:0xf bank_mask:0xf
	v_add_f32_dpp v62, v62, v62 row_mirror row_mask:0xf bank_mask:0xf
	v_add_f32_dpp v87, v87, v87 row_mirror row_mask:0xf bank_mask:0xf
	s_nop 1
	v_mov_b32_e32 v104, v55
	v_cndmask_b32_e64 v104, v104, v56, s[6:7]
	v_cndmask_b32_e64 v104, v104, v57, s[8:9]
	v_cndmask_b32_e64 v104, v104, v58, s[10:11]
	v_cndmask_b32_e64 v104, v104, v59, s[12:13]
	v_cndmask_b32_e64 v104, v104, v60, s[14:15]
	v_cndmask_b32_e64 v104, v104, v61, s[16:17]
	v_cndmask_b32_e64 v104, v104, v62, s[18:19]
	v_mul_f32_e32 v105, 0x3a800000, v87
	v_add_f32_e32 v105, 0x358637bd, v105
	v_rsq_f32_e32 v105, v105
	s_nop 0
	v_fma_f32 v104, v104, v105, v103
	v_mul_f32_e64 v105, |v104|, s65
	v_exp_f32_e32 v105, v105
	v_min_f32_e32 v104, 0, v104
	v_add_f32_e32 v105, 1.0, v105
	v_log_f32_e32 v105, v105
	s_nop 0
	v_fmac_f32_e32 v104, 0xbf317218, v105
	s_mov_b64 s[54:55], exec
	s_mov_b32 exec_lo, 0xff00ff
	s_mov_b32 exec_hi, 0xff00ff
	ds_write_b32 v107, v104
	s_mov_b64 exec, s[54:55]
	s_waitcnt vmcnt(0) lgkmcnt(0)
	v_lshlrev_b32_e32 v97, 16, v38
	v_and_b32_e32 v159, s40, v38
	v_lshlrev_b32_e32 v187, 16, v39
	v_and_b32_e32 v42, s40, v39
	v_lshlrev_b32_e32 v43, 16, v98
	v_and_b32_e32 v44, s40, v98
	v_lshlrev_b32_e32 v45, 16, v99
	v_and_b32_e32 v46, s40, v99
	v_lshlrev_b32_e32 v47, 16, v160
	v_and_b32_e32 v48, s40, v160
	v_lshlrev_b32_e32 v49, 16, v161
	v_and_b32_e32 v50, s40, v161
	v_lshlrev_b32_e32 v51, 16, v0
	v_and_b32_e32 v52, s40, v0
	v_lshlrev_b32_e32 v53, 16, v1
	v_and_b32_e32 v54, s40, v1
	v_mul_f32_e32 v87, v97, v97
	v_mul_f32_e32 v55, v97, v248
	v_mul_f32_e32 v56, v97, v232
	v_mul_f32_e32 v57, v97, v216
	v_mul_f32_e32 v58, v97, v200
	v_mul_f32_e32 v59, v97, v182
	v_mul_f32_e32 v60, v97, v166
	v_mul_f32_e32 v61, v97, v146
	v_mul_f32_e32 v62, v97, v130
	v_fmac_f32_e32 v87, v159, v159
	v_fmac_f32_e32 v55, v159, v249
	v_fmac_f32_e32 v56, v159, v233
	v_fmac_f32_e32 v57, v159, v217
	v_fmac_f32_e32 v58, v159, v201
	v_fmac_f32_e32 v59, v159, v183
	v_fmac_f32_e32 v60, v159, v167
	v_fmac_f32_e32 v61, v159, v147
	v_fmac_f32_e32 v62, v159, v131
	v_fmac_f32_e32 v87, v187, v187
	v_fmac_f32_e32 v55, v187, v250
	v_fmac_f32_e32 v56, v187, v234
	v_fmac_f32_e32 v57, v187, v218
	v_fmac_f32_e32 v58, v187, v202
	v_fmac_f32_e32 v59, v187, v184
	v_fmac_f32_e32 v60, v187, v168
	v_fmac_f32_e32 v61, v187, v148
	v_fmac_f32_e32 v62, v187, v132
	v_fmac_f32_e32 v87, v42, v42
	v_fmac_f32_e32 v55, v42, v251
	v_fmac_f32_e32 v56, v42, v235
	v_fmac_f32_e32 v57, v42, v219
	v_fmac_f32_e32 v58, v42, v203
	v_fmac_f32_e32 v59, v42, v185
	v_fmac_f32_e32 v60, v42, v169
	v_fmac_f32_e32 v61, v42, v149
	v_fmac_f32_e32 v62, v42, v133
	v_fmac_f32_e32 v87, v43, v43
	v_fmac_f32_e32 v55, v43, v244
	v_fmac_f32_e32 v56, v43, v228
	v_fmac_f32_e32 v57, v43, v212
	v_fmac_f32_e32 v58, v43, v196
	v_fmac_f32_e32 v59, v43, v178
	v_fmac_f32_e32 v60, v43, v162
	v_fmac_f32_e32 v61, v43, v142
	v_fmac_f32_e32 v62, v43, v124
	v_fmac_f32_e32 v87, v44, v44
	v_fmac_f32_e32 v55, v44, v245
	v_fmac_f32_e32 v56, v44, v229
	v_fmac_f32_e32 v57, v44, v213
	v_fmac_f32_e32 v58, v44, v197
	v_fmac_f32_e32 v59, v44, v179
	v_fmac_f32_e32 v60, v44, v163
	v_fmac_f32_e32 v61, v44, v143
	v_fmac_f32_e32 v62, v44, v125
	v_fmac_f32_e32 v87, v45, v45
	v_fmac_f32_e32 v55, v45, v246
	v_fmac_f32_e32 v56, v45, v230
	v_fmac_f32_e32 v57, v45, v214
	v_fmac_f32_e32 v58, v45, v198
	v_fmac_f32_e32 v59, v45, v180
	v_fmac_f32_e32 v60, v45, v164
	v_fmac_f32_e32 v61, v45, v144
	v_fmac_f32_e32 v62, v45, v126
	v_fmac_f32_e32 v87, v46, v46
	v_fmac_f32_e32 v55, v46, v247
	v_fmac_f32_e32 v56, v46, v231
	v_fmac_f32_e32 v57, v46, v215
	v_fmac_f32_e32 v58, v46, v199
	v_fmac_f32_e32 v59, v46, v181
	v_fmac_f32_e32 v60, v46, v165
	v_fmac_f32_e32 v61, v46, v145
	v_fmac_f32_e32 v62, v46, v127
	v_fmac_f32_e32 v87, v47, v47
	v_fmac_f32_e32 v55, v47, v240
	v_fmac_f32_e32 v56, v47, v224
	v_fmac_f32_e32 v57, v47, v208
	v_fmac_f32_e32 v58, v47, v192
	v_fmac_f32_e32 v59, v47, v174
	v_fmac_f32_e32 v60, v47, v154
	v_fmac_f32_e32 v61, v47, v138
	v_fmac_f32_e32 v62, v47, v120
	v_fmac_f32_e32 v87, v48, v48
	v_fmac_f32_e32 v55, v48, v241
	v_fmac_f32_e32 v56, v48, v225
	v_fmac_f32_e32 v57, v48, v209
	v_fmac_f32_e32 v58, v48, v193
	v_fmac_f32_e32 v59, v48, v175
	v_fmac_f32_e32 v60, v48, v155
	v_fmac_f32_e32 v61, v48, v139
	v_fmac_f32_e32 v62, v48, v121
	v_fmac_f32_e32 v87, v49, v49
	v_fmac_f32_e32 v55, v49, v242
	v_fmac_f32_e32 v56, v49, v226
	v_fmac_f32_e32 v57, v49, v210
	v_fmac_f32_e32 v58, v49, v194
	v_fmac_f32_e32 v59, v49, v176
	v_fmac_f32_e32 v60, v49, v156
	v_fmac_f32_e32 v61, v49, v140
	v_fmac_f32_e32 v62, v49, v122
	v_fmac_f32_e32 v87, v50, v50
	v_fmac_f32_e32 v55, v50, v243
	v_fmac_f32_e32 v56, v50, v227
	v_fmac_f32_e32 v57, v50, v211
	v_fmac_f32_e32 v58, v50, v195
	v_fmac_f32_e32 v59, v50, v177
	v_fmac_f32_e32 v60, v50, v157
	v_fmac_f32_e32 v61, v50, v141
	v_fmac_f32_e32 v62, v50, v123
	v_fmac_f32_e32 v87, v51, v51
	v_fmac_f32_e32 v55, v51, v236
	v_fmac_f32_e32 v56, v51, v220
	v_fmac_f32_e32 v57, v51, v204
; __device__ __forceinline__ void fgate_phase(const bfr* x, const float* wf, const float* bfg, float* cl, float* ctot, LAS float* scr, int bx, int G, int tid, int lane, int wave) {
;     ...
;             for (int jj = 0; jj < 4; ++jj) { const u32x2 wa = xa[64 * jj], wb = xb2[64 * jj]; va[jj] = (f32x4){bf_lo(wa.x), bf_hi(wa.x), bf_lo(wa.y), bf_hi(wa.y)}; vb[jj] = (f32x4){bf_lo(wb.x), bf_hi(wb.x), bf_lo(wb.y), bf_hi(wb.y)}; }
;             r[16] = 0.f; r[17] = 0.f;
; #pragma unroll
;             for (int jj = 0; jj < 4; ++jj) { r[16] += (va[jj].x * va[jj].x + va[jj].y * va[jj].y) + (va[jj].z * va[jj].z + va[jj].w * va[jj].w); r[17] += (vb[jj].x * vb[jj].x + vb[jj].y * vb[jj].y) + (vb[jj].z * vb[jj].z + vb[jj].w * vb[jj].w); }
; #pragma unroll
;             for (int h = 0; h < NH; ++h) { const f32x4* wr = (const f32x4*)(wf + h * D) + lane + zo; float da = 0.f, db = 0.f;
; #pragma unroll
;                 for (int jj = 0; jj < 4; ++jj) { const f32x4 w = wr[64 * jj]; da += (va[jj].x * w.x + va[jj].y * w.y) + (va[jj].z * w.z + va[jj].w * w.w); db += (vb[jj].x * w.x + vb[jj].y * w.y) + (vb[jj].z * w.z + vb[jj].w * w.w); }
;                 r[h] = da; r[8 + h] = db; }
	v_fmac_f32_e32 v58, v51, v188
	v_fmac_f32_e32 v59, v51, v170
	v_fmac_f32_e32 v60, v51, v150
	v_fmac_f32_e32 v61, v51, v134
	v_fmac_f32_e32 v62, v51, v116
	v_fmac_f32_e32 v87, v52, v52
	v_fmac_f32_e32 v55, v52, v237
	v_fmac_f32_e32 v56, v52, v221
	v_fmac_f32_e32 v57, v52, v205
	v_fmac_f32_e32 v58, v52, v189
	v_fmac_f32_e32 v59, v52, v171
	v_fmac_f32_e32 v60, v52, v151
	v_fmac_f32_e32 v61, v52, v135
	v_fmac_f32_e32 v62, v52, v117
	v_fmac_f32_e32 v87, v53, v53
	v_fmac_f32_e32 v55, v53, v238
	v_fmac_f32_e32 v56, v53, v222
	v_fmac_f32_e32 v57, v53, v206
	v_fmac_f32_e32 v58, v53, v190
	v_fmac_f32_e32 v59, v53, v172
	v_fmac_f32_e32 v60, v53, v152
	v_fmac_f32_e32 v61, v53, v136
	v_fmac_f32_e32 v62, v53, v118
	v_fmac_f32_e32 v87, v54, v54
	v_fmac_f32_e32 v55, v54, v239
	v_fmac_f32_e32 v56, v54, v223
	v_fmac_f32_e32 v57, v54, v207
	v_fmac_f32_e32 v58, v54, v191
	v_fmac_f32_e32 v59, v54, v173
	v_fmac_f32_e32 v60, v54, v153
	v_fmac_f32_e32 v61, v54, v137
	v_fmac_f32_e32 v62, v54, v119
	v_lshlrev_b32_e32 v97, 16, v2
	v_and_b32_e32 v159, s40, v2
	v_lshlrev_b32_e32 v187, 16, v3
	v_and_b32_e32 v42, s40, v3
	v_lshlrev_b32_e32 v43, 16, v4
	v_and_b32_e32 v44, s40, v4
	v_lshlrev_b32_e32 v45, 16, v5
	v_and_b32_e32 v46, s40, v5
	v_lshlrev_b32_e32 v47, 16, v6
	v_and_b32_e32 v48, s40, v6
	v_lshlrev_b32_e32 v49, 16, v7
	v_and_b32_e32 v50, s40, v7
	v_lshlrev_b32_e32 v51, 16, v8
	v_and_b32_e32 v52, s40, v8
	v_lshlrev_b32_e32 v53, 16, v9
	v_and_b32_e32 v54, s40, v9
	v_mul_f32_e32 v100, v97, v97
	v_mul_f32_e32 v63, v97, v248
	v_mul_f32_e32 v64, v97, v232
	v_mul_f32_e32 v65, v97, v216
	v_mul_f32_e32 v66, v97, v200
	v_mul_f32_e32 v67, v97, v182
	v_mul_f32_e32 v68, v97, v166
	v_mul_f32_e32 v69, v97, v146
	v_mul_f32_e32 v70, v97, v130
	v_fmac_f32_e32 v100, v159, v159
	v_fmac_f32_e32 v63, v159, v249
	v_fmac_f32_e32 v64, v159, v233
	v_fmac_f32_e32 v65, v159, v217
	v_fmac_f32_e32 v66, v159, v201
	v_fmac_f32_e32 v67, v159, v183
	v_fmac_f32_e32 v68, v159, v167
	v_fmac_f32_e32 v69, v159, v147
	v_fmac_f32_e32 v70, v159, v131
	v_fmac_f32_e32 v100, v187, v187
	v_fmac_f32_e32 v63, v187, v250
	v_fmac_f32_e32 v64, v187, v234
	v_fmac_f32_e32 v65, v187, v218
	v_fmac_f32_e32 v66, v187, v202
	v_fmac_f32_e32 v67, v187, v184
	v_fmac_f32_e32 v68, v187, v168
	v_fmac_f32_e32 v69, v187, v148
	v_fmac_f32_e32 v70, v187, v132
	v_fmac_f32_e32 v100, v42, v42
	v_fmac_f32_e32 v63, v42, v251
	v_fmac_f32_e32 v64, v42, v235
	v_fmac_f32_e32 v65, v42, v219
	v_fmac_f32_e32 v66, v42, v203
	v_fmac_f32_e32 v67, v42, v185
	v_fmac_f32_e32 v68, v42, v169
	v_fmac_f32_e32 v69, v42, v149
	v_fmac_f32_e32 v70, v42, v133
	v_fmac_f32_e32 v100, v43, v43
	v_fmac_f32_e32 v63, v43, v244
	v_fmac_f32_e32 v64, v43, v228
	v_fmac_f32_e32 v65, v43, v212
	v_fmac_f32_e32 v66, v43, v196
	v_fmac_f32_e32 v67, v43, v178
	v_fmac_f32_e32 v68, v43, v162
	v_fmac_f32_e32 v69, v43, v142
	v_fmac_f32_e32 v70, v43, v124
	v_fmac_f32_e32 v100, v44, v44
	v_fmac_f32_e32 v63, v44, v245
	v_fmac_f32_e32 v64, v44, v229
	v_fmac_f32_e32 v65, v44, v213
	v_fmac_f32_e32 v66, v44, v197
	v_fmac_f32_e32 v67, v44, v179
	v_fmac_f32_e32 v68, v44, v163
	v_fmac_f32_e32 v69, v44, v143
	v_fmac_f32_e32 v70, v44, v125
	v_fmac_f32_e32 v100, v45, v45
	v_fmac_f32_e32 v63, v45, v246
	v_fmac_f32_e32 v64, v45, v230
	v_fmac_f32_e32 v65, v45, v214
	v_fmac_f32_e32 v66, v45, v198
	v_fmac_f32_e32 v67, v45, v180
	v_fmac_f32_e32 v68, v45, v164
	v_fmac_f32_e32 v69, v45, v144
	v_fmac_f32_e32 v70, v45, v126
	v_fmac_f32_e32 v100, v46, v46
	v_fmac_f32_e32 v63, v46, v247
	v_fmac_f32_e32 v64, v46, v231
	v_fmac_f32_e32 v65, v46, v215
	v_fmac_f32_e32 v66, v46, v199
	v_fmac_f32_e32 v67, v46, v181
	v_fmac_f32_e32 v68, v46, v165
	v_fmac_f32_e32 v69, v46, v145
	v_fmac_f32_e32 v70, v46, v127
	v_fmac_f32_e32 v100, v47, v47
	v_fmac_f32_e32 v63, v47, v240
	v_fmac_f32_e32 v64, v47, v224
	v_fmac_f32_e32 v65, v47, v208
	v_fmac_f32_e32 v66, v47, v192
	v_fmac_f32_e32 v67, v47, v174
	v_fmac_f32_e32 v68, v47, v154
	v_fmac_f32_e32 v69, v47, v138
	v_fmac_f32_e32 v70, v47, v120
	v_fmac_f32_e32 v100, v48, v48
	v_fmac_f32_e32 v63, v48, v241
	v_fmac_f32_e32 v64, v48, v225
	v_fmac_f32_e32 v65, v48, v209
	v_fmac_f32_e32 v66, v48, v193
	v_fmac_f32_e32 v67, v48, v175
	v_fmac_f32_e32 v68, v48, v155
	v_fmac_f32_e32 v69, v48, v139
	v_fmac_f32_e32 v70, v48, v121
	v_fmac_f32_e32 v100, v49, v49
	v_fmac_f32_e32 v63, v49, v242
	v_fmac_f32_e32 v64, v49, v226
	v_fmac_f32_e32 v65, v49, v210
	v_fmac_f32_e32 v66, v49, v194
	v_fmac_f32_e32 v67, v49, v176
	v_fmac_f32_e32 v68, v49, v156
	v_fmac_f32_e32 v69, v49, v140
	v_fmac_f32_e32 v70, v49, v122
	v_fmac_f32_e32 v100, v50, v50
	v_fmac_f32_e32 v63, v50, v243
	v_fmac_f32_e32 v64, v50, v227
	v_fmac_f32_e32 v65, v50, v211
	v_fmac_f32_e32 v66, v50, v195
	v_fmac_f32_e32 v67, v50, v177
	v_fmac_f32_e32 v68, v50, v157
	v_fmac_f32_e32 v69, v50, v141
	v_fmac_f32_e32 v70, v50, v123
	v_fmac_f32_e32 v100, v51, v51
	v_fmac_f32_e32 v63, v51, v236
	v_fmac_f32_e32 v64, v51, v220
	v_fmac_f32_e32 v65, v51, v204
	v_fmac_f32_e32 v66, v51, v188
	v_fmac_f32_e32 v67, v51, v170
	v_fmac_f32_e32 v68, v51, v150
	v_fmac_f32_e32 v69, v51, v134
	v_fmac_f32_e32 v70, v51, v116
	v_fmac_f32_e32 v100, v52, v52
	v_fmac_f32_e32 v63, v52, v237
	v_fmac_f32_e32 v64, v52, v221
	v_fmac_f32_e32 v65, v52, v205
	v_fmac_f32_e32 v66, v52, v189
	v_fmac_f32_e32 v67, v52, v171
	v_fmac_f32_e32 v68, v52, v151
	v_fmac_f32_e32 v69, v52, v135
	v_fmac_f32_e32 v70, v52, v117
	v_fmac_f32_e32 v100, v53, v53
	v_fmac_f32_e32 v63, v53, v238
	v_fmac_f32_e32 v64, v53, v222
	v_fmac_f32_e32 v65, v53, v206
	v_fmac_f32_e32 v66, v53, v190
	v_fmac_f32_e32 v67, v53, v172
	v_fmac_f32_e32 v68, v53, v152
	v_fmac_f32_e32 v69, v53, v136
; __device__ __forceinline__ void fgate_phase(const bfr* x, const float* wf, const float* bfg, float* cl, float* ctot, LAS float* scr, int bx, int G, int tid, int lane, int wave) {
;     ...
;             for (int jj = 0; jj < 4; ++jj) { const u32x2 wa = xa[64 * jj], wb = xb2[64 * jj]; va[jj] = (f32x4){bf_lo(wa.x), bf_hi(wa.x), bf_lo(wa.y), bf_hi(wa.y)}; vb[jj] = (f32x4){bf_lo(wb.x), bf_hi(wb.x), bf_lo(wb.y), bf_hi(wb.y)}; }
;             r[16] = 0.f; r[17] = 0.f;
; #pragma unroll
;             for (int jj = 0; jj < 4; ++jj) { r[16] += (va[jj].x * va[jj].x + va[jj].y * va[jj].y) + (va[jj].z * va[jj].z + va[jj].w * va[jj].w); r[17] += (vb[jj].x * vb[jj].x + vb[jj].y * vb[jj].y) + (vb[jj].z * vb[jj].z + vb[jj].w * vb[jj].w); }
; #pragma unroll
;             for (int h = 0; h < NH; ++h) { const f32x4* wr = (const f32x4*)(wf + h * D) + lane + zo; float da = 0.f, db = 0.f;
; #pragma unroll
;                 for (int jj = 0; jj < 4; ++jj) { const f32x4 w = wr[64 * jj]; da += (va[jj].x * w.x + va[jj].y * w.y) + (va[jj].z * w.z + va[jj].w * w.w); db += (vb[jj].x * w.x + vb[jj].y * w.y) + (vb[jj].z * w.z + vb[jj].w * w.w); }
;                 r[h] = da; r[8 + h] = db; }
	v_fmac_f32_e32 v70, v53, v118
	v_fmac_f32_e32 v100, v54, v54
	v_fmac_f32_e32 v63, v54, v239
	v_fmac_f32_e32 v64, v54, v223
	v_fmac_f32_e32 v65, v54, v207
	v_fmac_f32_e32 v66, v54, v191
	v_fmac_f32_e32 v67, v54, v173
	v_fmac_f32_e32 v68, v54, v153
	v_fmac_f32_e32 v69, v54, v137
	v_fmac_f32_e32 v70, v54, v119
	v_lshlrev_b32_e32 v97, 16, v10
	v_and_b32_e32 v159, s40, v10
	v_lshlrev_b32_e32 v187, 16, v11
	v_and_b32_e32 v42, s40, v11
	v_lshlrev_b32_e32 v43, 16, v12
	v_and_b32_e32 v44, s40, v12
	v_lshlrev_b32_e32 v45, 16, v13
	v_and_b32_e32 v46, s40, v13
	v_lshlrev_b32_e32 v47, 16, v14
	v_and_b32_e32 v48, s40, v14
	v_lshlrev_b32_e32 v49, 16, v15
	v_and_b32_e32 v50, s40, v15
	v_lshlrev_b32_e32 v51, 16, v16
	v_and_b32_e32 v52, s40, v16
	v_lshlrev_b32_e32 v53, 16, v17
	v_and_b32_e32 v54, s40, v17
	v_mul_f32_e32 v101, v97, v97
	v_mul_f32_e32 v71, v97, v248
	v_mul_f32_e32 v72, v97, v232
	v_mul_f32_e32 v73, v97, v216
	v_mul_f32_e32 v74, v97, v200
	v_mul_f32_e32 v75, v97, v182
	v_mul_f32_e32 v76, v97, v166
	v_mul_f32_e32 v77, v97, v146
	v_mul_f32_e32 v78, v97, v130
	v_fmac_f32_e32 v101, v159, v159
	v_fmac_f32_e32 v71, v159, v249
	v_fmac_f32_e32 v72, v159, v233
	v_fmac_f32_e32 v73, v159, v217
	v_fmac_f32_e32 v74, v159, v201
	v_fmac_f32_e32 v75, v159, v183
	v_fmac_f32_e32 v76, v159, v167
	v_fmac_f32_e32 v77, v159, v147
	v_fmac_f32_e32 v78, v159, v131
	v_fmac_f32_e32 v101, v187, v187
	v_fmac_f32_e32 v71, v187, v250
	v_fmac_f32_e32 v72, v187, v234
	v_fmac_f32_e32 v73, v187, v218
	v_fmac_f32_e32 v74, v187, v202
	v_fmac_f32_e32 v75, v187, v184
	v_fmac_f32_e32 v76, v187, v168
	v_fmac_f32_e32 v77, v187, v148
	v_fmac_f32_e32 v78, v187, v132
	v_fmac_f32_e32 v101, v42, v42
	v_fmac_f32_e32 v71, v42, v251
	v_fmac_f32_e32 v72, v42, v235
	v_fmac_f32_e32 v73, v42, v219
	v_fmac_f32_e32 v74, v42, v203
	v_fmac_f32_e32 v75, v42, v185
	v_fmac_f32_e32 v76, v42, v169
	v_fmac_f32_e32 v77, v42, v149
	v_fmac_f32_e32 v78, v42, v133
	v_fmac_f32_e32 v101, v43, v43
	v_fmac_f32_e32 v71, v43, v244
	v_fmac_f32_e32 v72, v43, v228
	v_fmac_f32_e32 v73, v43, v212
	v_fmac_f32_e32 v74, v43, v196
	v_fmac_f32_e32 v75, v43, v178
	v_fmac_f32_e32 v76, v43, v162
	v_fmac_f32_e32 v77, v43, v142
	v_fmac_f32_e32 v78, v43, v124
	v_fmac_f32_e32 v101, v44, v44
	v_fmac_f32_e32 v71, v44, v245
	v_fmac_f32_e32 v72, v44, v229
	v_fmac_f32_e32 v73, v44, v213
	v_fmac_f32_e32 v74, v44, v197
	v_fmac_f32_e32 v75, v44, v179
	v_fmac_f32_e32 v76, v44, v163
	v_fmac_f32_e32 v77, v44, v143
	v_fmac_f32_e32 v78, v44, v125
	v_fmac_f32_e32 v101, v45, v45
	v_fmac_f32_e32 v71, v45, v246
	v_fmac_f32_e32 v72, v45, v230
	v_fmac_f32_e32 v73, v45, v214
	v_fmac_f32_e32 v74, v45, v198
	v_fmac_f32_e32 v75, v45, v180
	v_fmac_f32_e32 v76, v45, v164
	v_fmac_f32_e32 v77, v45, v144
	v_fmac_f32_e32 v78, v45, v126
	v_fmac_f32_e32 v101, v46, v46
	v_fmac_f32_e32 v71, v46, v247
	v_fmac_f32_e32 v72, v46, v231
	v_fmac_f32_e32 v73, v46, v215
	v_fmac_f32_e32 v74, v46, v199
	v_fmac_f32_e32 v75, v46, v181
	v_fmac_f32_e32 v76, v46, v165
	v_fmac_f32_e32 v77, v46, v145
	v_fmac_f32_e32 v78, v46, v127
	v_fmac_f32_e32 v101, v47, v47
	v_fmac_f32_e32 v71, v47, v240
	v_fmac_f32_e32 v72, v47, v224
	v_fmac_f32_e32 v73, v47, v208
	v_fmac_f32_e32 v74, v47, v192
	v_fmac_f32_e32 v75, v47, v174
	v_fmac_f32_e32 v76, v47, v154
	v_fmac_f32_e32 v77, v47, v138
	v_fmac_f32_e32 v78, v47, v120
	v_fmac_f32_e32 v101, v48, v48
	v_fmac_f32_e32 v71, v48, v241
	v_fmac_f32_e32 v72, v48, v225
	v_fmac_f32_e32 v73, v48, v209
	v_fmac_f32_e32 v74, v48, v193
	v_fmac_f32_e32 v75, v48, v175
	v_fmac_f32_e32 v76, v48, v155
	v_fmac_f32_e32 v77, v48, v139
	v_fmac_f32_e32 v78, v48, v121
	v_fmac_f32_e32 v101, v49, v49
	v_fmac_f32_e32 v71, v49, v242
	v_fmac_f32_e32 v72, v49, v226
	v_fmac_f32_e32 v73, v49, v210
	v_fmac_f32_e32 v74, v49, v194
	v_fmac_f32_e32 v75, v49, v176
	v_fmac_f32_e32 v76, v49, v156
	v_fmac_f32_e32 v77, v49, v140
	v_fmac_f32_e32 v78, v49, v122
	v_fmac_f32_e32 v101, v50, v50
	v_fmac_f32_e32 v71, v50, v243
	v_fmac_f32_e32 v72, v50, v227
	v_fmac_f32_e32 v73, v50, v211
	v_fmac_f32_e32 v74, v50, v195
	v_fmac_f32_e32 v75, v50, v177
	v_fmac_f32_e32 v76, v50, v157
	v_fmac_f32_e32 v77, v50, v141
	v_fmac_f32_e32 v78, v50, v123
	v_fmac_f32_e32 v101, v51, v51
	v_fmac_f32_e32 v71, v51, v236
	v_fmac_f32_e32 v72, v51, v220
	v_fmac_f32_e32 v73, v51, v204
	v_fmac_f32_e32 v74, v51, v188
	v_fmac_f32_e32 v75, v51, v170
	v_fmac_f32_e32 v76, v51, v150
	v_fmac_f32_e32 v77, v51, v134
	v_fmac_f32_e32 v78, v51, v116
	v_fmac_f32_e32 v101, v52, v52
	v_fmac_f32_e32 v71, v52, v237
	v_fmac_f32_e32 v72, v52, v221
	v_fmac_f32_e32 v73, v52, v205
	v_fmac_f32_e32 v74, v52, v189
	v_fmac_f32_e32 v75, v52, v171
	v_fmac_f32_e32 v76, v52, v151
	v_fmac_f32_e32 v77, v52, v135
	v_fmac_f32_e32 v78, v52, v117
	v_fmac_f32_e32 v101, v53, v53
	v_fmac_f32_e32 v71, v53, v238
	v_fmac_f32_e32 v72, v53, v222
	v_fmac_f32_e32 v73, v53, v206
	v_fmac_f32_e32 v74, v53, v190
	v_fmac_f32_e32 v75, v53, v172
	v_fmac_f32_e32 v76, v53, v152
	v_fmac_f32_e32 v77, v53, v136
	v_fmac_f32_e32 v78, v53, v118
	v_fmac_f32_e32 v101, v54, v54
	v_fmac_f32_e32 v71, v54, v239
	v_fmac_f32_e32 v72, v54, v223
	v_fmac_f32_e32 v73, v54, v207
	v_fmac_f32_e32 v74, v54, v191
	v_fmac_f32_e32 v75, v54, v173
	v_fmac_f32_e32 v76, v54, v153
	v_fmac_f32_e32 v77, v54, v137
	v_fmac_f32_e32 v78, v54, v119
	v_lshlrev_b32_e32 v97, 16, v18
	v_and_b32_e32 v159, s40, v18
	v_lshlrev_b32_e32 v187, 16, v19
	v_and_b32_e32 v42, s40, v19
	v_lshlrev_b32_e32 v43, 16, v20
	v_and_b32_e32 v44, s40, v20
	v_lshlrev_b32_e32 v45, 16, v21
	v_and_b32_e32 v46, s40, v21
	v_lshlrev_b32_e32 v47, 16, v22
	v_and_b32_e32 v48, s40, v22
	v_lshlrev_b32_e32 v49, 16, v23
	v_and_b32_e32 v50, s40, v23
; __device__ __forceinline__ float lane_get(float v, int src_lane) { return __builtin_bit_cast(float, __builtin_amdgcn_ds_bpermute(src_lane << 2, __builtin_bit_cast(int, v))); }
; __device__ __forceinline__ void fgate_phase(const bfr* x, const float* wf, const float* bfg, float* cl, float* ctot, LAS float* scr, int bx, int G, int tid, int lane, int wave) {
;     ...
;             for (int h = 0; h < NH; ++h) { const f32x4* wr = (const f32x4*)(wf + h * D) + lane + zo; float da = 0.f, db = 0.f;
; #pragma unroll
;                 for (int jj = 0; jj < 4; ++jj) { const f32x4 w = wr[64 * jj]; da += (va[jj].x * w.x + va[jj].y * w.y) + (va[jj].z * w.z + va[jj].w * w.w); db += (vb[jj].x * w.x + vb[jj].y * w.y) + (vb[jj].z * w.z + vb[jj].w * w.w); }
;                 r[h] = da; r[8 + h] = db; }
; #pragma unroll
;             for (int o = 1; o < 64; o <<= 1) {
; #pragma unroll
;                 for (int q = 0; q < 18; ++q) r[q] += lane_get(r[q], lane ^ o); }
	v_lshlrev_b32_e32 v51, 16, v24
	v_and_b32_e32 v52, s40, v24
	v_lshlrev_b32_e32 v53, 16, v25
	v_and_b32_e32 v54, s40, v25
	v_mul_f32_e32 v102, v97, v97
	v_mul_f32_e32 v79, v97, v248
	v_mul_f32_e32 v80, v97, v232
	v_mul_f32_e32 v81, v97, v216
	v_mul_f32_e32 v82, v97, v200
	v_mul_f32_e32 v83, v97, v182
	v_mul_f32_e32 v84, v97, v166
	v_mul_f32_e32 v85, v97, v146
	v_mul_f32_e32 v86, v97, v130
	v_fmac_f32_e32 v102, v159, v159
	v_fmac_f32_e32 v79, v159, v249
	v_fmac_f32_e32 v80, v159, v233
	v_fmac_f32_e32 v81, v159, v217
	v_fmac_f32_e32 v82, v159, v201
	v_fmac_f32_e32 v83, v159, v183
	v_fmac_f32_e32 v84, v159, v167
	v_fmac_f32_e32 v85, v159, v147
	v_fmac_f32_e32 v86, v159, v131
	v_fmac_f32_e32 v102, v187, v187
	v_fmac_f32_e32 v79, v187, v250
	v_fmac_f32_e32 v80, v187, v234
	v_fmac_f32_e32 v81, v187, v218
	v_fmac_f32_e32 v82, v187, v202
	v_fmac_f32_e32 v83, v187, v184
	v_fmac_f32_e32 v84, v187, v168
	v_fmac_f32_e32 v85, v187, v148
	v_fmac_f32_e32 v86, v187, v132
	v_fmac_f32_e32 v102, v42, v42
	v_fmac_f32_e32 v79, v42, v251
	v_fmac_f32_e32 v80, v42, v235
	v_fmac_f32_e32 v81, v42, v219
	v_fmac_f32_e32 v82, v42, v203
	v_fmac_f32_e32 v83, v42, v185
	v_fmac_f32_e32 v84, v42, v169
	v_fmac_f32_e32 v85, v42, v149
	v_fmac_f32_e32 v86, v42, v133
	v_fmac_f32_e32 v102, v43, v43
	v_fmac_f32_e32 v79, v43, v244
	v_fmac_f32_e32 v80, v43, v228
	v_fmac_f32_e32 v81, v43, v212
	v_fmac_f32_e32 v82, v43, v196
	v_fmac_f32_e32 v83, v43, v178
	v_fmac_f32_e32 v84, v43, v162
	v_fmac_f32_e32 v85, v43, v142
	v_fmac_f32_e32 v86, v43, v124
	v_fmac_f32_e32 v102, v44, v44
	v_fmac_f32_e32 v79, v44, v245
	v_fmac_f32_e32 v80, v44, v229
	v_fmac_f32_e32 v81, v44, v213
	v_fmac_f32_e32 v82, v44, v197
	v_fmac_f32_e32 v83, v44, v179
	v_fmac_f32_e32 v84, v44, v163
	v_fmac_f32_e32 v85, v44, v143
	v_fmac_f32_e32 v86, v44, v125
	v_fmac_f32_e32 v102, v45, v45
	v_fmac_f32_e32 v79, v45, v246
	v_fmac_f32_e32 v80, v45, v230
	v_fmac_f32_e32 v81, v45, v214
	v_fmac_f32_e32 v82, v45, v198
	v_fmac_f32_e32 v83, v45, v180
	v_fmac_f32_e32 v84, v45, v164
	v_fmac_f32_e32 v85, v45, v144
	v_fmac_f32_e32 v86, v45, v126
	v_fmac_f32_e32 v102, v46, v46
	v_fmac_f32_e32 v79, v46, v247
	v_fmac_f32_e32 v80, v46, v231
	v_fmac_f32_e32 v81, v46, v215
	v_fmac_f32_e32 v82, v46, v199
	v_fmac_f32_e32 v83, v46, v181
	v_fmac_f32_e32 v84, v46, v165
	v_fmac_f32_e32 v85, v46, v145
	v_fmac_f32_e32 v86, v46, v127
	v_fmac_f32_e32 v102, v47, v47
	v_fmac_f32_e32 v79, v47, v240
	v_fmac_f32_e32 v80, v47, v224
	v_fmac_f32_e32 v81, v47, v208
	v_fmac_f32_e32 v82, v47, v192
	v_fmac_f32_e32 v83, v47, v174
	v_fmac_f32_e32 v84, v47, v154
	v_fmac_f32_e32 v85, v47, v138
	v_fmac_f32_e32 v86, v47, v120
	v_fmac_f32_e32 v102, v48, v48
	v_fmac_f32_e32 v79, v48, v241
	v_fmac_f32_e32 v80, v48, v225
	v_fmac_f32_e32 v81, v48, v209
	v_fmac_f32_e32 v82, v48, v193
	v_fmac_f32_e32 v83, v48, v175
	v_fmac_f32_e32 v84, v48, v155
	v_fmac_f32_e32 v85, v48, v139
	v_fmac_f32_e32 v86, v48, v121
	v_fmac_f32_e32 v102, v49, v49
	v_fmac_f32_e32 v79, v49, v242
	v_fmac_f32_e32 v80, v49, v226
	v_fmac_f32_e32 v81, v49, v210
	v_fmac_f32_e32 v82, v49, v194
	v_fmac_f32_e32 v83, v49, v176
	v_fmac_f32_e32 v84, v49, v156
	v_fmac_f32_e32 v85, v49, v140
	v_fmac_f32_e32 v86, v49, v122
	v_fmac_f32_e32 v102, v50, v50
	v_fmac_f32_e32 v79, v50, v243
	v_fmac_f32_e32 v80, v50, v227
	v_fmac_f32_e32 v81, v50, v211
	v_fmac_f32_e32 v82, v50, v195
	v_fmac_f32_e32 v83, v50, v177
	v_fmac_f32_e32 v84, v50, v157
	v_fmac_f32_e32 v85, v50, v141
	v_fmac_f32_e32 v86, v50, v123
	v_fmac_f32_e32 v102, v51, v51
	v_fmac_f32_e32 v79, v51, v236
	v_fmac_f32_e32 v80, v51, v220
	v_fmac_f32_e32 v81, v51, v204
	v_fmac_f32_e32 v82, v51, v188
	v_fmac_f32_e32 v83, v51, v170
	v_fmac_f32_e32 v84, v51, v150
	v_fmac_f32_e32 v85, v51, v134
	v_fmac_f32_e32 v86, v51, v116
	v_fmac_f32_e32 v102, v52, v52
	v_fmac_f32_e32 v79, v52, v237
	v_fmac_f32_e32 v80, v52, v221
	v_fmac_f32_e32 v81, v52, v205
	v_fmac_f32_e32 v82, v52, v189
	v_fmac_f32_e32 v83, v52, v171
	v_fmac_f32_e32 v84, v52, v151
	v_fmac_f32_e32 v85, v52, v135
	v_fmac_f32_e32 v86, v52, v117
	v_fmac_f32_e32 v102, v53, v53
	v_fmac_f32_e32 v79, v53, v238
	v_fmac_f32_e32 v80, v53, v222
	v_fmac_f32_e32 v81, v53, v206
	v_fmac_f32_e32 v82, v53, v190
	v_fmac_f32_e32 v83, v53, v172
	v_fmac_f32_e32 v84, v53, v152
	v_fmac_f32_e32 v85, v53, v136
	v_fmac_f32_e32 v86, v53, v118
	v_fmac_f32_e32 v102, v54, v54
	v_fmac_f32_e32 v79, v54, v239
	v_fmac_f32_e32 v80, v54, v223
	v_fmac_f32_e32 v81, v54, v207
	v_fmac_f32_e32 v82, v54, v191
	v_fmac_f32_e32 v83, v54, v173
	v_fmac_f32_e32 v84, v54, v153
	v_fmac_f32_e32 v85, v54, v137
	v_fmac_f32_e32 v86, v54, v119
	s_nop 1
	v_permlane32_swap_b32_e32 v55, v71
	v_permlane32_swap_b32_e32 v56, v72
	v_permlane32_swap_b32_e32 v57, v73
	v_permlane32_swap_b32_e32 v58, v74
	v_permlane32_swap_b32_e32 v59, v75
	v_permlane32_swap_b32_e32 v60, v76
	v_permlane32_swap_b32_e32 v61, v77
	v_permlane32_swap_b32_e32 v62, v78
	v_permlane32_swap_b32_e32 v63, v79
; __device__ __forceinline__ float lane_get(float v, int src_lane) { return __builtin_bit_cast(float, __builtin_amdgcn_ds_bpermute(src_lane << 2, __builtin_bit_cast(int, v))); }
; __device__ __forceinline__ void fgate_phase(const bfr* x, const float* wf, const float* bfg, float* cl, float* ctot, LAS float* scr, int bx, int G, int tid, int lane, int wave) {
;     ...
;             for (int o = 1; o < 64; o <<= 1) {
; #pragma unroll
;                 for (int q = 0; q < 18; ++q) r[q] += lane_get(r[q], lane ^ o); }
;             const float rsa = rsqrtf(r[16] * (1.f / D) + EPS), rsb = rsqrtf(r[17] * (1.f / D) + EPS);
;             if (lane < 16) { const int h = lane & 7; float dsel = r[0];
; #pragma unroll
;                 for (int q = 1; q < 16; ++q) dsel = (lane == q) ? r[q] : dsel;
;                 const float zz = dsel * (lane < 8 ? rsa : rsb) + bfg[h]; const float lf = fminf(zz, 0.f) - 0.6931471805599453f * __builtin_amdgcn_logf(1.0f + __builtin_amdgcn_exp2f(-LOG2E * fabsf(zz)));
;                 scr[(wave * 8 + j + (lane >> 3)) * 8 + h] = lf; } }
	v_permlane32_swap_b32_e32 v64, v80
	v_permlane32_swap_b32_e32 v65, v81
	v_permlane32_swap_b32_e32 v66, v82
	v_permlane32_swap_b32_e32 v67, v83
	v_permlane32_swap_b32_e32 v68, v84
	v_permlane32_swap_b32_e32 v69, v85
	v_permlane32_swap_b32_e32 v70, v86
	v_permlane32_swap_b32_e32 v87, v101
	v_permlane32_swap_b32_e32 v100, v102
	s_nop 1
	v_add_f32_e32 v55, v55, v71
	v_add_f32_e32 v56, v56, v72
	v_add_f32_e32 v57, v57, v73
	v_add_f32_e32 v58, v58, v74
	v_add_f32_e32 v59, v59, v75
	v_add_f32_e32 v60, v60, v76
	v_add_f32_e32 v61, v61, v77
	v_add_f32_e32 v62, v62, v78
	v_add_f32_e32 v63, v63, v79
	v_add_f32_e32 v64, v64, v80
	v_add_f32_e32 v65, v65, v81
	v_add_f32_e32 v66, v66, v82
	v_add_f32_e32 v67, v67, v83
	v_add_f32_e32 v68, v68, v84
	v_add_f32_e32 v69, v69, v85
	v_add_f32_e32 v70, v70, v86
	v_add_f32_e32 v87, v87, v101
	v_add_f32_e32 v100, v100, v102
	s_nop 1
	v_permlane16_swap_b32_e32 v55, v63
	v_permlane16_swap_b32_e32 v56, v64
	v_permlane16_swap_b32_e32 v57, v65
	v_permlane16_swap_b32_e32 v58, v66
	v_permlane16_swap_b32_e32 v59, v67
	v_permlane16_swap_b32_e32 v60, v68
	v_permlane16_swap_b32_e32 v61, v69
	v_permlane16_swap_b32_e32 v62, v70
	v_permlane16_swap_b32_e32 v87, v100
	s_nop 1
	v_add_f32_e32 v55, v55, v63
	v_add_f32_e32 v56, v56, v64
	v_add_f32_e32 v57, v57, v65
	v_add_f32_e32 v58, v58, v66
	v_add_f32_e32 v59, v59, v67
	v_add_f32_e32 v60, v60, v68
	v_add_f32_e32 v61, v61, v69
	v_add_f32_e32 v62, v62, v70
	v_add_f32_e32 v87, v87, v100
	s_nop 1
	v_add_f32_dpp v55, v55, v55 quad_perm:[1,0,3,2] row_mask:0xf bank_mask:0xf
	v_add_f32_dpp v56, v56, v56 quad_perm:[1,0,3,2] row_mask:0xf bank_mask:0xf
	v_add_f32_dpp v57, v57, v57 quad_perm:[1,0,3,2] row_mask:0xf bank_mask:0xf
	v_add_f32_dpp v58, v58, v58 quad_perm:[1,0,3,2] row_mask:0xf bank_mask:0xf
	v_add_f32_dpp v59, v59, v59 quad_perm:[1,0,3,2] row_mask:0xf bank_mask:0xf
	v_add_f32_dpp v60, v60, v60 quad_perm:[1,0,3,2] row_mask:0xf bank_mask:0xf
	v_add_f32_dpp v61, v61, v61 quad_perm:[1,0,3,2] row_mask:0xf bank_mask:0xf
	v_add_f32_dpp v62, v62, v62 quad_perm:[1,0,3,2] row_mask:0xf bank_mask:0xf
	v_add_f32_dpp v87, v87, v87 quad_perm:[1,0,3,2] row_mask:0xf bank_mask:0xf
	s_nop 1
	v_add_f32_dpp v55, v55, v55 quad_perm:[2,3,0,1] row_mask:0xf bank_mask:0xf
	v_add_f32_dpp v56, v56, v56 quad_perm:[2,3,0,1] row_mask:0xf bank_mask:0xf
	v_add_f32_dpp v57, v57, v57 quad_perm:[2,3,0,1] row_mask:0xf bank_mask:0xf
	v_add_f32_dpp v58, v58, v58 quad_perm:[2,3,0,1] row_mask:0xf bank_mask:0xf
	v_add_f32_dpp v59, v59, v59 quad_perm:[2,3,0,1] row_mask:0xf bank_mask:0xf
	v_add_f32_dpp v60, v60, v60 quad_perm:[2,3,0,1] row_mask:0xf bank_mask:0xf
	v_add_f32_dpp v61, v61, v61 quad_perm:[2,3,0,1] row_mask:0xf bank_mask:0xf
	v_add_f32_dpp v62, v62, v62 quad_perm:[2,3,0,1] row_mask:0xf bank_mask:0xf
	v_add_f32_dpp v87, v87, v87 quad_perm:[2,3,0,1] row_mask:0xf bank_mask:0xf
	s_nop 1
	v_add_f32_dpp v55, v55, v55 row_half_mirror row_mask:0xf bank_mask:0xf
	v_add_f32_dpp v56, v56, v56 row_half_mirror row_mask:0xf bank_mask:0xf
	v_add_f32_dpp v57, v57, v57 row_half_mirror row_mask:0xf bank_mask:0xf
	v_add_f32_dpp v58, v58, v58 row_half_mirror row_mask:0xf bank_mask:0xf
	v_add_f32_dpp v59, v59, v59 row_half_mirror row_mask:0xf bank_mask:0xf
	v_add_f32_dpp v60, v60, v60 row_half_mirror row_mask:0xf bank_mask:0xf
	v_add_f32_dpp v61, v61, v61 row_half_mirror row_mask:0xf bank_mask:0xf
	v_add_f32_dpp v62, v62, v62 row_half_mirror row_mask:0xf bank_mask:0xf
	v_add_f32_dpp v87, v87, v87 row_half_mirror row_mask:0xf bank_mask:0xf
	s_nop 1
	v_add_f32_dpp v55, v55, v55 row_mirror row_mask:0xf bank_mask:0xf
	v_add_f32_dpp v56, v56, v56 row_mirror row_mask:0xf bank_mask:0xf
	v_add_f32_dpp v57, v57, v57 row_mirror row_mask:0xf bank_mask:0xf
	v_add_f32_dpp v58, v58, v58 row_mirror row_mask:0xf bank_mask:0xf
	v_add_f32_dpp v59, v59, v59 row_mirror row_mask:0xf bank_mask:0xf
	v_add_f32_dpp v60, v60, v60 row_mirror row_mask:0xf bank_mask:0xf
	v_add_f32_dpp v61, v61, v61 row_mirror row_mask:0xf bank_mask:0xf
	v_add_f32_dpp v62, v62, v62 row_mirror row_mask:0xf bank_mask:0xf
	v_add_f32_dpp v87, v87, v87 row_mirror row_mask:0xf bank_mask:0xf
	s_nop 1
	v_mov_b32_e32 v104, v55
	v_cndmask_b32_e64 v104, v104, v56, s[6:7]
	v_cndmask_b32_e64 v104, v104, v57, s[8:9]
	v_cndmask_b32_e64 v104, v104, v58, s[10:11]
	v_cndmask_b32_e64 v104, v104, v59, s[12:13]
	v_cndmask_b32_e64 v104, v104, v60, s[14:15]
	v_cndmask_b32_e64 v104, v104, v61, s[16:17]
	v_cndmask_b32_e64 v104, v104, v62, s[18:19]
	v_mul_f32_e32 v105, 0x3a800000, v87
	v_add_f32_e32 v105, 0x358637bd, v105
	v_rsq_f32_e32 v105, v105
	s_nop 0
	v_fma_f32 v104, v104, v105, v103
	v_mul_f32_e64 v105, |v104|, s65
	v_exp_f32_e32 v105, v105
	v_min_f32_e32 v104, 0, v104
	v_add_f32_e32 v105, 1.0, v105
	v_log_f32_e32 v105, v105
	s_nop 0
	v_fmac_f32_e32 v104, 0xbf317218, v105
	s_mov_b64 s[54:55], exec
	s_mov_b32 exec_lo, 0xff00ff
	s_mov_b32 exec_hi, 0xff00ff
	ds_write_b32 v107, v104 offset:128
	s_mov_b64 exec, s[54:55]

; __device__ __forceinline__ void fgate_phase(const bfr* x, const float* wf, const float* bfg, float* cl, float* ctot, LAS float* scr, int bx, int G, int tid, int lane, int wave) {
;     ...
;         for (int j = 0; j < 8; j += 2) { const int row = chunk * 64 + wave * 8 + j; typedef unsigned u32x2 __attribute__((ext_vector_type(2))); const u32x2* xa = (const u32x2*)(x + (size_t)row * D) + lane; const u32x2* xb2 = xa + D / 4; f32x4 va[4], vb[4]; float r[18]; int zo = 0; asm volatile("" : "+v"(zo));
; #pragma unroll
;             for (int jj = 0; jj < 4; ++jj) { const u32x2 wa = xa[64 * jj], wb = xb2[64 * jj]; va[jj] = (f32x4){bf_lo(wa.x), bf_hi(wa.x), bf_lo(wa.y), bf_hi(wa.y)}; vb[jj] = (f32x4){bf_lo(wb.x), bf_hi(wb.x), bf_lo(wb.y), bf_hi(wb.y)}; }
;             r[16] = 0.f; r[17] = 0.f;
; #pragma unroll
;             for (int jj = 0; jj < 4; ++jj) { r[16] += (va[jj].x * va[jj].x + va[jj].y * va[jj].y) + (va[jj].z * va[jj].z + va[jj].w * va[jj].w); r[17] += (vb[jj].x * vb[jj].x + vb[jj].y * vb[jj].y) + (vb[jj].z * vb[jj].z + vb[jj].w * vb[jj].w); }
; #pragma unroll
;             for (int h = 0; h < NH; ++h) { const f32x4* wr = (const f32x4*)(wf + h * D) + lane + zo; float da = 0.f, db = 0.f;
; #pragma unroll
;                 for (int jj = 0; jj < 4; ++jj) { const f32x4 w = wr[64 * jj]; da += (va[jj].x * w.x + va[jj].y * w.y) + (va[jj].z * w.z + va[jj].w * w.w); db += (vb[jj].x * w.x + vb[jj].y * w.y) + (vb[jj].z * w.z + vb[jj].w * w.w); }
;                 r[h] = da; r[8 + h] = db; }
.LBB0_1459:
	s_mov_b32 s38, s33
	s_ashr_i32 s39, s33, 31
	s_lshl_b64 s[38:39], s[38:39], 11
	s_mov_b64 s[98:99], 0x1000
	s_mov_b64 s[100:101], 0x2000
	v_lshl_add_u64 v[26:27], v[28:29], 0, s[38:39]
	v_lshl_add_u64 v[40:41], v[26:27], 0, s[98:99]
	global_load_dwordx2 v[38:39], v[26:27], off
	global_load_dwordx2 v[98:99], v[26:27], off offset:512
	global_load_dwordx2 v[160:161], v[26:27], off offset:1024
	global_load_dwordx2 v[0:1], v[26:27], off offset:1536
	global_load_dwordx2 v[2:3], v[26:27], off offset:2048
	global_load_dwordx2 v[4:5], v[26:27], off offset:2560
	global_load_dwordx2 v[6:7], v[26:27], off offset:3072
	global_load_dwordx2 v[8:9], v[26:27], off offset:3584
	global_load_dwordx2 v[10:11], v[40:41], off
	global_load_dwordx2 v[12:13], v[40:41], off offset:512
	global_load_dwordx2 v[14:15], v[40:41], off offset:1024
	global_load_dwordx2 v[16:17], v[40:41], off offset:1536
	global_load_dwordx2 v[18:19], v[40:41], off offset:2048
	global_load_dwordx2 v[20:21], v[40:41], off offset:2560
	global_load_dwordx2 v[22:23], v[40:41], off offset:3072
	global_load_dwordx2 v[24:25], v[40:41], off offset:3584
	global_load_dword v103, v[32:33], off offset:32
	v_lshrrev_b32_e32 v104, 6, v128
	v_lshlrev_b32_e32 v105, 4, v158
	v_readfirstlane_b32 s20, v30
	v_readfirstlane_b32 s21, v31
	v_readfirstlane_b32 s66, v104
	s_lshl_b32 s66, s66, 12
	s_add_u32 s20, s20, s66
	s_addc_u32 s21, s21, 0
	s_add_i32 s66, s66, 0x1000
	s_mov_b32 m0, s66
	s_nop 0
	global_load_lds_dwordx4 v105, s[20:21]
	s_add_u32 s20, s20, 0x400
	s_addc_u32 s21, s21, 0
	s_add_i32 s66, s66, 0x400
	s_mov_b32 m0, s66
	s_nop 0
	global_load_lds_dwordx4 v105, s[20:21]
	s_add_u32 s20, s20, 0x400
	s_addc_u32 s21, s21, 0
	s_add_i32 s66, s66, 0x400
	s_mov_b32 m0, s66
	s_nop 0
	global_load_lds_dwordx4 v105, s[20:21]
	s_add_u32 s20, s20, 0x400
	s_addc_u32 s21, s21, 0
	s_add_i32 s66, s66, 0x400
	s_mov_b32 m0, s66
	s_nop 0
	global_load_lds_dwordx4 v105, s[20:21]
	s_waitcnt vmcnt(0)
	s_barrier
	ds_read_b128 v[248:251], v105 offset:4096
	ds_read_b128 v[244:247], v105 offset:5120
	ds_read_b128 v[240:243], v105 offset:6144
	ds_read_b128 v[236:239], v105 offset:7168
	ds_read_b128 v[232:235], v105 offset:8192
	ds_read_b128 v[228:231], v105 offset:9216
	ds_read_b128 v[224:227], v105 offset:10240
	ds_read_b128 v[220:223], v105 offset:11264
	ds_read_b128 v[216:219], v105 offset:12288
	ds_read_b128 v[212:215], v105 offset:13312
	ds_read_b128 v[208:211], v105 offset:14336
	ds_read_b128 v[204:207], v105 offset:15360
	ds_read_b128 v[200:203], v105 offset:16384
	ds_read_b128 v[196:199], v105 offset:17408
	ds_read_b128 v[192:195], v105 offset:18432
	ds_read_b128 v[188:191], v105 offset:19456
	ds_read_b128 v[182:185], v105 offset:20480
	ds_read_b128 v[178:181], v105 offset:21504
	ds_read_b128 v[174:177], v105 offset:22528
	ds_read_b128 v[170:173], v105 offset:23552
	ds_read_b128 v[166:169], v105 offset:24576
	ds_read_b128 v[162:165], v105 offset:25600
	ds_read_b128 v[154:157], v105 offset:26624
	ds_read_b128 v[150:153], v105 offset:27648
	ds_read_b128 v[146:149], v105 offset:28672
	ds_read_b128 v[142:145], v105 offset:29696
	ds_read_b128 v[138:141], v105 offset:30720
	ds_read_b128 v[134:137], v105 offset:31744
	ds_read_b128 v[130:133], v105 offset:32768
	ds_read_b128 v[124:127], v105 offset:33792
	ds_read_b128 v[120:123], v105 offset:34816
	ds_read_b128 v[116:119], v105 offset:35840
	v_and_b32_e32 v106, 7, v158
	v_cmp_eq_u32_e64 s[6:7], 1, v106
	v_cmp_eq_u32_e64 s[8:9], 2, v106
	v_cmp_eq_u32_e64 s[10:11], 3, v106
	v_cmp_eq_u32_e64 s[12:13], 4, v106
	v_cmp_eq_u32_e64 s[14:15], 5, v106
	v_cmp_eq_u32_e64 s[16:17], 6, v106
	v_cmp_eq_u32_e64 s[18:19], 7, v106
	v_lshrrev_b32_e32 v104, 4, v158
	v_lshlrev_b32_e32 v104, 5, v104
	v_sub_u32_e32 v107, v95, v104
	s_mov_b32 s40, 0xffff0000
	s_waitcnt vmcnt(0) lgkmcnt(0)
	v_lshlrev_b32_e32 v97, 16, v38
	v_and_b32_e32 v159, s40, v38
	v_lshlrev_b32_e32 v187, 16, v39
	v_and_b32_e32 v42, s40, v39
	v_lshlrev_b32_e32 v43, 16, v98
	v_and_b32_e32 v44, s40, v98
	v_lshlrev_b32_e32 v45, 16, v99
	v_and_b32_e32 v46, s40, v99
	v_lshlrev_b32_e32 v47, 16, v160
	v_and_b32_e32 v48, s40, v160
	v_lshlrev_b32_e32 v49, 16, v161
	v_and_b32_e32 v50, s40, v161
	v_lshlrev_b32_e32 v51, 16, v0
	v_and_b32_e32 v52, s40, v0
	v_lshlrev_b32_e32 v53, 16, v1
	v_and_b32_e32 v54, s40, v1
	v_mul_f32_e32 v87, v97, v97
	v_mul_f32_e32 v55, v97, v248
	v_mul_f32_e32 v56, v97, v232
	v_mul_f32_e32 v57, v97, v216
	v_mul_f32_e32 v58, v97, v200
	v_mul_f32_e32 v59, v97, v182
	v_mul_f32_e32 v60, v97, v166
	v_mul_f32_e32 v61, v97, v146
	v_mul_f32_e32 v62, v97, v130
	v_fmac_f32_e32 v87, v159, v159
	v_fmac_f32_e32 v55, v159, v249
	v_fmac_f32_e32 v56, v159, v233
	v_fmac_f32_e32 v57, v159, v217
	v_fmac_f32_e32 v58, v159, v201
	v_fmac_f32_e32 v59, v159, v183
	v_fmac_f32_e32 v60, v159, v167
	v_fmac_f32_e32 v61, v159, v147
	v_fmac_f32_e32 v62, v159, v131
	v_fmac_f32_e32 v87, v187, v187
	v_fmac_f32_e32 v55, v187, v250
	v_fmac_f32_e32 v56, v187, v234
	v_fmac_f32_e32 v57, v187, v218
	v_fmac_f32_e32 v58, v187, v202
	v_fmac_f32_e32 v59, v187, v184
	v_fmac_f32_e32 v60, v187, v168
	v_fmac_f32_e32 v61, v187, v148
	v_fmac_f32_e32 v62, v187, v132
	v_fmac_f32_e32 v87, v42, v42
	v_fmac_f32_e32 v55, v42, v251
	v_fmac_f32_e32 v56, v42, v235
	v_fmac_f32_e32 v57, v42, v219
	v_fmac_f32_e32 v58, v42, v203
	v_fmac_f32_e32 v59, v42, v185
	v_fmac_f32_e32 v60, v42, v169
	v_fmac_f32_e32 v61, v42, v149
	v_fmac_f32_e32 v62, v42, v133
	v_fmac_f32_e32 v87, v43, v43
	v_fmac_f32_e32 v55, v43, v244
	v_fmac_f32_e32 v56, v43, v228
	v_fmac_f32_e32 v57, v43, v212
	v_fmac_f32_e32 v58, v43, v196
	v_fmac_f32_e32 v59, v43, v178
	v_fmac_f32_e32 v60, v43, v162
; __device__ __forceinline__ void fgate_phase(const bfr* x, const float* wf, const float* bfg, float* cl, float* ctot, LAS float* scr, int bx, int G, int tid, int lane, int wave) {
;     ...
;             for (int jj = 0; jj < 4; ++jj) { const u32x2 wa = xa[64 * jj], wb = xb2[64 * jj]; va[jj] = (f32x4){bf_lo(wa.x), bf_hi(wa.x), bf_lo(wa.y), bf_hi(wa.y)}; vb[jj] = (f32x4){bf_lo(wb.x), bf_hi(wb.x), bf_lo(wb.y), bf_hi(wb.y)}; }
;             r[16] = 0.f; r[17] = 0.f;
; #pragma unroll
;             for (int jj = 0; jj < 4; ++jj) { r[16] += (va[jj].x * va[jj].x + va[jj].y * va[jj].y) + (va[jj].z * va[jj].z + va[jj].w * va[jj].w); r[17] += (vb[jj].x * vb[jj].x + vb[jj].y * vb[jj].y) + (vb[jj].z * vb[jj].z + vb[jj].w * vb[jj].w); }
; #pragma unroll
;             for (int h = 0; h < NH; ++h) { const f32x4* wr = (const f32x4*)(wf + h * D) + lane + zo; float da = 0.f, db = 0.f;
; #pragma unroll
;                 for (int jj = 0; jj < 4; ++jj) { const f32x4 w = wr[64 * jj]; da += (va[jj].x * w.x + va[jj].y * w.y) + (va[jj].z * w.z + va[jj].w * w.w); db += (vb[jj].x * w.x + vb[jj].y * w.y) + (vb[jj].z * w.z + vb[jj].w * w.w); }
;                 r[h] = da; r[8 + h] = db; }
	v_fmac_f32_e32 v61, v43, v142
	v_fmac_f32_e32 v62, v43, v124
	v_fmac_f32_e32 v87, v44, v44
	v_fmac_f32_e32 v55, v44, v245
	v_fmac_f32_e32 v56, v44, v229
	v_fmac_f32_e32 v57, v44, v213
	v_fmac_f32_e32 v58, v44, v197
	v_fmac_f32_e32 v59, v44, v179
	v_fmac_f32_e32 v60, v44, v163
	v_fmac_f32_e32 v61, v44, v143
	v_fmac_f32_e32 v62, v44, v125
	v_fmac_f32_e32 v87, v45, v45
	v_fmac_f32_e32 v55, v45, v246
	v_fmac_f32_e32 v56, v45, v230
	v_fmac_f32_e32 v57, v45, v214
	v_fmac_f32_e32 v58, v45, v198
	v_fmac_f32_e32 v59, v45, v180
	v_fmac_f32_e32 v60, v45, v164
	v_fmac_f32_e32 v61, v45, v144
	v_fmac_f32_e32 v62, v45, v126
	v_fmac_f32_e32 v87, v46, v46
	v_fmac_f32_e32 v55, v46, v247
	v_fmac_f32_e32 v56, v46, v231
	v_fmac_f32_e32 v57, v46, v215
	v_fmac_f32_e32 v58, v46, v199
	v_fmac_f32_e32 v59, v46, v181
	v_fmac_f32_e32 v60, v46, v165
	v_fmac_f32_e32 v61, v46, v145
	v_fmac_f32_e32 v62, v46, v127
	v_fmac_f32_e32 v87, v47, v47
	v_fmac_f32_e32 v55, v47, v240
	v_fmac_f32_e32 v56, v47, v224
	v_fmac_f32_e32 v57, v47, v208
	v_fmac_f32_e32 v58, v47, v192
	v_fmac_f32_e32 v59, v47, v174
	v_fmac_f32_e32 v60, v47, v154
	v_fmac_f32_e32 v61, v47, v138
	v_fmac_f32_e32 v62, v47, v120
	v_fmac_f32_e32 v87, v48, v48
	v_fmac_f32_e32 v55, v48, v241
	v_fmac_f32_e32 v56, v48, v225
	v_fmac_f32_e32 v57, v48, v209
	v_fmac_f32_e32 v58, v48, v193
	v_fmac_f32_e32 v59, v48, v175
	v_fmac_f32_e32 v60, v48, v155
	v_fmac_f32_e32 v61, v48, v139
	v_fmac_f32_e32 v62, v48, v121
	v_fmac_f32_e32 v87, v49, v49
	v_fmac_f32_e32 v55, v49, v242
	v_fmac_f32_e32 v56, v49, v226
	v_fmac_f32_e32 v57, v49, v210
	v_fmac_f32_e32 v58, v49, v194
	v_fmac_f32_e32 v59, v49, v176
	v_fmac_f32_e32 v60, v49, v156
	v_fmac_f32_e32 v61, v49, v140
	v_fmac_f32_e32 v62, v49, v122
	v_fmac_f32_e32 v87, v50, v50
	v_fmac_f32_e32 v55, v50, v243
	v_fmac_f32_e32 v56, v50, v227
	v_fmac_f32_e32 v57, v50, v211
	v_fmac_f32_e32 v58, v50, v195
	v_fmac_f32_e32 v59, v50, v177
	v_fmac_f32_e32 v60, v50, v157
	v_fmac_f32_e32 v61, v50, v141
	v_fmac_f32_e32 v62, v50, v123
	v_fmac_f32_e32 v87, v51, v51
	v_fmac_f32_e32 v55, v51, v236
	v_fmac_f32_e32 v56, v51, v220
	v_fmac_f32_e32 v57, v51, v204
	v_fmac_f32_e32 v58, v51, v188
	v_fmac_f32_e32 v59, v51, v170
	v_fmac_f32_e32 v60, v51, v150
	v_fmac_f32_e32 v61, v51, v134
	v_fmac_f32_e32 v62, v51, v116
	v_fmac_f32_e32 v87, v52, v52
	v_fmac_f32_e32 v55, v52, v237
	v_fmac_f32_e32 v56, v52, v221
	v_fmac_f32_e32 v57, v52, v205
	v_fmac_f32_e32 v58, v52, v189
	v_fmac_f32_e32 v59, v52, v171
	v_fmac_f32_e32 v60, v52, v151
	v_fmac_f32_e32 v61, v52, v135
	v_fmac_f32_e32 v62, v52, v117
	v_fmac_f32_e32 v87, v53, v53
	v_fmac_f32_e32 v55, v53, v238
	v_fmac_f32_e32 v56, v53, v222
	v_fmac_f32_e32 v57, v53, v206
	v_fmac_f32_e32 v58, v53, v190
	v_fmac_f32_e32 v59, v53, v172
	v_fmac_f32_e32 v60, v53, v152
	v_fmac_f32_e32 v61, v53, v136
	v_fmac_f32_e32 v62, v53, v118
	v_fmac_f32_e32 v87, v54, v54
	v_fmac_f32_e32 v55, v54, v239
	v_fmac_f32_e32 v56, v54, v223
	v_fmac_f32_e32 v57, v54, v207
	v_fmac_f32_e32 v58, v54, v191
	v_fmac_f32_e32 v59, v54, v173
	v_fmac_f32_e32 v60, v54, v153
	v_fmac_f32_e32 v61, v54, v137
	v_fmac_f32_e32 v62, v54, v119
	v_lshlrev_b32_e32 v97, 16, v2
	v_and_b32_e32 v159, s40, v2
	v_lshlrev_b32_e32 v187, 16, v3
	v_and_b32_e32 v42, s40, v3
	v_lshlrev_b32_e32 v43, 16, v4
	v_and_b32_e32 v44, s40, v4
	v_lshlrev_b32_e32 v45, 16, v5
	v_and_b32_e32 v46, s40, v5
	v_lshlrev_b32_e32 v47, 16, v6
	v_and_b32_e32 v48, s40, v6
	v_lshlrev_b32_e32 v49, 16, v7
	v_and_b32_e32 v50, s40, v7
	v_lshlrev_b32_e32 v51, 16, v8
	v_and_b32_e32 v52, s40, v8
	v_lshlrev_b32_e32 v53, 16, v9
	v_and_b32_e32 v54, s40, v9
	v_mul_f32_e32 v100, v97, v97
	v_mul_f32_e32 v63, v97, v248
	v_mul_f32_e32 v64, v97, v232
	v_mul_f32_e32 v65, v97, v216
	v_mul_f32_e32 v66, v97, v200
	v_mul_f32_e32 v67, v97, v182
	v_mul_f32_e32 v68, v97, v166
	v_mul_f32_e32 v69, v97, v146
	v_mul_f32_e32 v70, v97, v130
	v_fmac_f32_e32 v100, v159, v159
	v_fmac_f32_e32 v63, v159, v249
	v_fmac_f32_e32 v64, v159, v233
	v_fmac_f32_e32 v65, v159, v217
	v_fmac_f32_e32 v66, v159, v201
	v_fmac_f32_e32 v67, v159, v183
	v_fmac_f32_e32 v68, v159, v167
	v_fmac_f32_e32 v69, v159, v147
	v_fmac_f32_e32 v70, v159, v131
	v_fmac_f32_e32 v100, v187, v187
	v_fmac_f32_e32 v63, v187, v250
	v_fmac_f32_e32 v64, v187, v234
	v_fmac_f32_e32 v65, v187, v218
	v_fmac_f32_e32 v66, v187, v202
	v_fmac_f32_e32 v67, v187, v184
	v_fmac_f32_e32 v68, v187, v168
	v_fmac_f32_e32 v69, v187, v148
	v_fmac_f32_e32 v70, v187, v132
	v_fmac_f32_e32 v100, v42, v42
	v_fmac_f32_e32 v63, v42, v251
	v_fmac_f32_e32 v64, v42, v235
	v_fmac_f32_e32 v65, v42, v219
	v_fmac_f32_e32 v66, v42, v203
	v_fmac_f32_e32 v67, v42, v185
	v_fmac_f32_e32 v68, v42, v169
	v_fmac_f32_e32 v69, v42, v149
	v_fmac_f32_e32 v70, v42, v133
	v_fmac_f32_e32 v100, v43, v43
	v_fmac_f32_e32 v63, v43, v244
	v_fmac_f32_e32 v64, v43, v228
	v_fmac_f32_e32 v65, v43, v212
	v_fmac_f32_e32 v66, v43, v196
	v_fmac_f32_e32 v67, v43, v178
	v_fmac_f32_e32 v68, v43, v162
	v_fmac_f32_e32 v69, v43, v142
	v_fmac_f32_e32 v70, v43, v124
	v_fmac_f32_e32 v100, v44, v44
	v_fmac_f32_e32 v63, v44, v245
	v_fmac_f32_e32 v64, v44, v229
	v_fmac_f32_e32 v65, v44, v213
	v_fmac_f32_e32 v66, v44, v197
	v_fmac_f32_e32 v67, v44, v179
	v_fmac_f32_e32 v68, v44, v163
	v_fmac_f32_e32 v69, v44, v143
	v_fmac_f32_e32 v70, v44, v125
	v_fmac_f32_e32 v100, v45, v45
	v_fmac_f32_e32 v63, v45, v246
	v_fmac_f32_e32 v64, v45, v230
	v_fmac_f32_e32 v65, v45, v214
	v_fmac_f32_e32 v66, v45, v198
	v_fmac_f32_e32 v67, v45, v180
	v_fmac_f32_e32 v68, v45, v164
	v_fmac_f32_e32 v69, v45, v144
	v_fmac_f32_e32 v70, v45, v126
	v_fmac_f32_e32 v100, v46, v46
	v_fmac_f32_e32 v63, v46, v247
	v_fmac_f32_e32 v64, v46, v231
; __device__ __forceinline__ void fgate_phase(const bfr* x, const float* wf, const float* bfg, float* cl, float* ctot, LAS float* scr, int bx, int G, int tid, int lane, int wave) {
;     ...
;             for (int jj = 0; jj < 4; ++jj) { const u32x2 wa = xa[64 * jj], wb = xb2[64 * jj]; va[jj] = (f32x4){bf_lo(wa.x), bf_hi(wa.x), bf_lo(wa.y), bf_hi(wa.y)}; vb[jj] = (f32x4){bf_lo(wb.x), bf_hi(wb.x), bf_lo(wb.y), bf_hi(wb.y)}; }
;             r[16] = 0.f; r[17] = 0.f;
; #pragma unroll
;             for (int jj = 0; jj < 4; ++jj) { r[16] += (va[jj].x * va[jj].x + va[jj].y * va[jj].y) + (va[jj].z * va[jj].z + va[jj].w * va[jj].w); r[17] += (vb[jj].x * vb[jj].x + vb[jj].y * vb[jj].y) + (vb[jj].z * vb[jj].z + vb[jj].w * vb[jj].w); }
; #pragma unroll
;             for (int h = 0; h < NH; ++h) { const f32x4* wr = (const f32x4*)(wf + h * D) + lane + zo; float da = 0.f, db = 0.f;
; #pragma unroll
;                 for (int jj = 0; jj < 4; ++jj) { const f32x4 w = wr[64 * jj]; da += (va[jj].x * w.x + va[jj].y * w.y) + (va[jj].z * w.z + va[jj].w * w.w); db += (vb[jj].x * w.x + vb[jj].y * w.y) + (vb[jj].z * w.z + vb[jj].w * w.w); }
;                 r[h] = da; r[8 + h] = db; }
	v_fmac_f32_e32 v65, v46, v215
	v_fmac_f32_e32 v66, v46, v199
	v_fmac_f32_e32 v67, v46, v181
	v_fmac_f32_e32 v68, v46, v165
	v_fmac_f32_e32 v69, v46, v145
	v_fmac_f32_e32 v70, v46, v127
	v_fmac_f32_e32 v100, v47, v47
	v_fmac_f32_e32 v63, v47, v240
	v_fmac_f32_e32 v64, v47, v224
	v_fmac_f32_e32 v65, v47, v208
	v_fmac_f32_e32 v66, v47, v192
	v_fmac_f32_e32 v67, v47, v174
	v_fmac_f32_e32 v68, v47, v154
	v_fmac_f32_e32 v69, v47, v138
	v_fmac_f32_e32 v70, v47, v120
	v_fmac_f32_e32 v100, v48, v48
	v_fmac_f32_e32 v63, v48, v241
	v_fmac_f32_e32 v64, v48, v225
	v_fmac_f32_e32 v65, v48, v209
	v_fmac_f32_e32 v66, v48, v193
	v_fmac_f32_e32 v67, v48, v175
	v_fmac_f32_e32 v68, v48, v155
	v_fmac_f32_e32 v69, v48, v139
	v_fmac_f32_e32 v70, v48, v121
	v_fmac_f32_e32 v100, v49, v49
	v_fmac_f32_e32 v63, v49, v242
	v_fmac_f32_e32 v64, v49, v226
	v_fmac_f32_e32 v65, v49, v210
	v_fmac_f32_e32 v66, v49, v194
	v_fmac_f32_e32 v67, v49, v176
	v_fmac_f32_e32 v68, v49, v156
	v_fmac_f32_e32 v69, v49, v140
	v_fmac_f32_e32 v70, v49, v122
	v_fmac_f32_e32 v100, v50, v50
	v_fmac_f32_e32 v63, v50, v243
	v_fmac_f32_e32 v64, v50, v227
	v_fmac_f32_e32 v65, v50, v211
	v_fmac_f32_e32 v66, v50, v195
	v_fmac_f32_e32 v67, v50, v177
	v_fmac_f32_e32 v68, v50, v157
	v_fmac_f32_e32 v69, v50, v141
	v_fmac_f32_e32 v70, v50, v123
	v_fmac_f32_e32 v100, v51, v51
	v_fmac_f32_e32 v63, v51, v236
	v_fmac_f32_e32 v64, v51, v220
	v_fmac_f32_e32 v65, v51, v204
	v_fmac_f32_e32 v66, v51, v188
	v_fmac_f32_e32 v67, v51, v170
	v_fmac_f32_e32 v68, v51, v150
	v_fmac_f32_e32 v69, v51, v134
	v_fmac_f32_e32 v70, v51, v116
	v_fmac_f32_e32 v100, v52, v52
	v_fmac_f32_e32 v63, v52, v237
	v_fmac_f32_e32 v64, v52, v221
	v_fmac_f32_e32 v65, v52, v205
	v_fmac_f32_e32 v66, v52, v189
	v_fmac_f32_e32 v67, v52, v171
	v_fmac_f32_e32 v68, v52, v151
	v_fmac_f32_e32 v69, v52, v135
	v_fmac_f32_e32 v70, v52, v117
	v_fmac_f32_e32 v100, v53, v53
	v_fmac_f32_e32 v63, v53, v238
	v_fmac_f32_e32 v64, v53, v222
	v_fmac_f32_e32 v65, v53, v206
	v_fmac_f32_e32 v66, v53, v190
	v_fmac_f32_e32 v67, v53, v172
	v_fmac_f32_e32 v68, v53, v152
	v_fmac_f32_e32 v69, v53, v136
	v_fmac_f32_e32 v70, v53, v118
	v_fmac_f32_e32 v100, v54, v54
	v_fmac_f32_e32 v63, v54, v239
	v_fmac_f32_e32 v64, v54, v223
	v_fmac_f32_e32 v65, v54, v207
	v_fmac_f32_e32 v66, v54, v191
	v_fmac_f32_e32 v67, v54, v173
	v_fmac_f32_e32 v68, v54, v153
	v_fmac_f32_e32 v69, v54, v137
	v_fmac_f32_e32 v70, v54, v119
	v_lshlrev_b32_e32 v97, 16, v10
	v_and_b32_e32 v159, s40, v10
	v_lshlrev_b32_e32 v187, 16, v11
	v_and_b32_e32 v42, s40, v11
	v_lshlrev_b32_e32 v43, 16, v12
	v_and_b32_e32 v44, s40, v12
	v_lshlrev_b32_e32 v45, 16, v13
	v_and_b32_e32 v46, s40, v13
	v_lshlrev_b32_e32 v47, 16, v14
	v_and_b32_e32 v48, s40, v14
	v_lshlrev_b32_e32 v49, 16, v15
	v_and_b32_e32 v50, s40, v15
	v_lshlrev_b32_e32 v51, 16, v16
	v_and_b32_e32 v52, s40, v16
	v_lshlrev_b32_e32 v53, 16, v17
	v_and_b32_e32 v54, s40, v17
	v_mul_f32_e32 v101, v97, v97
	v_mul_f32_e32 v71, v97, v248
	v_mul_f32_e32 v72, v97, v232
	v_mul_f32_e32 v73, v97, v216
	v_mul_f32_e32 v74, v97, v200
	v_mul_f32_e32 v75, v97, v182
	v_mul_f32_e32 v76, v97, v166
	v_mul_f32_e32 v77, v97, v146
	v_mul_f32_e32 v78, v97, v130
	v_fmac_f32_e32 v101, v159, v159
	v_fmac_f32_e32 v71, v159, v249
	v_fmac_f32_e32 v72, v159, v233
	v_fmac_f32_e32 v73, v159, v217
	v_fmac_f32_e32 v74, v159, v201
	v_fmac_f32_e32 v75, v159, v183
	v_fmac_f32_e32 v76, v159, v167
	v_fmac_f32_e32 v77, v159, v147
	v_fmac_f32_e32 v78, v159, v131
	v_fmac_f32_e32 v101, v187, v187
	v_fmac_f32_e32 v71, v187, v250
	v_fmac_f32_e32 v72, v187, v234
	v_fmac_f32_e32 v73, v187, v218
	v_fmac_f32_e32 v74, v187, v202
	v_fmac_f32_e32 v75, v187, v184
	v_fmac_f32_e32 v76, v187, v168
	v_fmac_f32_e32 v77, v187, v148
	v_fmac_f32_e32 v78, v187, v132
	v_fmac_f32_e32 v101, v42, v42
	v_fmac_f32_e32 v71, v42, v251
	v_fmac_f32_e32 v72, v42, v235
	v_fmac_f32_e32 v73, v42, v219
	v_fmac_f32_e32 v74, v42, v203
	v_fmac_f32_e32 v75, v42, v185
	v_fmac_f32_e32 v76, v42, v169
	v_fmac_f32_e32 v77, v42, v149
	v_fmac_f32_e32 v78, v42, v133
	v_fmac_f32_e32 v101, v43, v43
	v_fmac_f32_e32 v71, v43, v244
	v_fmac_f32_e32 v72, v43, v228
	v_fmac_f32_e32 v73, v43, v212
	v_fmac_f32_e32 v74, v43, v196
	v_fmac_f32_e32 v75, v43, v178
	v_fmac_f32_e32 v76, v43, v162
	v_fmac_f32_e32 v77, v43, v142
	v_fmac_f32_e32 v78, v43, v124
	v_fmac_f32_e32 v101, v44, v44
	v_fmac_f32_e32 v71, v44, v245
	v_fmac_f32_e32 v72, v44, v229
	v_fmac_f32_e32 v73, v44, v213
	v_fmac_f32_e32 v74, v44, v197
	v_fmac_f32_e32 v75, v44, v179
	v_fmac_f32_e32 v76, v44, v163
	v_fmac_f32_e32 v77, v44, v143
	v_fmac_f32_e32 v78, v44, v125
	v_fmac_f32_e32 v101, v45, v45
	v_fmac_f32_e32 v71, v45, v246
	v_fmac_f32_e32 v72, v45, v230
	v_fmac_f32_e32 v73, v45, v214
	v_fmac_f32_e32 v74, v45, v198
	v_fmac_f32_e32 v75, v45, v180
	v_fmac_f32_e32 v76, v45, v164
	v_fmac_f32_e32 v77, v45, v144
	v_fmac_f32_e32 v78, v45, v126
	v_fmac_f32_e32 v101, v46, v46
	v_fmac_f32_e32 v71, v46, v247
	v_fmac_f32_e32 v72, v46, v231
	v_fmac_f32_e32 v73, v46, v215
	v_fmac_f32_e32 v74, v46, v199
	v_fmac_f32_e32 v75, v46, v181
	v_fmac_f32_e32 v76, v46, v165
	v_fmac_f32_e32 v77, v46, v145
	v_fmac_f32_e32 v78, v46, v127
	v_fmac_f32_e32 v101, v47, v47
	v_fmac_f32_e32 v71, v47, v240
	v_fmac_f32_e32 v72, v47, v224
	v_fmac_f32_e32 v73, v47, v208
	v_fmac_f32_e32 v74, v47, v192
	v_fmac_f32_e32 v75, v47, v174
	v_fmac_f32_e32 v76, v47, v154
	v_fmac_f32_e32 v77, v47, v138
	v_fmac_f32_e32 v78, v47, v120
	v_fmac_f32_e32 v101, v48, v48
	v_fmac_f32_e32 v71, v48, v241
	v_fmac_f32_e32 v72, v48, v225
	v_fmac_f32_e32 v73, v48, v209
	v_fmac_f32_e32 v74, v48, v193
	v_fmac_f32_e32 v75, v48, v175
	v_fmac_f32_e32 v76, v48, v155
; __device__ __forceinline__ void fgate_phase(const bfr* x, const float* wf, const float* bfg, float* cl, float* ctot, LAS float* scr, int bx, int G, int tid, int lane, int wave) {
;     ...
;             for (int jj = 0; jj < 4; ++jj) { const u32x2 wa = xa[64 * jj], wb = xb2[64 * jj]; va[jj] = (f32x4){bf_lo(wa.x), bf_hi(wa.x), bf_lo(wa.y), bf_hi(wa.y)}; vb[jj] = (f32x4){bf_lo(wb.x), bf_hi(wb.x), bf_lo(wb.y), bf_hi(wb.y)}; }
;             r[16] = 0.f; r[17] = 0.f;
; #pragma unroll
;             for (int jj = 0; jj < 4; ++jj) { r[16] += (va[jj].x * va[jj].x + va[jj].y * va[jj].y) + (va[jj].z * va[jj].z + va[jj].w * va[jj].w); r[17] += (vb[jj].x * vb[jj].x + vb[jj].y * vb[jj].y) + (vb[jj].z * vb[jj].z + vb[jj].w * vb[jj].w); }
; #pragma unroll
;             for (int h = 0; h < NH; ++h) { const f32x4* wr = (const f32x4*)(wf + h * D) + lane + zo; float da = 0.f, db = 0.f;
; #pragma unroll
;                 for (int jj = 0; jj < 4; ++jj) { const f32x4 w = wr[64 * jj]; da += (va[jj].x * w.x + va[jj].y * w.y) + (va[jj].z * w.z + va[jj].w * w.w); db += (vb[jj].x * w.x + vb[jj].y * w.y) + (vb[jj].z * w.z + vb[jj].w * w.w); }
;                 r[h] = da; r[8 + h] = db; }
	v_fmac_f32_e32 v77, v48, v139
	v_fmac_f32_e32 v78, v48, v121
	v_fmac_f32_e32 v101, v49, v49
	v_fmac_f32_e32 v71, v49, v242
	v_fmac_f32_e32 v72, v49, v226
	v_fmac_f32_e32 v73, v49, v210
	v_fmac_f32_e32 v74, v49, v194
	v_fmac_f32_e32 v75, v49, v176
	v_fmac_f32_e32 v76, v49, v156
	v_fmac_f32_e32 v77, v49, v140
	v_fmac_f32_e32 v78, v49, v122
	v_fmac_f32_e32 v101, v50, v50
	v_fmac_f32_e32 v71, v50, v243
	v_fmac_f32_e32 v72, v50, v227
	v_fmac_f32_e32 v73, v50, v211
	v_fmac_f32_e32 v74, v50, v195
	v_fmac_f32_e32 v75, v50, v177
	v_fmac_f32_e32 v76, v50, v157
	v_fmac_f32_e32 v77, v50, v141
	v_fmac_f32_e32 v78, v50, v123
	v_fmac_f32_e32 v101, v51, v51
	v_fmac_f32_e32 v71, v51, v236
	v_fmac_f32_e32 v72, v51, v220
	v_fmac_f32_e32 v73, v51, v204
	v_fmac_f32_e32 v74, v51, v188
	v_fmac_f32_e32 v75, v51, v170
	v_fmac_f32_e32 v76, v51, v150
	v_fmac_f32_e32 v77, v51, v134
	v_fmac_f32_e32 v78, v51, v116
	v_fmac_f32_e32 v101, v52, v52
	v_fmac_f32_e32 v71, v52, v237
	v_fmac_f32_e32 v72, v52, v221
	v_fmac_f32_e32 v73, v52, v205
	v_fmac_f32_e32 v74, v52, v189
	v_fmac_f32_e32 v75, v52, v171
	v_fmac_f32_e32 v76, v52, v151
	v_fmac_f32_e32 v77, v52, v135
	v_fmac_f32_e32 v78, v52, v117
	v_fmac_f32_e32 v101, v53, v53
	v_fmac_f32_e32 v71, v53, v238
	v_fmac_f32_e32 v72, v53, v222
	v_fmac_f32_e32 v73, v53, v206
	v_fmac_f32_e32 v74, v53, v190
	v_fmac_f32_e32 v75, v53, v172
	v_fmac_f32_e32 v76, v53, v152
	v_fmac_f32_e32 v77, v53, v136
	v_fmac_f32_e32 v78, v53, v118
	v_fmac_f32_e32 v101, v54, v54
	v_fmac_f32_e32 v71, v54, v239
	v_fmac_f32_e32 v72, v54, v223
	v_fmac_f32_e32 v73, v54, v207
	v_fmac_f32_e32 v74, v54, v191
	v_fmac_f32_e32 v75, v54, v173
	v_fmac_f32_e32 v76, v54, v153
	v_fmac_f32_e32 v77, v54, v137
	v_fmac_f32_e32 v78, v54, v119
	v_lshlrev_b32_e32 v97, 16, v18
	v_and_b32_e32 v159, s40, v18
	v_lshlrev_b32_e32 v187, 16, v19
	v_and_b32_e32 v42, s40, v19
	v_lshlrev_b32_e32 v43, 16, v20
	v_and_b32_e32 v44, s40, v20
	v_lshlrev_b32_e32 v45, 16, v21
	v_and_b32_e32 v46, s40, v21
	v_lshlrev_b32_e32 v47, 16, v22
	v_and_b32_e32 v48, s40, v22
	v_lshlrev_b32_e32 v49, 16, v23
	v_and_b32_e32 v50, s40, v23
	v_lshlrev_b32_e32 v51, 16, v24
	v_and_b32_e32 v52, s40, v24
	v_lshlrev_b32_e32 v53, 16, v25
	v_and_b32_e32 v54, s40, v25
	v_mul_f32_e32 v102, v97, v97
	v_mul_f32_e32 v79, v97, v248
	v_mul_f32_e32 v80, v97, v232
	v_mul_f32_e32 v81, v97, v216
	v_mul_f32_e32 v82, v97, v200
	v_mul_f32_e32 v83, v97, v182
	v_mul_f32_e32 v84, v97, v166
	v_mul_f32_e32 v85, v97, v146
	v_mul_f32_e32 v86, v97, v130
	v_fmac_f32_e32 v102, v159, v159
	v_fmac_f32_e32 v79, v159, v249
	v_fmac_f32_e32 v80, v159, v233
	v_fmac_f32_e32 v81, v159, v217
	v_fmac_f32_e32 v82, v159, v201
	v_fmac_f32_e32 v83, v159, v183
	v_fmac_f32_e32 v84, v159, v167
	v_fmac_f32_e32 v85, v159, v147
	v_fmac_f32_e32 v86, v159, v131
	v_fmac_f32_e32 v102, v187, v187
	v_fmac_f32_e32 v79, v187, v250
	v_fmac_f32_e32 v80, v187, v234
	v_fmac_f32_e32 v81, v187, v218
	v_fmac_f32_e32 v82, v187, v202
	v_fmac_f32_e32 v83, v187, v184
	v_fmac_f32_e32 v84, v187, v168
	v_fmac_f32_e32 v85, v187, v148
	v_fmac_f32_e32 v86, v187, v132
	v_fmac_f32_e32 v102, v42, v42
	v_fmac_f32_e32 v79, v42, v251
	v_fmac_f32_e32 v80, v42, v235
	v_fmac_f32_e32 v81, v42, v219
	v_fmac_f32_e32 v82, v42, v203
	v_fmac_f32_e32 v83, v42, v185
	v_fmac_f32_e32 v84, v42, v169
	v_fmac_f32_e32 v85, v42, v149
	v_fmac_f32_e32 v86, v42, v133
	v_fmac_f32_e32 v102, v43, v43
	v_fmac_f32_e32 v79, v43, v244
	v_fmac_f32_e32 v80, v43, v228
	v_fmac_f32_e32 v81, v43, v212
	v_fmac_f32_e32 v82, v43, v196
	v_fmac_f32_e32 v83, v43, v178
	v_fmac_f32_e32 v84, v43, v162
	v_fmac_f32_e32 v85, v43, v142
	v_fmac_f32_e32 v86, v43, v124
	v_fmac_f32_e32 v102, v44, v44
	v_fmac_f32_e32 v79, v44, v245
	v_fmac_f32_e32 v80, v44, v229
	v_fmac_f32_e32 v81, v44, v213
	v_fmac_f32_e32 v82, v44, v197
	v_fmac_f32_e32 v83, v44, v179
	v_fmac_f32_e32 v84, v44, v163
	v_fmac_f32_e32 v85, v44, v143
	v_fmac_f32_e32 v86, v44, v125
	v_fmac_f32_e32 v102, v45, v45
	v_fmac_f32_e32 v79, v45, v246
	v_fmac_f32_e32 v80, v45, v230
	v_fmac_f32_e32 v81, v45, v214
	v_fmac_f32_e32 v82, v45, v198
	v_fmac_f32_e32 v83, v45, v180
	v_fmac_f32_e32 v84, v45, v164
	v_fmac_f32_e32 v85, v45, v144
	v_fmac_f32_e32 v86, v45, v126
	v_fmac_f32_e32 v102, v46, v46
	v_fmac_f32_e32 v79, v46, v247
	v_fmac_f32_e32 v80, v46, v231
	v_fmac_f32_e32 v81, v46, v215
	v_fmac_f32_e32 v82, v46, v199
	v_fmac_f32_e32 v83, v46, v181
	v_fmac_f32_e32 v84, v46, v165
	v_fmac_f32_e32 v85, v46, v145
	v_fmac_f32_e32 v86, v46, v127
	v_fmac_f32_e32 v102, v47, v47
	v_fmac_f32_e32 v79, v47, v240
	v_fmac_f32_e32 v80, v47, v224
	v_fmac_f32_e32 v81, v47, v208
	v_fmac_f32_e32 v82, v47, v192
	v_fmac_f32_e32 v83, v47, v174
	v_fmac_f32_e32 v84, v47, v154
	v_fmac_f32_e32 v85, v47, v138
	v_fmac_f32_e32 v86, v47, v120
	v_fmac_f32_e32 v102, v48, v48
	v_fmac_f32_e32 v79, v48, v241
	v_fmac_f32_e32 v80, v48, v225
	v_fmac_f32_e32 v81, v48, v209
	v_fmac_f32_e32 v82, v48, v193
	v_fmac_f32_e32 v83, v48, v175
	v_fmac_f32_e32 v84, v48, v155
	v_fmac_f32_e32 v85, v48, v139
	v_fmac_f32_e32 v86, v48, v121
	v_fmac_f32_e32 v102, v49, v49
	v_fmac_f32_e32 v79, v49, v242
	v_fmac_f32_e32 v80, v49, v226
	v_fmac_f32_e32 v81, v49, v210
	v_fmac_f32_e32 v82, v49, v194
	v_fmac_f32_e32 v83, v49, v176
	v_fmac_f32_e32 v84, v49, v156
	v_fmac_f32_e32 v85, v49, v140
	v_fmac_f32_e32 v86, v49, v122
	v_fmac_f32_e32 v102, v50, v50
	v_fmac_f32_e32 v79, v50, v243
	v_fmac_f32_e32 v80, v50, v227
	v_fmac_f32_e32 v81, v50, v211
	v_fmac_f32_e32 v82, v50, v195
	v_fmac_f32_e32 v83, v50, v177
	v_fmac_f32_e32 v84, v50, v157
	v_fmac_f32_e32 v85, v50, v141
	v_fmac_f32_e32 v86, v50, v123
	v_fmac_f32_e32 v102, v51, v51
	v_fmac_f32_e32 v79, v51, v236
; __device__ __forceinline__ float lane_get(float v, int src_lane) { return __builtin_bit_cast(float, __builtin_amdgcn_ds_bpermute(src_lane << 2, __builtin_bit_cast(int, v))); }
; __device__ __forceinline__ void fgate_phase(const bfr* x, const float* wf, const float* bfg, float* cl, float* ctot, LAS float* scr, int bx, int G, int tid, int lane, int wave) {
;     ...
;         for (int j = 0; j < 8; j += 2) { const int row = chunk * 64 + wave * 8 + j; typedef unsigned u32x2 __attribute__((ext_vector_type(2))); const u32x2* xa = (const u32x2*)(x + (size_t)row * D) + lane; const u32x2* xb2 = xa + D / 4; f32x4 va[4], vb[4]; float r[18]; int zo = 0; asm volatile("" : "+v"(zo));
; #pragma unroll
;             for (int jj = 0; jj < 4; ++jj) { const u32x2 wa = xa[64 * jj], wb = xb2[64 * jj]; va[jj] = (f32x4){bf_lo(wa.x), bf_hi(wa.x), bf_lo(wa.y), bf_hi(wa.y)}; vb[jj] = (f32x4){bf_lo(wb.x), bf_hi(wb.x), bf_lo(wb.y), bf_hi(wb.y)}; }
;             r[16] = 0.f; r[17] = 0.f;
; #pragma unroll
;             for (int jj = 0; jj < 4; ++jj) { r[16] += (va[jj].x * va[jj].x + va[jj].y * va[jj].y) + (va[jj].z * va[jj].z + va[jj].w * va[jj].w); r[17] += (vb[jj].x * vb[jj].x + vb[jj].y * vb[jj].y) + (vb[jj].z * vb[jj].z + vb[jj].w * vb[jj].w); }
; #pragma unroll
;             for (int h = 0; h < NH; ++h) { const f32x4* wr = (const f32x4*)(wf + h * D) + lane + zo; float da = 0.f, db = 0.f;
; #pragma unroll
;                 for (int jj = 0; jj < 4; ++jj) { const f32x4 w = wr[64 * jj]; da += (va[jj].x * w.x + va[jj].y * w.y) + (va[jj].z * w.z + va[jj].w * w.w); db += (vb[jj].x * w.x + vb[jj].y * w.y) + (vb[jj].z * w.z + vb[jj].w * w.w); }
;                 r[h] = da; r[8 + h] = db; }
; #pragma unroll
;             for (int o = 1; o < 64; o <<= 1) {
; #pragma unroll
;                 for (int q = 0; q < 18; ++q) r[q] += lane_get(r[q], lane ^ o); }
	v_fmac_f32_e32 v80, v51, v220
	v_fmac_f32_e32 v81, v51, v204
	v_fmac_f32_e32 v82, v51, v188
	v_fmac_f32_e32 v83, v51, v170
	v_fmac_f32_e32 v84, v51, v150
	v_fmac_f32_e32 v85, v51, v134
	v_fmac_f32_e32 v86, v51, v116
	v_fmac_f32_e32 v102, v52, v52
	v_fmac_f32_e32 v79, v52, v237
	v_fmac_f32_e32 v80, v52, v221
	v_fmac_f32_e32 v81, v52, v205
	v_fmac_f32_e32 v82, v52, v189
	v_fmac_f32_e32 v83, v52, v171
	v_fmac_f32_e32 v84, v52, v151
	v_fmac_f32_e32 v85, v52, v135
	v_fmac_f32_e32 v86, v52, v117
	v_fmac_f32_e32 v102, v53, v53
	v_fmac_f32_e32 v79, v53, v238
	v_fmac_f32_e32 v80, v53, v222
	v_fmac_f32_e32 v81, v53, v206
	v_fmac_f32_e32 v82, v53, v190
	v_fmac_f32_e32 v83, v53, v172
	v_fmac_f32_e32 v84, v53, v152
	v_fmac_f32_e32 v85, v53, v136
	v_fmac_f32_e32 v86, v53, v118
	v_fmac_f32_e32 v102, v54, v54
	v_fmac_f32_e32 v79, v54, v239
	v_fmac_f32_e32 v80, v54, v223
	v_fmac_f32_e32 v81, v54, v207
	v_fmac_f32_e32 v82, v54, v191
	v_fmac_f32_e32 v83, v54, v173
	v_fmac_f32_e32 v84, v54, v153
	v_fmac_f32_e32 v85, v54, v137
	v_fmac_f32_e32 v86, v54, v119
	v_lshl_add_u64 v[26:27], v[26:27], 0, s[100:101]
	v_lshl_add_u64 v[40:41], v[40:41], 0, s[100:101]
	global_load_dwordx2 v[38:39], v[26:27], off
	global_load_dwordx2 v[98:99], v[26:27], off offset:512
	global_load_dwordx2 v[160:161], v[26:27], off offset:1024
	global_load_dwordx2 v[0:1], v[26:27], off offset:1536
	global_load_dwordx2 v[2:3], v[26:27], off offset:2048
	global_load_dwordx2 v[4:5], v[26:27], off offset:2560
	global_load_dwordx2 v[6:7], v[26:27], off offset:3072
	global_load_dwordx2 v[8:9], v[26:27], off offset:3584
	global_load_dwordx2 v[10:11], v[40:41], off
	global_load_dwordx2 v[12:13], v[40:41], off offset:512
	global_load_dwordx2 v[14:15], v[40:41], off offset:1024
	global_load_dwordx2 v[16:17], v[40:41], off offset:1536
	global_load_dwordx2 v[18:19], v[40:41], off offset:2048
	global_load_dwordx2 v[20:21], v[40:41], off offset:2560
	global_load_dwordx2 v[22:23], v[40:41], off offset:3072
	global_load_dwordx2 v[24:25], v[40:41], off offset:3584
	s_nop 1
	v_permlane32_swap_b32_e32 v55, v71
	v_permlane32_swap_b32_e32 v56, v72
	v_permlane32_swap_b32_e32 v57, v73
	v_permlane32_swap_b32_e32 v58, v74
	v_permlane32_swap_b32_e32 v59, v75
	v_permlane32_swap_b32_e32 v60, v76
	v_permlane32_swap_b32_e32 v61, v77
	v_permlane32_swap_b32_e32 v62, v78
	v_permlane32_swap_b32_e32 v63, v79
	v_permlane32_swap_b32_e32 v64, v80
	v_permlane32_swap_b32_e32 v65, v81
	v_permlane32_swap_b32_e32 v66, v82
	v_permlane32_swap_b32_e32 v67, v83
	v_permlane32_swap_b32_e32 v68, v84
	v_permlane32_swap_b32_e32 v69, v85
	v_permlane32_swap_b32_e32 v70, v86
	v_permlane32_swap_b32_e32 v87, v101
	v_permlane32_swap_b32_e32 v100, v102
	s_nop 1
	v_add_f32_e32 v55, v55, v71
	v_add_f32_e32 v56, v56, v72
	v_add_f32_e32 v57, v57, v73
	v_add_f32_e32 v58, v58, v74
	v_add_f32_e32 v59, v59, v75
	v_add_f32_e32 v60, v60, v76
	v_add_f32_e32 v61, v61, v77
	v_add_f32_e32 v62, v62, v78
	v_add_f32_e32 v63, v63, v79
	v_add_f32_e32 v64, v64, v80
	v_add_f32_e32 v65, v65, v81
	v_add_f32_e32 v66, v66, v82
	v_add_f32_e32 v67, v67, v83
	v_add_f32_e32 v68, v68, v84
	v_add_f32_e32 v69, v69, v85
	v_add_f32_e32 v70, v70, v86
	v_add_f32_e32 v87, v87, v101
	v_add_f32_e32 v100, v100, v102
	s_nop 1
	v_permlane16_swap_b32_e32 v55, v63
	v_permlane16_swap_b32_e32 v56, v64
	v_permlane16_swap_b32_e32 v57, v65
	v_permlane16_swap_b32_e32 v58, v66
	v_permlane16_swap_b32_e32 v59, v67
	v_permlane16_swap_b32_e32 v60, v68
	v_permlane16_swap_b32_e32 v61, v69
	v_permlane16_swap_b32_e32 v62, v70
	v_permlane16_swap_b32_e32 v87, v100
	s_nop 1
	v_add_f32_e32 v55, v55, v63
	v_add_f32_e32 v56, v56, v64
	v_add_f32_e32 v57, v57, v65
	v_add_f32_e32 v58, v58, v66
	v_add_f32_e32 v59, v59, v67
	v_add_f32_e32 v60, v60, v68
	v_add_f32_e32 v61, v61, v69
	v_add_f32_e32 v62, v62, v70
	v_add_f32_e32 v87, v87, v100
	s_nop 1
	v_add_f32_dpp v55, v55, v55 quad_perm:[1,0,3,2] row_mask:0xf bank_mask:0xf
	v_add_f32_dpp v56, v56, v56 quad_perm:[1,0,3,2] row_mask:0xf bank_mask:0xf
	v_add_f32_dpp v57, v57, v57 quad_perm:[1,0,3,2] row_mask:0xf bank_mask:0xf
	v_add_f32_dpp v58, v58, v58 quad_perm:[1,0,3,2] row_mask:0xf bank_mask:0xf
	v_add_f32_dpp v59, v59, v59 quad_perm:[1,0,3,2] row_mask:0xf bank_mask:0xf
	v_add_f32_dpp v60, v60, v60 quad_perm:[1,0,3,2] row_mask:0xf bank_mask:0xf
	v_add_f32_dpp v61, v61, v61 quad_perm:[1,0,3,2] row_mask:0xf bank_mask:0xf
	v_add_f32_dpp v62, v62, v62 quad_perm:[1,0,3,2] row_mask:0xf bank_mask:0xf
	v_add_f32_dpp v87, v87, v87 quad_perm:[1,0,3,2] row_mask:0xf bank_mask:0xf
	s_nop 1
	v_add_f32_dpp v55, v55, v55 quad_perm:[2,3,0,1] row_mask:0xf bank_mask:0xf
	v_add_f32_dpp v56, v56, v56 quad_perm:[2,3,0,1] row_mask:0xf bank_mask:0xf
	v_add_f32_dpp v57, v57, v57 quad_perm:[2,3,0,1] row_mask:0xf bank_mask:0xf
	v_add_f32_dpp v58, v58, v58 quad_perm:[2,3,0,1] row_mask:0xf bank_mask:0xf
	v_add_f32_dpp v59, v59, v59 quad_perm:[2,3,0,1] row_mask:0xf bank_mask:0xf
	v_add_f32_dpp v60, v60, v60 quad_perm:[2,3,0,1] row_mask:0xf bank_mask:0xf
	v_add_f32_dpp v61, v61, v61 quad_perm:[2,3,0,1] row_mask:0xf bank_mask:0xf
	v_add_f32_dpp v62, v62, v62 quad_perm:[2,3,0,1] row_mask:0xf bank_mask:0xf
	v_add_f32_dpp v87, v87, v87 quad_perm:[2,3,0,1] row_mask:0xf bank_mask:0xf
	s_nop 1
	v_add_f32_dpp v55, v55, v55 row_half_mirror row_mask:0xf bank_mask:0xf
	v_add_f32_dpp v56, v56, v56 row_half_mirror row_mask:0xf bank_mask:0xf
	v_add_f32_dpp v57, v57, v57 row_half_mirror row_mask:0xf bank_mask:0xf
	v_add_f32_dpp v58, v58, v58 row_half_mirror row_mask:0xf bank_mask:0xf
	v_add_f32_dpp v59, v59, v59 row_half_mirror row_mask:0xf bank_mask:0xf
	v_add_f32_dpp v60, v60, v60 row_half_mirror row_mask:0xf bank_mask:0xf
; __device__ __forceinline__ float lane_get(float v, int src_lane) { return __builtin_bit_cast(float, __builtin_amdgcn_ds_bpermute(src_lane << 2, __builtin_bit_cast(int, v))); }
; __device__ __forceinline__ void fgate_phase(const bfr* x, const float* wf, const float* bfg, float* cl, float* ctot, LAS float* scr, int bx, int G, int tid, int lane, int wave) {
;     ...
;             for (int jj = 0; jj < 4; ++jj) { const u32x2 wa = xa[64 * jj], wb = xb2[64 * jj]; va[jj] = (f32x4){bf_lo(wa.x), bf_hi(wa.x), bf_lo(wa.y), bf_hi(wa.y)}; vb[jj] = (f32x4){bf_lo(wb.x), bf_hi(wb.x), bf_lo(wb.y), bf_hi(wb.y)}; }
;             r[16] = 0.f; r[17] = 0.f;
; #pragma unroll
;             for (int jj = 0; jj < 4; ++jj) { r[16] += (va[jj].x * va[jj].x + va[jj].y * va[jj].y) + (va[jj].z * va[jj].z + va[jj].w * va[jj].w); r[17] += (vb[jj].x * vb[jj].x + vb[jj].y * vb[jj].y) + (vb[jj].z * vb[jj].z + vb[jj].w * vb[jj].w); }
; #pragma unroll
;             for (int h = 0; h < NH; ++h) { const f32x4* wr = (const f32x4*)(wf + h * D) + lane + zo; float da = 0.f, db = 0.f;
; #pragma unroll
;                 for (int jj = 0; jj < 4; ++jj) { const f32x4 w = wr[64 * jj]; da += (va[jj].x * w.x + va[jj].y * w.y) + (va[jj].z * w.z + va[jj].w * w.w); db += (vb[jj].x * w.x + vb[jj].y * w.y) + (vb[jj].z * w.z + vb[jj].w * w.w); }
;                 r[h] = da; r[8 + h] = db; }
;     ...
;             for (int o = 1; o < 64; o <<= 1) {
; #pragma unroll
;                 for (int q = 0; q < 18; ++q) r[q] += lane_get(r[q], lane ^ o); }
;             const float rsa = rsqrtf(r[16] * (1.f / D) + EPS), rsb = rsqrtf(r[17] * (1.f / D) + EPS);
;             if (lane < 16) { const int h = lane & 7; float dsel = r[0];
; #pragma unroll
;                 for (int q = 1; q < 16; ++q) dsel = (lane == q) ? r[q] : dsel;
;                 const float zz = dsel * (lane < 8 ? rsa : rsb) + bfg[h]; const float lf = fminf(zz, 0.f) - 0.6931471805599453f * __builtin_amdgcn_logf(1.0f + __builtin_amdgcn_exp2f(-LOG2E * fabsf(zz)));
;                 scr[(wave * 8 + j + (lane >> 3)) * 8 + h] = lf; } }
	v_add_f32_dpp v61, v61, v61 row_half_mirror row_mask:0xf bank_mask:0xf
	v_add_f32_dpp v62, v62, v62 row_half_mirror row_mask:0xf bank_mask:0xf
	v_add_f32_dpp v87, v87, v87 row_half_mirror row_mask:0xf bank_mask:0xf
	s_nop 1
	v_add_f32_dpp v55, v55, v55 row_mirror row_mask:0xf bank_mask:0xf
	v_add_f32_dpp v56, v56, v56 row_mirror row_mask:0xf bank_mask:0xf
	v_add_f32_dpp v57, v57, v57 row_mirror row_mask:0xf bank_mask:0xf
	v_add_f32_dpp v58, v58, v58 row_mirror row_mask:0xf bank_mask:0xf
	v_add_f32_dpp v59, v59, v59 row_mirror row_mask:0xf bank_mask:0xf
	v_add_f32_dpp v60, v60, v60 row_mirror row_mask:0xf bank_mask:0xf
	v_add_f32_dpp v61, v61, v61 row_mirror row_mask:0xf bank_mask:0xf
	v_add_f32_dpp v62, v62, v62 row_mirror row_mask:0xf bank_mask:0xf
	v_add_f32_dpp v87, v87, v87 row_mirror row_mask:0xf bank_mask:0xf
	s_nop 1
	v_mov_b32_e32 v104, v55
	v_cndmask_b32_e64 v104, v104, v56, s[6:7]
	v_cndmask_b32_e64 v104, v104, v57, s[8:9]
	v_cndmask_b32_e64 v104, v104, v58, s[10:11]
	v_cndmask_b32_e64 v104, v104, v59, s[12:13]
	v_cndmask_b32_e64 v104, v104, v60, s[14:15]
	v_cndmask_b32_e64 v104, v104, v61, s[16:17]
	v_cndmask_b32_e64 v104, v104, v62, s[18:19]
	v_mul_f32_e32 v105, 0x3a800000, v87
	v_add_f32_e32 v105, 0x358637bd, v105
	v_rsq_f32_e32 v105, v105
	s_nop 0
	v_fma_f32 v104, v104, v105, v103
	v_mul_f32_e64 v105, |v104|, s65
	v_exp_f32_e32 v105, v105
	v_min_f32_e32 v104, 0, v104
	v_add_f32_e32 v105, 1.0, v105
	v_log_f32_e32 v105, v105
	s_nop 0
	v_fmac_f32_e32 v104, 0xbf317218, v105
	s_mov_b64 s[54:55], exec
	s_mov_b32 exec_lo, 0xff00ff
	s_mov_b32 exec_hi, 0xff00ff
	ds_write_b32 v107, v104
	s_mov_b64 exec, s[54:55]
	s_waitcnt vmcnt(0) lgkmcnt(0)
	v_lshlrev_b32_e32 v97, 16, v38
	v_and_b32_e32 v159, s40, v38
	v_lshlrev_b32_e32 v187, 16, v39
	v_and_b32_e32 v42, s40, v39
	v_lshlrev_b32_e32 v43, 16, v98
	v_and_b32_e32 v44, s40, v98
	v_lshlrev_b32_e32 v45, 16, v99
	v_and_b32_e32 v46, s40, v99
	v_lshlrev_b32_e32 v47, 16, v160
	v_and_b32_e32 v48, s40, v160
	v_lshlrev_b32_e32 v49, 16, v161
	v_and_b32_e32 v50, s40, v161
	v_lshlrev_b32_e32 v51, 16, v0
	v_and_b32_e32 v52, s40, v0
	v_lshlrev_b32_e32 v53, 16, v1
	v_and_b32_e32 v54, s40, v1
	v_mul_f32_e32 v87, v97, v97
	v_mul_f32_e32 v55, v97, v248
	v_mul_f32_e32 v56, v97, v232
	v_mul_f32_e32 v57, v97, v216
	v_mul_f32_e32 v58, v97, v200
	v_mul_f32_e32 v59, v97, v182
	v_mul_f32_e32 v60, v97, v166
	v_mul_f32_e32 v61, v97, v146
	v_mul_f32_e32 v62, v97, v130
	v_fmac_f32_e32 v87, v159, v159
	v_fmac_f32_e32 v55, v159, v249
	v_fmac_f32_e32 v56, v159, v233
	v_fmac_f32_e32 v57, v159, v217
	v_fmac_f32_e32 v58, v159, v201
	v_fmac_f32_e32 v59, v159, v183
	v_fmac_f32_e32 v60, v159, v167
	v_fmac_f32_e32 v61, v159, v147
	v_fmac_f32_e32 v62, v159, v131
	v_fmac_f32_e32 v87, v187, v187
	v_fmac_f32_e32 v55, v187, v250
	v_fmac_f32_e32 v56, v187, v234
	v_fmac_f32_e32 v57, v187, v218
	v_fmac_f32_e32 v58, v187, v202
	v_fmac_f32_e32 v59, v187, v184
	v_fmac_f32_e32 v60, v187, v168
	v_fmac_f32_e32 v61, v187, v148
	v_fmac_f32_e32 v62, v187, v132
	v_fmac_f32_e32 v87, v42, v42
	v_fmac_f32_e32 v55, v42, v251
	v_fmac_f32_e32 v56, v42, v235
	v_fmac_f32_e32 v57, v42, v219
	v_fmac_f32_e32 v58, v42, v203
	v_fmac_f32_e32 v59, v42, v185
	v_fmac_f32_e32 v60, v42, v169
	v_fmac_f32_e32 v61, v42, v149
	v_fmac_f32_e32 v62, v42, v133
	v_fmac_f32_e32 v87, v43, v43
	v_fmac_f32_e32 v55, v43, v244
	v_fmac_f32_e32 v56, v43, v228
	v_fmac_f32_e32 v57, v43, v212
	v_fmac_f32_e32 v58, v43, v196
	v_fmac_f32_e32 v59, v43, v178
	v_fmac_f32_e32 v60, v43, v162
	v_fmac_f32_e32 v61, v43, v142
	v_fmac_f32_e32 v62, v43, v124
	v_fmac_f32_e32 v87, v44, v44
	v_fmac_f32_e32 v55, v44, v245
	v_fmac_f32_e32 v56, v44, v229
	v_fmac_f32_e32 v57, v44, v213
	v_fmac_f32_e32 v58, v44, v197
	v_fmac_f32_e32 v59, v44, v179
	v_fmac_f32_e32 v60, v44, v163
	v_fmac_f32_e32 v61, v44, v143
	v_fmac_f32_e32 v62, v44, v125
	v_fmac_f32_e32 v87, v45, v45
	v_fmac_f32_e32 v55, v45, v246
	v_fmac_f32_e32 v56, v45, v230
	v_fmac_f32_e32 v57, v45, v214
	v_fmac_f32_e32 v58, v45, v198
	v_fmac_f32_e32 v59, v45, v180
	v_fmac_f32_e32 v60, v45, v164
	v_fmac_f32_e32 v61, v45, v144
	v_fmac_f32_e32 v62, v45, v126
	v_fmac_f32_e32 v87, v46, v46
	v_fmac_f32_e32 v55, v46, v247
	v_fmac_f32_e32 v56, v46, v231
	v_fmac_f32_e32 v57, v46, v215
	v_fmac_f32_e32 v58, v46, v199
	v_fmac_f32_e32 v59, v46, v181
	v_fmac_f32_e32 v60, v46, v165
	v_fmac_f32_e32 v61, v46, v145
	v_fmac_f32_e32 v62, v46, v127
	v_fmac_f32_e32 v87, v47, v47
	v_fmac_f32_e32 v55, v47, v240
	v_fmac_f32_e32 v56, v47, v224
	v_fmac_f32_e32 v57, v47, v208
	v_fmac_f32_e32 v58, v47, v192
	v_fmac_f32_e32 v59, v47, v174
	v_fmac_f32_e32 v60, v47, v154
	v_fmac_f32_e32 v61, v47, v138
	v_fmac_f32_e32 v62, v47, v120
	v_fmac_f32_e32 v87, v48, v48
	v_fmac_f32_e32 v55, v48, v241
	v_fmac_f32_e32 v56, v48, v225
	v_fmac_f32_e32 v57, v48, v209
	v_fmac_f32_e32 v58, v48, v193
	v_fmac_f32_e32 v59, v48, v175
	v_fmac_f32_e32 v60, v48, v155
	v_fmac_f32_e32 v61, v48, v139
	v_fmac_f32_e32 v62, v48, v121
	v_fmac_f32_e32 v87, v49, v49
	v_fmac_f32_e32 v55, v49, v242
	v_fmac_f32_e32 v56, v49, v226
	v_fmac_f32_e32 v57, v49, v210
	v_fmac_f32_e32 v58, v49, v194
	v_fmac_f32_e32 v59, v49, v176
	v_fmac_f32_e32 v60, v49, v156
	v_fmac_f32_e32 v61, v49, v140
	v_fmac_f32_e32 v62, v49, v122
	v_fmac_f32_e32 v87, v50, v50
	v_fmac_f32_e32 v55, v50, v243
	v_fmac_f32_e32 v56, v50, v227
	v_fmac_f32_e32 v57, v50, v211
	v_fmac_f32_e32 v58, v50, v195
	v_fmac_f32_e32 v59, v50, v177
	v_fmac_f32_e32 v60, v50, v157
	v_fmac_f32_e32 v61, v50, v141
	v_fmac_f32_e32 v62, v50, v123
	v_fmac_f32_e32 v87, v51, v51
	v_fmac_f32_e32 v55, v51, v236
	v_fmac_f32_e32 v56, v51, v220
	v_fmac_f32_e32 v57, v51, v204
; __device__ __forceinline__ void fgate_phase(const bfr* x, const float* wf, const float* bfg, float* cl, float* ctot, LAS float* scr, int bx, int G, int tid, int lane, int wave) {
;     ...
;             for (int jj = 0; jj < 4; ++jj) { const u32x2 wa = xa[64 * jj], wb = xb2[64 * jj]; va[jj] = (f32x4){bf_lo(wa.x), bf_hi(wa.x), bf_lo(wa.y), bf_hi(wa.y)}; vb[jj] = (f32x4){bf_lo(wb.x), bf_hi(wb.x), bf_lo(wb.y), bf_hi(wb.y)}; }
;             r[16] = 0.f; r[17] = 0.f;
; #pragma unroll
;             for (int jj = 0; jj < 4; ++jj) { r[16] += (va[jj].x * va[jj].x + va[jj].y * va[jj].y) + (va[jj].z * va[jj].z + va[jj].w * va[jj].w); r[17] += (vb[jj].x * vb[jj].x + vb[jj].y * vb[jj].y) + (vb[jj].z * vb[jj].z + vb[jj].w * vb[jj].w); }
; #pragma unroll
;             for (int h = 0; h < NH; ++h) { const f32x4* wr = (const f32x4*)(wf + h * D) + lane + zo; float da = 0.f, db = 0.f;
; #pragma unroll
;                 for (int jj = 0; jj < 4; ++jj) { const f32x4 w = wr[64 * jj]; da += (va[jj].x * w.x + va[jj].y * w.y) + (va[jj].z * w.z + va[jj].w * w.w); db += (vb[jj].x * w.x + vb[jj].y * w.y) + (vb[jj].z * w.z + vb[jj].w * w.w); }
;                 r[h] = da; r[8 + h] = db; }
	v_fmac_f32_e32 v58, v51, v188
	v_fmac_f32_e32 v59, v51, v170
	v_fmac_f32_e32 v60, v51, v150
	v_fmac_f32_e32 v61, v51, v134
	v_fmac_f32_e32 v62, v51, v116
	v_fmac_f32_e32 v87, v52, v52
	v_fmac_f32_e32 v55, v52, v237
	v_fmac_f32_e32 v56, v52, v221
	v_fmac_f32_e32 v57, v52, v205
	v_fmac_f32_e32 v58, v52, v189
	v_fmac_f32_e32 v59, v52, v171
	v_fmac_f32_e32 v60, v52, v151
	v_fmac_f32_e32 v61, v52, v135
	v_fmac_f32_e32 v62, v52, v117
	v_fmac_f32_e32 v87, v53, v53
	v_fmac_f32_e32 v55, v53, v238
	v_fmac_f32_e32 v56, v53, v222
	v_fmac_f32_e32 v57, v53, v206
	v_fmac_f32_e32 v58, v53, v190
	v_fmac_f32_e32 v59, v53, v172
	v_fmac_f32_e32 v60, v53, v152
	v_fmac_f32_e32 v61, v53, v136
	v_fmac_f32_e32 v62, v53, v118
	v_fmac_f32_e32 v87, v54, v54
	v_fmac_f32_e32 v55, v54, v239
	v_fmac_f32_e32 v56, v54, v223
	v_fmac_f32_e32 v57, v54, v207
	v_fmac_f32_e32 v58, v54, v191
	v_fmac_f32_e32 v59, v54, v173
	v_fmac_f32_e32 v60, v54, v153
	v_fmac_f32_e32 v61, v54, v137
	v_fmac_f32_e32 v62, v54, v119
	v_lshlrev_b32_e32 v97, 16, v2
	v_and_b32_e32 v159, s40, v2
	v_lshlrev_b32_e32 v187, 16, v3
	v_and_b32_e32 v42, s40, v3
	v_lshlrev_b32_e32 v43, 16, v4
	v_and_b32_e32 v44, s40, v4
	v_lshlrev_b32_e32 v45, 16, v5
	v_and_b32_e32 v46, s40, v5
	v_lshlrev_b32_e32 v47, 16, v6
	v_and_b32_e32 v48, s40, v6
	v_lshlrev_b32_e32 v49, 16, v7
	v_and_b32_e32 v50, s40, v7
	v_lshlrev_b32_e32 v51, 16, v8
	v_and_b32_e32 v52, s40, v8
	v_lshlrev_b32_e32 v53, 16, v9
	v_and_b32_e32 v54, s40, v9
	v_mul_f32_e32 v100, v97, v97
	v_mul_f32_e32 v63, v97, v248
	v_mul_f32_e32 v64, v97, v232
	v_mul_f32_e32 v65, v97, v216
	v_mul_f32_e32 v66, v97, v200
	v_mul_f32_e32 v67, v97, v182
	v_mul_f32_e32 v68, v97, v166
	v_mul_f32_e32 v69, v97, v146
	v_mul_f32_e32 v70, v97, v130
	v_fmac_f32_e32 v100, v159, v159
	v_fmac_f32_e32 v63, v159, v249
	v_fmac_f32_e32 v64, v159, v233
	v_fmac_f32_e32 v65, v159, v217
	v_fmac_f32_e32 v66, v159, v201
	v_fmac_f32_e32 v67, v159, v183
	v_fmac_f32_e32 v68, v159, v167
	v_fmac_f32_e32 v69, v159, v147
	v_fmac_f32_e32 v70, v159, v131
	v_fmac_f32_e32 v100, v187, v187
	v_fmac_f32_e32 v63, v187, v250
	v_fmac_f32_e32 v64, v187, v234
	v_fmac_f32_e32 v65, v187, v218
	v_fmac_f32_e32 v66, v187, v202
	v_fmac_f32_e32 v67, v187, v184
	v_fmac_f32_e32 v68, v187, v168
	v_fmac_f32_e32 v69, v187, v148
	v_fmac_f32_e32 v70, v187, v132
	v_fmac_f32_e32 v100, v42, v42
	v_fmac_f32_e32 v63, v42, v251
	v_fmac_f32_e32 v64, v42, v235
	v_fmac_f32_e32 v65, v42, v219
	v_fmac_f32_e32 v66, v42, v203
	v_fmac_f32_e32 v67, v42, v185
	v_fmac_f32_e32 v68, v42, v169
	v_fmac_f32_e32 v69, v42, v149
	v_fmac_f32_e32 v70, v42, v133
	v_fmac_f32_e32 v100, v43, v43
	v_fmac_f32_e32 v63, v43, v244
	v_fmac_f32_e32 v64, v43, v228
	v_fmac_f32_e32 v65, v43, v212
	v_fmac_f32_e32 v66, v43, v196
	v_fmac_f32_e32 v67, v43, v178
	v_fmac_f32_e32 v68, v43, v162
	v_fmac_f32_e32 v69, v43, v142
	v_fmac_f32_e32 v70, v43, v124
	v_fmac_f32_e32 v100, v44, v44
	v_fmac_f32_e32 v63, v44, v245
	v_fmac_f32_e32 v64, v44, v229
	v_fmac_f32_e32 v65, v44, v213
	v_fmac_f32_e32 v66, v44, v197
	v_fmac_f32_e32 v67, v44, v179
	v_fmac_f32_e32 v68, v44, v163
	v_fmac_f32_e32 v69, v44, v143
	v_fmac_f32_e32 v70, v44, v125
	v_fmac_f32_e32 v100, v45, v45
	v_fmac_f32_e32 v63, v45, v246
	v_fmac_f32_e32 v64, v45, v230
	v_fmac_f32_e32 v65, v45, v214
	v_fmac_f32_e32 v66, v45, v198
	v_fmac_f32_e32 v67, v45, v180
	v_fmac_f32_e32 v68, v45, v164
	v_fmac_f32_e32 v69, v45, v144
	v_fmac_f32_e32 v70, v45, v126
	v_fmac_f32_e32 v100, v46, v46
	v_fmac_f32_e32 v63, v46, v247
	v_fmac_f32_e32 v64, v46, v231
	v_fmac_f32_e32 v65, v46, v215
	v_fmac_f32_e32 v66, v46, v199
	v_fmac_f32_e32 v67, v46, v181
	v_fmac_f32_e32 v68, v46, v165
	v_fmac_f32_e32 v69, v46, v145
	v_fmac_f32_e32 v70, v46, v127
	v_fmac_f32_e32 v100, v47, v47
	v_fmac_f32_e32 v63, v47, v240
	v_fmac_f32_e32 v64, v47, v224
	v_fmac_f32_e32 v65, v47, v208
	v_fmac_f32_e32 v66, v47, v192
	v_fmac_f32_e32 v67, v47, v174
	v_fmac_f32_e32 v68, v47, v154
	v_fmac_f32_e32 v69, v47, v138
	v_fmac_f32_e32 v70, v47, v120
	v_fmac_f32_e32 v100, v48, v48
	v_fmac_f32_e32 v63, v48, v241
	v_fmac_f32_e32 v64, v48, v225
	v_fmac_f32_e32 v65, v48, v209
	v_fmac_f32_e32 v66, v48, v193
	v_fmac_f32_e32 v67, v48, v175
	v_fmac_f32_e32 v68, v48, v155
	v_fmac_f32_e32 v69, v48, v139
	v_fmac_f32_e32 v70, v48, v121
	v_fmac_f32_e32 v100, v49, v49
	v_fmac_f32_e32 v63, v49, v242
	v_fmac_f32_e32 v64, v49, v226
	v_fmac_f32_e32 v65, v49, v210
	v_fmac_f32_e32 v66, v49, v194
	v_fmac_f32_e32 v67, v49, v176
	v_fmac_f32_e32 v68, v49, v156
	v_fmac_f32_e32 v69, v49, v140
	v_fmac_f32_e32 v70, v49, v122
	v_fmac_f32_e32 v100, v50, v50
	v_fmac_f32_e32 v63, v50, v243
	v_fmac_f32_e32 v64, v50, v227
	v_fmac_f32_e32 v65, v50, v211
	v_fmac_f32_e32 v66, v50, v195
	v_fmac_f32_e32 v67, v50, v177
	v_fmac_f32_e32 v68, v50, v157
	v_fmac_f32_e32 v69, v50, v141
	v_fmac_f32_e32 v70, v50, v123
	v_fmac_f32_e32 v100, v51, v51
	v_fmac_f32_e32 v63, v51, v236
	v_fmac_f32_e32 v64, v51, v220
	v_fmac_f32_e32 v65, v51, v204
	v_fmac_f32_e32 v66, v51, v188
	v_fmac_f32_e32 v67, v51, v170
	v_fmac_f32_e32 v68, v51, v150
	v_fmac_f32_e32 v69, v51, v134
	v_fmac_f32_e32 v70, v51, v116
	v_fmac_f32_e32 v100, v52, v52
	v_fmac_f32_e32 v63, v52, v237
	v_fmac_f32_e32 v64, v52, v221
	v_fmac_f32_e32 v65, v52, v205
	v_fmac_f32_e32 v66, v52, v189
	v_fmac_f32_e32 v67, v52, v171
	v_fmac_f32_e32 v68, v52, v151
	v_fmac_f32_e32 v69, v52, v135
	v_fmac_f32_e32 v70, v52, v117
	v_fmac_f32_e32 v100, v53, v53
	v_fmac_f32_e32 v63, v53, v238
	v_fmac_f32_e32 v64, v53, v222
	v_fmac_f32_e32 v65, v53, v206
	v_fmac_f32_e32 v66, v53, v190
	v_fmac_f32_e32 v67, v53, v172
	v_fmac_f32_e32 v68, v53, v152
	v_fmac_f32_e32 v69, v53, v136
; __device__ __forceinline__ void fgate_phase(const bfr* x, const float* wf, const float* bfg, float* cl, float* ctot, LAS float* scr, int bx, int G, int tid, int lane, int wave) {
;     ...
;             for (int jj = 0; jj < 4; ++jj) { const u32x2 wa = xa[64 * jj], wb = xb2[64 * jj]; va[jj] = (f32x4){bf_lo(wa.x), bf_hi(wa.x), bf_lo(wa.y), bf_hi(wa.y)}; vb[jj] = (f32x4){bf_lo(wb.x), bf_hi(wb.x), bf_lo(wb.y), bf_hi(wb.y)}; }
;             r[16] = 0.f; r[17] = 0.f;
; #pragma unroll
;             for (int jj = 0; jj < 4; ++jj) { r[16] += (va[jj].x * va[jj].x + va[jj].y * va[jj].y) + (va[jj].z * va[jj].z + va[jj].w * va[jj].w); r[17] += (vb[jj].x * vb[jj].x + vb[jj].y * vb[jj].y) + (vb[jj].z * vb[jj].z + vb[jj].w * vb[jj].w); }
; #pragma unroll
;             for (int h = 0; h < NH; ++h) { const f32x4* wr = (const f32x4*)(wf + h * D) + lane + zo; float da = 0.f, db = 0.f;
; #pragma unroll
;                 for (int jj = 0; jj < 4; ++jj) { const f32x4 w = wr[64 * jj]; da += (va[jj].x * w.x + va[jj].y * w.y) + (va[jj].z * w.z + va[jj].w * w.w); db += (vb[jj].x * w.x + vb[jj].y * w.y) + (vb[jj].z * w.z + vb[jj].w * w.w); }
;                 r[h] = da; r[8 + h] = db; }
	v_fmac_f32_e32 v70, v53, v118
	v_fmac_f32_e32 v100, v54, v54
	v_fmac_f32_e32 v63, v54, v239
	v_fmac_f32_e32 v64, v54, v223
	v_fmac_f32_e32 v65, v54, v207
	v_fmac_f32_e32 v66, v54, v191
	v_fmac_f32_e32 v67, v54, v173
	v_fmac_f32_e32 v68, v54, v153
	v_fmac_f32_e32 v69, v54, v137
	v_fmac_f32_e32 v70, v54, v119
	v_lshlrev_b32_e32 v97, 16, v10
	v_and_b32_e32 v159, s40, v10
	v_lshlrev_b32_e32 v187, 16, v11
	v_and_b32_e32 v42, s40, v11
	v_lshlrev_b32_e32 v43, 16, v12
	v_and_b32_e32 v44, s40, v12
	v_lshlrev_b32_e32 v45, 16, v13
	v_and_b32_e32 v46, s40, v13
	v_lshlrev_b32_e32 v47, 16, v14
	v_and_b32_e32 v48, s40, v14
	v_lshlrev_b32_e32 v49, 16, v15
	v_and_b32_e32 v50, s40, v15
	v_lshlrev_b32_e32 v51, 16, v16
	v_and_b32_e32 v52, s40, v16
	v_lshlrev_b32_e32 v53, 16, v17
	v_and_b32_e32 v54, s40, v17
	v_mul_f32_e32 v101, v97, v97
	v_mul_f32_e32 v71, v97, v248
	v_mul_f32_e32 v72, v97, v232
	v_mul_f32_e32 v73, v97, v216
	v_mul_f32_e32 v74, v97, v200
	v_mul_f32_e32 v75, v97, v182
	v_mul_f32_e32 v76, v97, v166
	v_mul_f32_e32 v77, v97, v146
	v_mul_f32_e32 v78, v97, v130
	v_fmac_f32_e32 v101, v159, v159
	v_fmac_f32_e32 v71, v159, v249
	v_fmac_f32_e32 v72, v159, v233
	v_fmac_f32_e32 v73, v159, v217
	v_fmac_f32_e32 v74, v159, v201
	v_fmac_f32_e32 v75, v159, v183
	v_fmac_f32_e32 v76, v159, v167
	v_fmac_f32_e32 v77, v159, v147
	v_fmac_f32_e32 v78, v159, v131
	v_fmac_f32_e32 v101, v187, v187
	v_fmac_f32_e32 v71, v187, v250
	v_fmac_f32_e32 v72, v187, v234
	v_fmac_f32_e32 v73, v187, v218
	v_fmac_f32_e32 v74, v187, v202
	v_fmac_f32_e32 v75, v187, v184
	v_fmac_f32_e32 v76, v187, v168
	v_fmac_f32_e32 v77, v187, v148
	v_fmac_f32_e32 v78, v187, v132
	v_fmac_f32_e32 v101, v42, v42
	v_fmac_f32_e32 v71, v42, v251
	v_fmac_f32_e32 v72, v42, v235
	v_fmac_f32_e32 v73, v42, v219
	v_fmac_f32_e32 v74, v42, v203
	v_fmac_f32_e32 v75, v42, v185
	v_fmac_f32_e32 v76, v42, v169
	v_fmac_f32_e32 v77, v42, v149
	v_fmac_f32_e32 v78, v42, v133
	v_fmac_f32_e32 v101, v43, v43
	v_fmac_f32_e32 v71, v43, v244
	v_fmac_f32_e32 v72, v43, v228
	v_fmac_f32_e32 v73, v43, v212
	v_fmac_f32_e32 v74, v43, v196
	v_fmac_f32_e32 v75, v43, v178
	v_fmac_f32_e32 v76, v43, v162
	v_fmac_f32_e32 v77, v43, v142
	v_fmac_f32_e32 v78, v43, v124
	v_fmac_f32_e32 v101, v44, v44
	v_fmac_f32_e32 v71, v44, v245
	v_fmac_f32_e32 v72, v44, v229
	v_fmac_f32_e32 v73, v44, v213
	v_fmac_f32_e32 v74, v44, v197
	v_fmac_f32_e32 v75, v44, v179
	v_fmac_f32_e32 v76, v44, v163
	v_fmac_f32_e32 v77, v44, v143
	v_fmac_f32_e32 v78, v44, v125
	v_fmac_f32_e32 v101, v45, v45
	v_fmac_f32_e32 v71, v45, v246
	v_fmac_f32_e32 v72, v45, v230
	v_fmac_f32_e32 v73, v45, v214
	v_fmac_f32_e32 v74, v45, v198
	v_fmac_f32_e32 v75, v45, v180
	v_fmac_f32_e32 v76, v45, v164
	v_fmac_f32_e32 v77, v45, v144
	v_fmac_f32_e32 v78, v45, v126
	v_fmac_f32_e32 v101, v46, v46
	v_fmac_f32_e32 v71, v46, v247
	v_fmac_f32_e32 v72, v46, v231
	v_fmac_f32_e32 v73, v46, v215
	v_fmac_f32_e32 v74, v46, v199
	v_fmac_f32_e32 v75, v46, v181
	v_fmac_f32_e32 v76, v46, v165
	v_fmac_f32_e32 v77, v46, v145
	v_fmac_f32_e32 v78, v46, v127
	v_fmac_f32_e32 v101, v47, v47
	v_fmac_f32_e32 v71, v47, v240
	v_fmac_f32_e32 v72, v47, v224
	v_fmac_f32_e32 v73, v47, v208
	v_fmac_f32_e32 v74, v47, v192
	v_fmac_f32_e32 v75, v47, v174
	v_fmac_f32_e32 v76, v47, v154
	v_fmac_f32_e32 v77, v47, v138
	v_fmac_f32_e32 v78, v47, v120
	v_fmac_f32_e32 v101, v48, v48
	v_fmac_f32_e32 v71, v48, v241
	v_fmac_f32_e32 v72, v48, v225
	v_fmac_f32_e32 v73, v48, v209
	v_fmac_f32_e32 v74, v48, v193
	v_fmac_f32_e32 v75, v48, v175
	v_fmac_f32_e32 v76, v48, v155
	v_fmac_f32_e32 v77, v48, v139
	v_fmac_f32_e32 v78, v48, v121
	v_fmac_f32_e32 v101, v49, v49
	v_fmac_f32_e32 v71, v49, v242
	v_fmac_f32_e32 v72, v49, v226
	v_fmac_f32_e32 v73, v49, v210
	v_fmac_f32_e32 v74, v49, v194
	v_fmac_f32_e32 v75, v49, v176
	v_fmac_f32_e32 v76, v49, v156
	v_fmac_f32_e32 v77, v49, v140
	v_fmac_f32_e32 v78, v49, v122
	v_fmac_f32_e32 v101, v50, v50
	v_fmac_f32_e32 v71, v50, v243
	v_fmac_f32_e32 v72, v50, v227
	v_fmac_f32_e32 v73, v50, v211
	v_fmac_f32_e32 v74, v50, v195
	v_fmac_f32_e32 v75, v50, v177
	v_fmac_f32_e32 v76, v50, v157
	v_fmac_f32_e32 v77, v50, v141
	v_fmac_f32_e32 v78, v50, v123
	v_fmac_f32_e32 v101, v51, v51
	v_fmac_f32_e32 v71, v51, v236
	v_fmac_f32_e32 v72, v51, v220
	v_fmac_f32_e32 v73, v51, v204
	v_fmac_f32_e32 v74, v51, v188
	v_fmac_f32_e32 v75, v51, v170
	v_fmac_f32_e32 v76, v51, v150
	v_fmac_f32_e32 v77, v51, v134
	v_fmac_f32_e32 v78, v51, v116
	v_fmac_f32_e32 v101, v52, v52
	v_fmac_f32_e32 v71, v52, v237
	v_fmac_f32_e32 v72, v52, v221
	v_fmac_f32_e32 v73, v52, v205
	v_fmac_f32_e32 v74, v52, v189
	v_fmac_f32_e32 v75, v52, v171
	v_fmac_f32_e32 v76, v52, v151
	v_fmac_f32_e32 v77, v52, v135
	v_fmac_f32_e32 v78, v52, v117
	v_fmac_f32_e32 v101, v53, v53
	v_fmac_f32_e32 v71, v53, v238
	v_fmac_f32_e32 v72, v53, v222
	v_fmac_f32_e32 v73, v53, v206
	v_fmac_f32_e32 v74, v53, v190
	v_fmac_f32_e32 v75, v53, v172
	v_fmac_f32_e32 v76, v53, v152
	v_fmac_f32_e32 v77, v53, v136
	v_fmac_f32_e32 v78, v53, v118
	v_fmac_f32_e32 v101, v54, v54
	v_fmac_f32_e32 v71, v54, v239
	v_fmac_f32_e32 v72, v54, v223
	v_fmac_f32_e32 v73, v54, v207
	v_fmac_f32_e32 v74, v54, v191
	v_fmac_f32_e32 v75, v54, v173
	v_fmac_f32_e32 v76, v54, v153
	v_fmac_f32_e32 v77, v54, v137
	v_fmac_f32_e32 v78, v54, v119
	v_lshlrev_b32_e32 v97, 16, v18
	v_and_b32_e32 v159, s40, v18
	v_lshlrev_b32_e32 v187, 16, v19
	v_and_b32_e32 v42, s40, v19
	v_lshlrev_b32_e32 v43, 16, v20
	v_and_b32_e32 v44, s40, v20
	v_lshlrev_b32_e32 v45, 16, v21
	v_and_b32_e32 v46, s40, v21
	v_lshlrev_b32_e32 v47, 16, v22
	v_and_b32_e32 v48, s40, v22
	v_lshlrev_b32_e32 v49, 16, v23
	v_and_b32_e32 v50, s40, v23
; __device__ __forceinline__ float lane_get(float v, int src_lane) { return __builtin_bit_cast(float, __builtin_amdgcn_ds_bpermute(src_lane << 2, __builtin_bit_cast(int, v))); }
; __device__ __forceinline__ void fgate_phase(const bfr* x, const float* wf, const float* bfg, float* cl, float* ctot, LAS float* scr, int bx, int G, int tid, int lane, int wave) {
;     ...
;             for (int jj = 0; jj < 4; ++jj) { r[16] += (va[jj].x * va[jj].x + va[jj].y * va[jj].y) + (va[jj].z * va[jj].z + va[jj].w * va[jj].w); r[17] += (vb[jj].x * vb[jj].x + vb[jj].y * vb[jj].y) + (vb[jj].z * vb[jj].z + vb[jj].w * vb[jj].w); }
; #pragma unroll
;             for (int h = 0; h < NH; ++h) { const f32x4* wr = (const f32x4*)(wf + h * D) + lane + zo; float da = 0.f, db = 0.f;
; #pragma unroll
;                 for (int jj = 0; jj < 4; ++jj) { const f32x4 w = wr[64 * jj]; da += (va[jj].x * w.x + va[jj].y * w.y) + (va[jj].z * w.z + va[jj].w * w.w); db += (vb[jj].x * w.x + vb[jj].y * w.y) + (vb[jj].z * w.z + vb[jj].w * w.w); }
;                 r[h] = da; r[8 + h] = db; }
; #pragma unroll
;             for (int o = 1; o < 64; o <<= 1) {
; #pragma unroll
;                 for (int q = 0; q < 18; ++q) r[q] += lane_get(r[q], lane ^ o); }
	v_lshlrev_b32_e32 v51, 16, v24
	v_and_b32_e32 v52, s40, v24
	v_lshlrev_b32_e32 v53, 16, v25
	v_and_b32_e32 v54, s40, v25
	v_mul_f32_e32 v102, v97, v97
	v_mul_f32_e32 v79, v97, v248
	v_mul_f32_e32 v80, v97, v232
	v_mul_f32_e32 v81, v97, v216
	v_mul_f32_e32 v82, v97, v200
	v_mul_f32_e32 v83, v97, v182
	v_mul_f32_e32 v84, v97, v166
	v_mul_f32_e32 v85, v97, v146
	v_mul_f32_e32 v86, v97, v130
	v_fmac_f32_e32 v102, v159, v159
	v_fmac_f32_e32 v79, v159, v249
	v_fmac_f32_e32 v80, v159, v233
	v_fmac_f32_e32 v81, v159, v217
	v_fmac_f32_e32 v82, v159, v201
	v_fmac_f32_e32 v83, v159, v183
	v_fmac_f32_e32 v84, v159, v167
	v_fmac_f32_e32 v85, v159, v147
	v_fmac_f32_e32 v86, v159, v131
	v_fmac_f32_e32 v102, v187, v187
	v_fmac_f32_e32 v79, v187, v250
	v_fmac_f32_e32 v80, v187, v234
	v_fmac_f32_e32 v81, v187, v218
	v_fmac_f32_e32 v82, v187, v202
	v_fmac_f32_e32 v83, v187, v184
	v_fmac_f32_e32 v84, v187, v168
	v_fmac_f32_e32 v85, v187, v148
	v_fmac_f32_e32 v86, v187, v132
	v_fmac_f32_e32 v102, v42, v42
	v_fmac_f32_e32 v79, v42, v251
	v_fmac_f32_e32 v80, v42, v235
	v_fmac_f32_e32 v81, v42, v219
	v_fmac_f32_e32 v82, v42, v203
	v_fmac_f32_e32 v83, v42, v185
	v_fmac_f32_e32 v84, v42, v169
	v_fmac_f32_e32 v85, v42, v149
	v_fmac_f32_e32 v86, v42, v133
	v_fmac_f32_e32 v102, v43, v43
	v_fmac_f32_e32 v79, v43, v244
	v_fmac_f32_e32 v80, v43, v228
	v_fmac_f32_e32 v81, v43, v212
	v_fmac_f32_e32 v82, v43, v196
	v_fmac_f32_e32 v83, v43, v178
	v_fmac_f32_e32 v84, v43, v162
	v_fmac_f32_e32 v85, v43, v142
	v_fmac_f32_e32 v86, v43, v124
	v_fmac_f32_e32 v102, v44, v44
	v_fmac_f32_e32 v79, v44, v245
	v_fmac_f32_e32 v80, v44, v229
	v_fmac_f32_e32 v81, v44, v213
	v_fmac_f32_e32 v82, v44, v197
	v_fmac_f32_e32 v83, v44, v179
	v_fmac_f32_e32 v84, v44, v163
	v_fmac_f32_e32 v85, v44, v143
	v_fmac_f32_e32 v86, v44, v125
	v_fmac_f32_e32 v102, v45, v45
	v_fmac_f32_e32 v79, v45, v246
	v_fmac_f32_e32 v80, v45, v230
	v_fmac_f32_e32 v81, v45, v214
	v_fmac_f32_e32 v82, v45, v198
	v_fmac_f32_e32 v83, v45, v180
	v_fmac_f32_e32 v84, v45, v164
	v_fmac_f32_e32 v85, v45, v144
	v_fmac_f32_e32 v86, v45, v126
	v_fmac_f32_e32 v102, v46, v46
	v_fmac_f32_e32 v79, v46, v247
	v_fmac_f32_e32 v80, v46, v231
	v_fmac_f32_e32 v81, v46, v215
	v_fmac_f32_e32 v82, v46, v199
	v_fmac_f32_e32 v83, v46, v181
	v_fmac_f32_e32 v84, v46, v165
	v_fmac_f32_e32 v85, v46, v145
	v_fmac_f32_e32 v86, v46, v127
	v_fmac_f32_e32 v102, v47, v47
	v_fmac_f32_e32 v79, v47, v240
	v_fmac_f32_e32 v80, v47, v224
	v_fmac_f32_e32 v81, v47, v208
	v_fmac_f32_e32 v82, v47, v192
	v_fmac_f32_e32 v83, v47, v174
	v_fmac_f32_e32 v84, v47, v154
	v_fmac_f32_e32 v85, v47, v138
	v_fmac_f32_e32 v86, v47, v120
	v_fmac_f32_e32 v102, v48, v48
	v_fmac_f32_e32 v79, v48, v241
	v_fmac_f32_e32 v80, v48, v225
	v_fmac_f32_e32 v81, v48, v209
	v_fmac_f32_e32 v82, v48, v193
	v_fmac_f32_e32 v83, v48, v175
	v_fmac_f32_e32 v84, v48, v155
	v_fmac_f32_e32 v85, v48, v139
	v_fmac_f32_e32 v86, v48, v121
	v_fmac_f32_e32 v102, v49, v49
	v_fmac_f32_e32 v79, v49, v242
	v_fmac_f32_e32 v80, v49, v226
	v_fmac_f32_e32 v81, v49, v210
	v_fmac_f32_e32 v82, v49, v194
	v_fmac_f32_e32 v83, v49, v176
	v_fmac_f32_e32 v84, v49, v156
	v_fmac_f32_e32 v85, v49, v140
	v_fmac_f32_e32 v86, v49, v122
	v_fmac_f32_e32 v102, v50, v50
	v_fmac_f32_e32 v79, v50, v243
	v_fmac_f32_e32 v80, v50, v227
	v_fmac_f32_e32 v81, v50, v211
	v_fmac_f32_e32 v82, v50, v195
	v_fmac_f32_e32 v83, v50, v177
	v_fmac_f32_e32 v84, v50, v157
	v_fmac_f32_e32 v85, v50, v141
	v_fmac_f32_e32 v86, v50, v123
	v_fmac_f32_e32 v102, v51, v51
	v_fmac_f32_e32 v79, v51, v236
	v_fmac_f32_e32 v80, v51, v220
	v_fmac_f32_e32 v81, v51, v204
	v_fmac_f32_e32 v82, v51, v188
	v_fmac_f32_e32 v83, v51, v170
	v_fmac_f32_e32 v84, v51, v150
	v_fmac_f32_e32 v85, v51, v134
	v_fmac_f32_e32 v86, v51, v116
	v_fmac_f32_e32 v102, v52, v52
	v_fmac_f32_e32 v79, v52, v237
	v_fmac_f32_e32 v80, v52, v221
	v_fmac_f32_e32 v81, v52, v205
	v_fmac_f32_e32 v82, v52, v189
	v_fmac_f32_e32 v83, v52, v171
	v_fmac_f32_e32 v84, v52, v151
	v_fmac_f32_e32 v85, v52, v135
	v_fmac_f32_e32 v86, v52, v117
	v_fmac_f32_e32 v102, v53, v53
	v_fmac_f32_e32 v79, v53, v238
	v_fmac_f32_e32 v80, v53, v222
	v_fmac_f32_e32 v81, v53, v206
	v_fmac_f32_e32 v82, v53, v190
	v_fmac_f32_e32 v83, v53, v172
	v_fmac_f32_e32 v84, v53, v152
	v_fmac_f32_e32 v85, v53, v136
	v_fmac_f32_e32 v86, v53, v118
	v_fmac_f32_e32 v102, v54, v54
	v_fmac_f32_e32 v79, v54, v239
	v_fmac_f32_e32 v80, v54, v223
	v_fmac_f32_e32 v81, v54, v207
	v_fmac_f32_e32 v82, v54, v191
	v_fmac_f32_e32 v83, v54, v173
	v_fmac_f32_e32 v84, v54, v153
	v_fmac_f32_e32 v85, v54, v137
	v_fmac_f32_e32 v86, v54, v119
	s_nop 1
	v_permlane32_swap_b32_e32 v55, v71
	v_permlane32_swap_b32_e32 v56, v72
	v_permlane32_swap_b32_e32 v57, v73
	v_permlane32_swap_b32_e32 v58, v74
	v_permlane32_swap_b32_e32 v59, v75
	v_permlane32_swap_b32_e32 v60, v76
	v_permlane32_swap_b32_e32 v61, v77
	v_permlane32_swap_b32_e32 v62, v78
	v_permlane32_swap_b32_e32 v63, v79
; __device__ __forceinline__ float lane_get(float v, int src_lane) { return __builtin_bit_cast(float, __builtin_amdgcn_ds_bpermute(src_lane << 2, __builtin_bit_cast(int, v))); }
; __device__ __forceinline__ void fgate_phase(const bfr* x, const float* wf, const float* bfg, float* cl, float* ctot, LAS float* scr, int bx, int G, int tid, int lane, int wave) {
;     ...
;             for (int o = 1; o < 64; o <<= 1) {
; #pragma unroll
;                 for (int q = 0; q < 18; ++q) r[q] += lane_get(r[q], lane ^ o); }
;             const float rsa = rsqrtf(r[16] * (1.f / D) + EPS), rsb = rsqrtf(r[17] * (1.f / D) + EPS);
;             if (lane < 16) { const int h = lane & 7; float dsel = r[0];
; #pragma unroll
;                 for (int q = 1; q < 16; ++q) dsel = (lane == q) ? r[q] : dsel;
;                 const float zz = dsel * (lane < 8 ? rsa : rsb) + bfg[h]; const float lf = fminf(zz, 0.f) - 0.6931471805599453f * __builtin_amdgcn_logf(1.0f + __builtin_amdgcn_exp2f(-LOG2E * fabsf(zz)));
;                 scr[(wave * 8 + j + (lane >> 3)) * 8 + h] = lf; } }
	v_permlane32_swap_b32_e32 v64, v80
	v_permlane32_swap_b32_e32 v65, v81
	v_permlane32_swap_b32_e32 v66, v82
	v_permlane32_swap_b32_e32 v67, v83
	v_permlane32_swap_b32_e32 v68, v84
	v_permlane32_swap_b32_e32 v69, v85
	v_permlane32_swap_b32_e32 v70, v86
	v_permlane32_swap_b32_e32 v87, v101
	v_permlane32_swap_b32_e32 v100, v102
	s_nop 1
	v_add_f32_e32 v55, v55, v71
	v_add_f32_e32 v56, v56, v72
	v_add_f32_e32 v57, v57, v73
	v_add_f32_e32 v58, v58, v74
	v_add_f32_e32 v59, v59, v75
	v_add_f32_e32 v60, v60, v76
	v_add_f32_e32 v61, v61, v77
	v_add_f32_e32 v62, v62, v78
	v_add_f32_e32 v63, v63, v79
	v_add_f32_e32 v64, v64, v80
	v_add_f32_e32 v65, v65, v81
	v_add_f32_e32 v66, v66, v82
	v_add_f32_e32 v67, v67, v83
	v_add_f32_e32 v68, v68, v84
	v_add_f32_e32 v69, v69, v85
	v_add_f32_e32 v70, v70, v86
	v_add_f32_e32 v87, v87, v101
	v_add_f32_e32 v100, v100, v102
	s_nop 1
	v_permlane16_swap_b32_e32 v55, v63
	v_permlane16_swap_b32_e32 v56, v64
	v_permlane16_swap_b32_e32 v57, v65
	v_permlane16_swap_b32_e32 v58, v66
	v_permlane16_swap_b32_e32 v59, v67
	v_permlane16_swap_b32_e32 v60, v68
	v_permlane16_swap_b32_e32 v61, v69
	v_permlane16_swap_b32_e32 v62, v70
	v_permlane16_swap_b32_e32 v87, v100
	s_nop 1
	v_add_f32_e32 v55, v55, v63
	v_add_f32_e32 v56, v56, v64
	v_add_f32_e32 v57, v57, v65
	v_add_f32_e32 v58, v58, v66
	v_add_f32_e32 v59, v59, v67
	v_add_f32_e32 v60, v60, v68
	v_add_f32_e32 v61, v61, v69
	v_add_f32_e32 v62, v62, v70
	v_add_f32_e32 v87, v87, v100
	s_nop 1
	v_add_f32_dpp v55, v55, v55 quad_perm:[1,0,3,2] row_mask:0xf bank_mask:0xf
	v_add_f32_dpp v56, v56, v56 quad_perm:[1,0,3,2] row_mask:0xf bank_mask:0xf
	v_add_f32_dpp v57, v57, v57 quad_perm:[1,0,3,2] row_mask:0xf bank_mask:0xf
	v_add_f32_dpp v58, v58, v58 quad_perm:[1,0,3,2] row_mask:0xf bank_mask:0xf
	v_add_f32_dpp v59, v59, v59 quad_perm:[1,0,3,2] row_mask:0xf bank_mask:0xf
	v_add_f32_dpp v60, v60, v60 quad_perm:[1,0,3,2] row_mask:0xf bank_mask:0xf
	v_add_f32_dpp v61, v61, v61 quad_perm:[1,0,3,2] row_mask:0xf bank_mask:0xf
	v_add_f32_dpp v62, v62, v62 quad_perm:[1,0,3,2] row_mask:0xf bank_mask:0xf
	v_add_f32_dpp v87, v87, v87 quad_perm:[1,0,3,2] row_mask:0xf bank_mask:0xf
	s_nop 1
	v_add_f32_dpp v55, v55, v55 quad_perm:[2,3,0,1] row_mask:0xf bank_mask:0xf
	v_add_f32_dpp v56, v56, v56 quad_perm:[2,3,0,1] row_mask:0xf bank_mask:0xf
	v_add_f32_dpp v57, v57, v57 quad_perm:[2,3,0,1] row_mask:0xf bank_mask:0xf
	v_add_f32_dpp v58, v58, v58 quad_perm:[2,3,0,1] row_mask:0xf bank_mask:0xf
	v_add_f32_dpp v59, v59, v59 quad_perm:[2,3,0,1] row_mask:0xf bank_mask:0xf
	v_add_f32_dpp v60, v60, v60 quad_perm:[2,3,0,1] row_mask:0xf bank_mask:0xf
	v_add_f32_dpp v61, v61, v61 quad_perm:[2,3,0,1] row_mask:0xf bank_mask:0xf
	v_add_f32_dpp v62, v62, v62 quad_perm:[2,3,0,1] row_mask:0xf bank_mask:0xf
	v_add_f32_dpp v87, v87, v87 quad_perm:[2,3,0,1] row_mask:0xf bank_mask:0xf
	s_nop 1
	v_add_f32_dpp v55, v55, v55 row_half_mirror row_mask:0xf bank_mask:0xf
	v_add_f32_dpp v56, v56, v56 row_half_mirror row_mask:0xf bank_mask:0xf
	v_add_f32_dpp v57, v57, v57 row_half_mirror row_mask:0xf bank_mask:0xf
	v_add_f32_dpp v58, v58, v58 row_half_mirror row_mask:0xf bank_mask:0xf
	v_add_f32_dpp v59, v59, v59 row_half_mirror row_mask:0xf bank_mask:0xf
	v_add_f32_dpp v60, v60, v60 row_half_mirror row_mask:0xf bank_mask:0xf
	v_add_f32_dpp v61, v61, v61 row_half_mirror row_mask:0xf bank_mask:0xf
	v_add_f32_dpp v62, v62, v62 row_half_mirror row_mask:0xf bank_mask:0xf
	v_add_f32_dpp v87, v87, v87 row_half_mirror row_mask:0xf bank_mask:0xf
	s_nop 1
	v_add_f32_dpp v55, v55, v55 row_mirror row_mask:0xf bank_mask:0xf
	v_add_f32_dpp v56, v56, v56 row_mirror row_mask:0xf bank_mask:0xf
	v_add_f32_dpp v57, v57, v57 row_mirror row_mask:0xf bank_mask:0xf
	v_add_f32_dpp v58, v58, v58 row_mirror row_mask:0xf bank_mask:0xf
	v_add_f32_dpp v59, v59, v59 row_mirror row_mask:0xf bank_mask:0xf
	v_add_f32_dpp v60, v60, v60 row_mirror row_mask:0xf bank_mask:0xf
	v_add_f32_dpp v61, v61, v61 row_mirror row_mask:0xf bank_mask:0xf
	v_add_f32_dpp v62, v62, v62 row_mirror row_mask:0xf bank_mask:0xf
	v_add_f32_dpp v87, v87, v87 row_mirror row_mask:0xf bank_mask:0xf
	s_nop 1
	v_mov_b32_e32 v104, v55
	v_cndmask_b32_e64 v104, v104, v56, s[6:7]
	v_cndmask_b32_e64 v104, v104, v57, s[8:9]
	v_cndmask_b32_e64 v104, v104, v58, s[10:11]
	v_cndmask_b32_e64 v104, v104, v59, s[12:13]
	v_cndmask_b32_e64 v104, v104, v60, s[14:15]
	v_cndmask_b32_e64 v104, v104, v61, s[16:17]
	v_cndmask_b32_e64 v104, v104, v62, s[18:19]
	v_mul_f32_e32 v105, 0x3a800000, v87
	v_add_f32_e32 v105, 0x358637bd, v105
	v_rsq_f32_e32 v105, v105
	s_nop 0
	v_fma_f32 v104, v104, v105, v103
	v_mul_f32_e64 v105, |v104|, s65
	v_exp_f32_e32 v105, v105
	v_min_f32_e32 v104, 0, v104
	v_add_f32_e32 v105, 1.0, v105
	v_log_f32_e32 v105, v105
	s_nop 0
	v_fmac_f32_e32 v104, 0xbf317218, v105
	s_mov_b64 s[54:55], exec
	s_mov_b32 exec_lo, 0xff00ff
	s_mov_b32 exec_hi, 0xff00ff
	ds_write_b32 v107, v104 offset:128
	s_mov_b64 exec, s[54:55]
